# norm phases: all 4 rows of a wave in flight, residual-row and parameter loads issued before the seam's counter wait (the wait moved inside the norm body), gate*norm_post and (scale+1)*norm_pre pre-mul
# speedup vs baseline: 1.0085x; 1.0085x over previous
.LBB0_265:
	v_mov_b32_e32 v0, v147
	v_readlane_b32 s2, v255, 0
	s_mov_b32 s71, s39
	v_ashrrev_i32_e32 v1, 6, v0
	v_lshl_add_u32 v96, s2, 3, v1
	s_movk_i32 s2, 0x2000
	v_cmp_gt_i32_e32 vcc, s2, v96
	s_mul_i32 s2, s70, 0xc00
	v_writelane_b32 v255, s2, 12
	s_nop 1
	v_writelane_b32 v255, s3, 13
	s_and_saveexec_b64 s[16:17], vcc
	s_cbranch_execz .LBB0_280
	s_load_dwordx4 s[8:11], s[0:1], 0x90
	s_load_dwordx4 s[12:15], s[0:1], 0x0
	s_load_dwordx4 s[4:7], s[0:1], 0x40
	s_mul_i32 s2, s70, 0x2d000
	s_mul_i32 s24, s70, 0xc00
	s_waitcnt lgkmcnt(0)
	s_add_u32 s22, s10, 0x100000
	s_addc_u32 s23, s11, 0
	s_cmp_lg_u32 s70, 0
	s_cselect_b64 s[18:19], -1, 0
	s_add_u32 s20, s22, s2
	s_mul_hi_u32 s2, s70, 0x2d000
	s_addc_u32 s21, s23, s2
	s_mov_b32 s2, s24
	v_writelane_b32 v255, s2, 12
	v_sub_u32_e64 v1, s70, 1 clamp
	v_cmp_lt_i32_e32 vcc, v188, v183
	v_writelane_b32 v255, s3, 13
	s_movk_i32 s2, 0xc00
	v_mul_lo_u32 v144, v1, s2
	s_mov_b32 s2, 0x2d000
	v_lshlrev_b64 v[2:3], 2, v[144:145]
	v_mul_lo_u32 v144, v1, s2
	v_lshlrev_b32_e32 v1, 2, v0
	v_and_b32_e32 v98, 0xfc, v1
	v_cndmask_b32_e32 v1, v182, v188, vcc
	v_cmp_lt_i32_e32 vcc, v254, v183
	v_lshlrev_b32_e32 v99, 2, v1
	v_lshl_add_u64 v[4:5], s[22:23], 0, v[144:145]
	v_cndmask_b32_e32 v1, v182, v254, vcc
	v_lshlrev_b32_e32 v128, 2, v1
	v_xor_b32_e32 v1, 4, v182
	v_cmp_lt_i32_e32 vcc, v1, v183
	v_lshlrev_b32_e32 v144, 2, v98
	s_mov_b32 s25, s39
	v_cndmask_b32_e32 v1, v182, v1, vcc
	v_lshlrev_b32_e32 v129, 2, v1
	v_xor_b32_e32 v1, 8, v182
	v_lshl_add_u64 v[2:3], s[6:7], 0, v[2:3]
	v_lshl_add_u64 v[4:5], v[4:5], 0, v[144:145]
	s_mov_b64 s[6:7], 0x8000
	v_cmp_lt_i32_e32 vcc, v1, v183
	s_lshl_b64 s[24:25], s[24:25], 2
	v_lshl_add_u64 v[100:101], v[4:5], 0, s[6:7]
	v_lshl_add_u64 v[2:3], v[2:3], 0, v[144:145]
	s_mov_b64 s[6:7], 0x2000
	v_cndmask_b32_e32 v1, v182, v1, vcc
	v_cmp_lt_i32_e32 vcc, v187, v183
	v_ashrrev_i32_e32 v97, 31, v96
	s_add_u32 s4, s4, s24
	v_lshl_add_u64 v[102:103], v[2:3], 0, s[6:7]
	v_lshlrev_b32_e32 v130, 2, v1
	v_cndmask_b32_e32 v1, v182, v187, vcc
	v_cmp_lt_i32_e32 vcc, v184, v183
	v_lshlrev_b64 v[2:3], 11, v[96:97]
	v_and_b32_e32 v4, 63, v0
	s_addc_u32 s5, s5, s25
	v_lshlrev_b32_e32 v131, 2, v1
	v_cndmask_b32_e32 v1, v182, v184, vcc
	v_lshl_or_b32 v2, v4, 3, v2
	v_lshl_add_u64 v[104:105], s[4:5], 0, v[144:145]
	v_lshlrev_b32_e32 v132, 2, v1
	v_lshl_add_u64 v[0:1], s[10:11], 0, v[2:3]
	s_mov_b64 s[4:5], 0x9800600
	v_lshlrev_b64 v[108:109], 12, v[96:97]
	v_lshl_add_u64 v[106:107], v[0:1], 0, s[4:5]
	v_lshl_or_b32 v108, v4, 4, v108
	s_mov_b64 s[10:11], 0
	s_cmp_eq_u32 s70, 0
	s_cbranch_scc1 .Lnorm0_first
	v_readlane_b32 s2, v255, 0
	v_readfirstlane_b32 s7, v147
	s_load_dwordx2 s[4:5], s[0:1], 0x90
	s_load_dwordx2 s[12:13], s[0:1], 0x98
	s_load_dwordx2 s[14:15], s[0:1], 0x40
	s_load_dwordx2 s[40:41], s[0:1], 0x48
	v_and_b32_e32 v0, 63, v147
	v_lshlrev_b32_e32 v1, 3, v0
	v_lshlrev_b32_e32 v0, 4, v0
	s_lshr_b32 s7, s7, 6
	s_and_b32 s27, s2, 6
	s_lshl_b32 s27, s27, 5
	s_and_b32 s37, s2, 0x39
	s_or_b32 s27, s27, s37
	s_lshr_b32 s37, s2, 6
	s_lshl_b32 s37, s37, 1
	s_or_b32 s2, s27, s37
	s_lshl_b32 s2, s2, 3
	s_add_u32 s2, s2, s7
	s_lshl_b32 s24, s2, 2
	s_sub_u32 s27, s24, 0x1000
	s_lshr_b32 s27, s27, 10
	s_add_u32 s27, s27, 1
	s_cmp_lt_u32 s24, 0x1000
	s_cselect_b32 s30, 0, s27
	v_add_u32_e32 v2, 0x8000, v0
	v_mov_b32_e32 v3, v0
	v_add_u32_e32 v4, 0x1000, v0
	s_waitcnt lgkmcnt(0)
	s_lshl_b32 s27, s24, 11
	s_add_u32 s62, s12, s27
	s_addc_u32 s63, s13, 0
	s_add_u32 s58, s62, 0x8800000
	s_addc_u32 s59, s63, 0
	s_add_u32 s60, s58, 0x1000000
	s_addc_u32 s61, s59, 0
	s_add_u32 s62, s62, 0x1000000
	s_addc_u32 s63, s63, 0
	s_lshl_b32 s27, s24, 12
	s_add_u32 s46, s4, s27
	s_addc_u32 s47, s5, 0
	s_mov_b64 s[4:5], s[46:47]
	s_mul_i32 s27, s70, 5
	s_add_u32 s27, s27, s30
	s_mul_i32 s27, s27, 0x9000
	s_add_u32 s27, s27, 0x100000
	s_add_u32 s88, s12, s27
	s_addc_u32 s89, s13, 0
	s_sub_u32 s100, s88, 0x2d000
	s_subb_u32 s101, s89, 0
	s_mul_i32 s27, s70, 0x3000
	s_add_u32 s27, s27, 0xfffff000
	s_add_u32 s40, s40, s27
	s_addc_u32 s41, s41, 0
	s_mul_i32 s27, s70, 0x3000
	s_add_u32 s14, s14, s27
	s_addc_u32 s15, s15, 0
	global_load_dwordx4 v[22:25], v2, s[100:101] offset:0
	global_load_dwordx4 v[172:175], v0, s[40:41] offset:0
	global_load_dwordx4 v[38:41], v3, s[88:89] offset:0
	global_load_dwordx4 v[54:57], v4, s[88:89] offset:0
	global_load_dwordx4 v[234:237], v0, s[14:15] offset:0
	global_load_dwordx4 v[26:29], v2, s[100:101] offset:1024
	global_load_dwordx4 v[176:179], v0, s[40:41] offset:1024
	global_load_dwordx4 v[42:45], v3, s[88:89] offset:1024
	global_load_dwordx4 v[58:61], v4, s[88:89] offset:1024
	global_load_dwordx4 v[238:241], v0, s[14:15] offset:1024
	global_load_dwordx4 v[30:33], v2, s[100:101] offset:2048
	global_load_dwordx4 v[204:207], v0, s[40:41] offset:2048
	global_load_dwordx4 v[46:49], v3, s[88:89] offset:2048
	global_load_dwordx4 v[62:65], v4, s[88:89] offset:2048
	global_load_dwordx4 v[242:245], v0, s[14:15] offset:2048
	global_load_dwordx4 v[34:37], v2, s[100:101] offset:3072
	global_load_dwordx4 v[214:217], v0, s[40:41] offset:3072
	global_load_dwordx4 v[50:53], v3, s[88:89] offset:3072
	global_load_dwordx4 v[66:69], v4, s[88:89] offset:3072
	global_load_dwordx4 v[246:249], v0, s[14:15] offset:3072
	global_load_dwordx4 v[70:73], v0, s[4:5] offset:0
	global_load_dwordx4 v[74:77], v0, s[4:5] offset:1024
	global_load_dwordx4 v[78:81], v0, s[4:5] offset:2048
	global_load_dwordx4 v[82:85], v0, s[4:5] offset:3072
	s_add_u32 s4, s4, 0x1000
	s_addc_u32 s5, s5, 0
	global_load_dwordx4 v[102:105], v0, s[4:5] offset:0
	global_load_dwordx4 v[106:109], v0, s[4:5] offset:1024
	global_load_dwordx4 v[110:113], v0, s[4:5] offset:2048
	global_load_dwordx4 v[114:117], v0, s[4:5] offset:3072
	s_add_u32 s4, s4, 0x1000
	s_addc_u32 s5, s5, 0
	global_load_dwordx4 v[154:157], v0, s[4:5] offset:0
	global_load_dwordx4 v[158:161], v0, s[4:5] offset:1024
	global_load_dwordx4 v[162:165], v0, s[4:5] offset:2048
	global_load_dwordx4 v[168:171], v0, s[4:5] offset:3072
	s_add_u32 s4, s4, 0x1000
	s_addc_u32 s5, s5, 0
	global_load_dwordx4 v[218:221], v0, s[4:5] offset:0
	global_load_dwordx4 v[222:225], v0, s[4:5] offset:1024
	global_load_dwordx4 v[226:229], v0, s[4:5] offset:2048
	global_load_dwordx4 v[230:233], v0, s[4:5] offset:3072
	s_add_u32 s4, s4, 0x1000
	s_addc_u32 s5, s5, 0
	s_waitcnt vmcnt(16)
	v_pk_mul_f32 v[22:23], v[22:23], v[172:173]
	v_pk_mul_f32 v[24:25], v[24:25], v[174:175]
	v_pk_mul_f32 v[26:27], v[26:27], v[176:177]
	v_pk_mul_f32 v[28:29], v[28:29], v[178:179]
	v_pk_mul_f32 v[30:31], v[30:31], v[204:205]
	v_pk_mul_f32 v[32:33], v[32:33], v[206:207]
	v_pk_mul_f32 v[34:35], v[34:35], v[214:215]
	v_pk_mul_f32 v[36:37], v[36:37], v[216:217]
	v_pk_add_f32 v[54:55], v[54:55], 1.0 op_sel_hi:[1,0]
	v_pk_mul_f32 v[54:55], v[54:55], v[234:235]
	v_pk_add_f32 v[56:57], v[56:57], 1.0 op_sel_hi:[1,0]
	v_pk_mul_f32 v[56:57], v[56:57], v[236:237]
	v_pk_add_f32 v[58:59], v[58:59], 1.0 op_sel_hi:[1,0]
	v_pk_mul_f32 v[58:59], v[58:59], v[238:239]
	v_pk_add_f32 v[60:61], v[60:61], 1.0 op_sel_hi:[1,0]
	v_pk_mul_f32 v[60:61], v[60:61], v[240:241]
	v_pk_add_f32 v[62:63], v[62:63], 1.0 op_sel_hi:[1,0]
	v_pk_mul_f32 v[62:63], v[62:63], v[242:243]
	v_pk_add_f32 v[64:65], v[64:65], 1.0 op_sel_hi:[1,0]
	v_pk_mul_f32 v[64:65], v[64:65], v[244:245]
	v_pk_add_f32 v[66:67], v[66:67], 1.0 op_sel_hi:[1,0]
	v_pk_mul_f32 v[66:67], v[66:67], v[246:247]
	v_pk_add_f32 v[68:69], v[68:69], 1.0 op_sel_hi:[1,0]
	v_pk_mul_f32 v[68:69], v[68:69], v[248:249]
	v_cmp_eq_u32_e32 vcc, 0, v147
	s_and_saveexec_b64 s[40:41], vcc
	s_cbranch_execz .Lnw_skip_n0g
	v_readlane_b32 s2, v255, 0
	v_readlane_b32 s7, v255, 46
	s_nop 0
	s_lshr_b32 s24, s2, 3
	s_and_b32 s24, s24, 7
	s_and_b32 s27, s2, 6
	s_lshl_b32 s27, s27, 2
	s_or_b32 s27, s27, s24
	s_lshl_b32 s27, s27, 7
	s_add_u32 s27, s27, 0xa000
	v_mov_b32_e32 v14, s27
	s_mov_b32 s30, 0
.Lnw_poll_n0g:
	global_load_dword v16, v14, s[12:13] sc1
	s_waitcnt vmcnt(0)
	v_readfirstlane_b32 s37, v16
	s_nop 0
	s_cmp_ge_u32 s37, s7
	s_cbranch_scc1 .Lnw_skip_n0g
	s_sleep 1
	s_add_u32 s30, s30, 1
	s_cmp_lt_u32 s30, 0x2000
	s_cbranch_scc1 .Lnw_poll_n0g
.Lnw_skip_n0g:
	s_or_b64 exec, exec, s[40:41]
	s_barrier
	global_load_dwordx2 v[86:87], v1, s[58:59] offset:0
	global_load_dwordx2 v[90:91], v1, s[58:59] offset:512
	global_load_dwordx2 v[94:95], v1, s[58:59] offset:1024
	global_load_dwordx2 v[98:99], v1, s[58:59] offset:1536
	global_load_dwordx2 v[88:89], v1, s[60:61] offset:0
	global_load_dwordx2 v[92:93], v1, s[60:61] offset:512
	global_load_dwordx2 v[96:97], v1, s[60:61] offset:1024
	global_load_dwordx2 v[100:101], v1, s[60:61] offset:1536
	s_add_u32 s58, s58, 0x800
	s_addc_u32 s59, s59, 0
	s_add_u32 s60, s60, 0x800
	s_addc_u32 s61, s61, 0
	global_load_dwordx2 v[118:119], v1, s[58:59] offset:0
	global_load_dwordx2 v[122:123], v1, s[58:59] offset:512
	global_load_dwordx2 v[134:135], v1, s[58:59] offset:1024
	global_load_dwordx2 v[138:139], v1, s[58:59] offset:1536
	global_load_dwordx2 v[120:121], v1, s[60:61] offset:0
	global_load_dwordx2 v[124:125], v1, s[60:61] offset:512
	global_load_dwordx2 v[136:137], v1, s[60:61] offset:1024
	global_load_dwordx2 v[140:141], v1, s[60:61] offset:1536
	s_add_u32 s58, s58, 0x800
	s_addc_u32 s59, s59, 0
	s_add_u32 s60, s60, 0x800
	s_addc_u32 s61, s61, 0
	global_load_dwordx2 v[172:173], v1, s[58:59] offset:0
	global_load_dwordx2 v[176:177], v1, s[58:59] offset:512
	global_load_dwordx2 v[204:205], v1, s[58:59] offset:1024
	global_load_dwordx2 v[214:215], v1, s[58:59] offset:1536
	global_load_dwordx2 v[174:175], v1, s[60:61] offset:0
	global_load_dwordx2 v[178:179], v1, s[60:61] offset:512
	global_load_dwordx2 v[206:207], v1, s[60:61] offset:1024
	global_load_dwordx2 v[216:217], v1, s[60:61] offset:1536
	s_add_u32 s58, s58, 0x800
	s_addc_u32 s59, s59, 0
	s_add_u32 s60, s60, 0x800
	s_addc_u32 s61, s61, 0
	global_load_dwordx2 v[234:235], v1, s[58:59] offset:0
	global_load_dwordx2 v[238:239], v1, s[58:59] offset:512
	global_load_dwordx2 v[242:243], v1, s[58:59] offset:1024
	global_load_dwordx2 v[246:247], v1, s[58:59] offset:1536
	global_load_dwordx2 v[236:237], v1, s[60:61] offset:0
	global_load_dwordx2 v[240:241], v1, s[60:61] offset:512
	global_load_dwordx2 v[244:245], v1, s[60:61] offset:1024
	global_load_dwordx2 v[248:249], v1, s[60:61] offset:1536
	s_add_u32 s58, s58, 0x800
	s_addc_u32 s59, s59, 0
	s_add_u32 s60, s60, 0x800
	s_addc_u32 s61, s61, 0
	s_waitcnt vmcnt(24)
	v_lshlrev_b32_e32 v14, 16, v86
	v_and_b32_e32 v15, 0xffff0000, v86
	v_lshlrev_b32_e32 v16, 16, v88
	v_and_b32_e32 v17, 0xffff0000, v88
	v_lshlrev_b32_e32 v18, 16, v87
	v_and_b32_e32 v19, 0xffff0000, v87
	v_lshlrev_b32_e32 v20, 16, v89
	v_and_b32_e32 v21, 0xffff0000, v89
	v_pk_add_f32 v[86:87], v[14:15], v[16:17]
	v_pk_add_f32 v[88:89], v[18:19], v[20:21]
	v_lshlrev_b32_e32 v14, 16, v90
	v_and_b32_e32 v15, 0xffff0000, v90
	v_lshlrev_b32_e32 v16, 16, v92
	v_and_b32_e32 v17, 0xffff0000, v92
	v_lshlrev_b32_e32 v18, 16, v91
	v_and_b32_e32 v19, 0xffff0000, v91
	v_lshlrev_b32_e32 v20, 16, v93
	v_and_b32_e32 v21, 0xffff0000, v93
	v_pk_add_f32 v[90:91], v[14:15], v[16:17]
	v_pk_add_f32 v[92:93], v[18:19], v[20:21]
	v_lshlrev_b32_e32 v14, 16, v94
	v_and_b32_e32 v15, 0xffff0000, v94
	v_lshlrev_b32_e32 v16, 16, v96
	v_and_b32_e32 v17, 0xffff0000, v96
	v_lshlrev_b32_e32 v18, 16, v95
	v_and_b32_e32 v19, 0xffff0000, v95
	v_lshlrev_b32_e32 v20, 16, v97
	v_and_b32_e32 v21, 0xffff0000, v97
	v_pk_add_f32 v[94:95], v[14:15], v[16:17]
	v_pk_add_f32 v[96:97], v[18:19], v[20:21]
	v_lshlrev_b32_e32 v14, 16, v98
	v_and_b32_e32 v15, 0xffff0000, v98
	v_lshlrev_b32_e32 v16, 16, v100
	v_and_b32_e32 v17, 0xffff0000, v100
	v_lshlrev_b32_e32 v18, 16, v99
	v_and_b32_e32 v19, 0xffff0000, v99
	v_lshlrev_b32_e32 v20, 16, v101
	v_and_b32_e32 v21, 0xffff0000, v101
	v_pk_add_f32 v[98:99], v[14:15], v[16:17]
	v_pk_add_f32 v[100:101], v[18:19], v[20:21]
	v_pk_mul_f32 v[12:13], v[86:87], v[86:87]
	v_pk_fma_f32 v[12:13], v[88:89], v[88:89], v[12:13]
	v_pk_fma_f32 v[12:13], v[90:91], v[90:91], v[12:13]
	v_pk_fma_f32 v[12:13], v[92:93], v[92:93], v[12:13]
	v_pk_fma_f32 v[12:13], v[94:95], v[94:95], v[12:13]
	v_pk_fma_f32 v[12:13], v[96:97], v[96:97], v[12:13]
	v_pk_fma_f32 v[12:13], v[98:99], v[98:99], v[12:13]
	v_pk_fma_f32 v[12:13], v[100:101], v[100:101], v[12:13]
	v_add_f32_e32 v5, v12, v13
	s_nop 1
	v_add_f32_dpp v5, v5, v5 quad_perm:[1,0,3,2] row_mask:0xf bank_mask:0xf
	s_nop 1
	v_add_f32_dpp v5, v5, v5 quad_perm:[2,3,0,1] row_mask:0xf bank_mask:0xf
	s_nop 1
	v_add_f32_dpp v5, v5, v5 row_half_mirror row_mask:0xf bank_mask:0xf
	s_nop 1
	v_add_f32_dpp v5, v5, v5 row_mirror row_mask:0xf bank_mask:0xf
	s_nop 1
	v_add_f32_dpp v5, v5, v5 row_bcast:15 row_mask:0xa bank_mask:0xf
	s_nop 1
	v_add_f32_dpp v5, v5, v5 row_bcast:31 row_mask:0xc bank_mask:0xf
	s_nop 1
	v_readlane_b32 s32, v5, 63
	s_nop 1
	v_mov_b32_e32 v6, s32
	v_fmamk_f32 v6, v6, 0x3a800000, v146
	v_rsq_f32_e32 v6, v6
	s_nop 0
	v_mul_f32_e32 v8, 0.5, v6
	v_pk_mul_f32 v[14:15], v[86:87], v[8:9] op_sel_hi:[1,0]
	v_pk_fma_f32 v[70:71], v[22:23], v[14:15], v[70:71]
	v_pk_mul_f32 v[14:15], v[88:89], v[8:9] op_sel_hi:[1,0]
	v_pk_fma_f32 v[72:73], v[24:25], v[14:15], v[72:73]
	v_pk_mul_f32 v[14:15], v[90:91], v[8:9] op_sel_hi:[1,0]
	v_pk_fma_f32 v[74:75], v[26:27], v[14:15], v[74:75]
	v_pk_mul_f32 v[14:15], v[92:93], v[8:9] op_sel_hi:[1,0]
	v_pk_fma_f32 v[76:77], v[28:29], v[14:15], v[76:77]
	v_pk_mul_f32 v[14:15], v[94:95], v[8:9] op_sel_hi:[1,0]
	v_pk_fma_f32 v[78:79], v[30:31], v[14:15], v[78:79]
	v_pk_mul_f32 v[14:15], v[96:97], v[8:9] op_sel_hi:[1,0]
	v_pk_fma_f32 v[80:81], v[32:33], v[14:15], v[80:81]
	v_pk_mul_f32 v[14:15], v[98:99], v[8:9] op_sel_hi:[1,0]
	v_pk_fma_f32 v[82:83], v[34:35], v[14:15], v[82:83]
	v_pk_mul_f32 v[14:15], v[100:101], v[8:9] op_sel_hi:[1,0]
	v_pk_fma_f32 v[84:85], v[36:37], v[14:15], v[84:85]
	v_pk_mul_f32 v[12:13], v[70:71], v[70:71]
	v_pk_fma_f32 v[12:13], v[72:73], v[72:73], v[12:13]
	v_pk_fma_f32 v[12:13], v[74:75], v[74:75], v[12:13]
	v_pk_fma_f32 v[12:13], v[76:77], v[76:77], v[12:13]
	v_pk_fma_f32 v[12:13], v[78:79], v[78:79], v[12:13]
	v_pk_fma_f32 v[12:13], v[80:81], v[80:81], v[12:13]
	v_pk_fma_f32 v[12:13], v[82:83], v[82:83], v[12:13]
	v_pk_fma_f32 v[12:13], v[84:85], v[84:85], v[12:13]
	v_add_f32_e32 v5, v12, v13
	s_nop 1
	v_add_f32_dpp v5, v5, v5 quad_perm:[1,0,3,2] row_mask:0xf bank_mask:0xf
	s_nop 1
	v_add_f32_dpp v5, v5, v5 quad_perm:[2,3,0,1] row_mask:0xf bank_mask:0xf
	s_nop 1
	v_add_f32_dpp v5, v5, v5 row_half_mirror row_mask:0xf bank_mask:0xf
	s_nop 1
	v_add_f32_dpp v5, v5, v5 row_mirror row_mask:0xf bank_mask:0xf
	s_nop 1
	v_add_f32_dpp v5, v5, v5 row_bcast:15 row_mask:0xa bank_mask:0xf
	s_nop 1
	v_add_f32_dpp v5, v5, v5 row_bcast:31 row_mask:0xc bank_mask:0xf
	s_nop 1
	v_readlane_b32 s32, v5, 63
	s_nop 1
	v_mov_b32_e32 v6, s32
	v_fmamk_f32 v6, v6, 0x3a800000, v146
	v_rsq_f32_e32 v6, v6
	s_nop 0
	v_mov_b32_e32 v10, v6
	v_pk_mul_f32 v[14:15], v[70:71], v[10:11] op_sel_hi:[1,0]
	v_pk_fma_f32 v[16:17], v[54:55], v[14:15], v[38:39]
	v_pk_mul_f32 v[14:15], v[72:73], v[10:11] op_sel_hi:[1,0]
	v_pk_fma_f32 v[18:19], v[56:57], v[14:15], v[40:41]
	v_cvt_pk_bf16_f32 v86, v16, v17
	v_cvt_pk_bf16_f32 v87, v18, v19
	v_pk_mul_f32 v[14:15], v[74:75], v[10:11] op_sel_hi:[1,0]
	v_pk_fma_f32 v[16:17], v[58:59], v[14:15], v[42:43]
	v_pk_mul_f32 v[14:15], v[76:77], v[10:11] op_sel_hi:[1,0]
	v_pk_fma_f32 v[18:19], v[60:61], v[14:15], v[44:45]
	v_cvt_pk_bf16_f32 v90, v16, v17
	v_cvt_pk_bf16_f32 v91, v18, v19
	v_pk_mul_f32 v[14:15], v[78:79], v[10:11] op_sel_hi:[1,0]
	v_pk_fma_f32 v[16:17], v[62:63], v[14:15], v[46:47]
	v_pk_mul_f32 v[14:15], v[80:81], v[10:11] op_sel_hi:[1,0]
	v_pk_fma_f32 v[18:19], v[64:65], v[14:15], v[48:49]
	v_cvt_pk_bf16_f32 v94, v16, v17
	v_cvt_pk_bf16_f32 v95, v18, v19
	v_pk_mul_f32 v[14:15], v[82:83], v[10:11] op_sel_hi:[1,0]
	v_pk_fma_f32 v[16:17], v[66:67], v[14:15], v[50:51]
	v_pk_mul_f32 v[14:15], v[84:85], v[10:11] op_sel_hi:[1,0]
	v_pk_fma_f32 v[18:19], v[68:69], v[14:15], v[52:53]
	v_cvt_pk_bf16_f32 v98, v16, v17
	v_cvt_pk_bf16_f32 v99, v18, v19
	global_store_dwordx4 v0, v[70:73], s[46:47] offset:0 sc1
	global_store_dwordx4 v0, v[74:77], s[46:47] offset:1024 sc1
	global_store_dwordx4 v0, v[78:81], s[46:47] offset:2048 sc1
	global_store_dwordx4 v0, v[82:85], s[46:47] offset:3072 sc1
	global_store_dwordx2 v1, v[86:87], s[62:63] offset:0 sc1
	global_store_dwordx2 v1, v[90:91], s[62:63] offset:512 sc1
	global_store_dwordx2 v1, v[94:95], s[62:63] offset:1024 sc1
	global_store_dwordx2 v1, v[98:99], s[62:63] offset:1536 sc1
	s_add_u32 s46, s46, 0x1000
	s_addc_u32 s47, s47, 0
	s_add_u32 s62, s62, 0x800
	s_addc_u32 s63, s63, 0
	s_waitcnt vmcnt(24)
	v_lshlrev_b32_e32 v14, 16, v118
	v_and_b32_e32 v15, 0xffff0000, v118
	v_lshlrev_b32_e32 v16, 16, v120
	v_and_b32_e32 v17, 0xffff0000, v120
	v_lshlrev_b32_e32 v18, 16, v119
	v_and_b32_e32 v19, 0xffff0000, v119
	v_lshlrev_b32_e32 v20, 16, v121
	v_and_b32_e32 v21, 0xffff0000, v121
	v_pk_add_f32 v[118:119], v[14:15], v[16:17]
	v_pk_add_f32 v[120:121], v[18:19], v[20:21]
	v_lshlrev_b32_e32 v14, 16, v122
	v_and_b32_e32 v15, 0xffff0000, v122
	v_lshlrev_b32_e32 v16, 16, v124
	v_and_b32_e32 v17, 0xffff0000, v124
	v_lshlrev_b32_e32 v18, 16, v123
	v_and_b32_e32 v19, 0xffff0000, v123
	v_lshlrev_b32_e32 v20, 16, v125
	v_and_b32_e32 v21, 0xffff0000, v125
	v_pk_add_f32 v[122:123], v[14:15], v[16:17]
	v_pk_add_f32 v[124:125], v[18:19], v[20:21]
	v_lshlrev_b32_e32 v14, 16, v134
	v_and_b32_e32 v15, 0xffff0000, v134
	v_lshlrev_b32_e32 v16, 16, v136
	v_and_b32_e32 v17, 0xffff0000, v136
	v_lshlrev_b32_e32 v18, 16, v135
	v_and_b32_e32 v19, 0xffff0000, v135
	v_lshlrev_b32_e32 v20, 16, v137
	v_and_b32_e32 v21, 0xffff0000, v137
	v_pk_add_f32 v[134:135], v[14:15], v[16:17]
	v_pk_add_f32 v[136:137], v[18:19], v[20:21]
	v_lshlrev_b32_e32 v14, 16, v138
	v_and_b32_e32 v15, 0xffff0000, v138
	v_lshlrev_b32_e32 v16, 16, v140
	v_and_b32_e32 v17, 0xffff0000, v140
	v_lshlrev_b32_e32 v18, 16, v139
	v_and_b32_e32 v19, 0xffff0000, v139
	v_lshlrev_b32_e32 v20, 16, v141
	v_and_b32_e32 v21, 0xffff0000, v141
	v_pk_add_f32 v[138:139], v[14:15], v[16:17]
	v_pk_add_f32 v[140:141], v[18:19], v[20:21]
	v_pk_mul_f32 v[12:13], v[118:119], v[118:119]
	v_pk_fma_f32 v[12:13], v[120:121], v[120:121], v[12:13]
	v_pk_fma_f32 v[12:13], v[122:123], v[122:123], v[12:13]
	v_pk_fma_f32 v[12:13], v[124:125], v[124:125], v[12:13]
	v_pk_fma_f32 v[12:13], v[134:135], v[134:135], v[12:13]
	v_pk_fma_f32 v[12:13], v[136:137], v[136:137], v[12:13]
	v_pk_fma_f32 v[12:13], v[138:139], v[138:139], v[12:13]
	v_pk_fma_f32 v[12:13], v[140:141], v[140:141], v[12:13]
	v_add_f32_e32 v5, v12, v13
	s_nop 1
	v_add_f32_dpp v5, v5, v5 quad_perm:[1,0,3,2] row_mask:0xf bank_mask:0xf
	s_nop 1
	v_add_f32_dpp v5, v5, v5 quad_perm:[2,3,0,1] row_mask:0xf bank_mask:0xf
	s_nop 1
	v_add_f32_dpp v5, v5, v5 row_half_mirror row_mask:0xf bank_mask:0xf
	s_nop 1
	v_add_f32_dpp v5, v5, v5 row_mirror row_mask:0xf bank_mask:0xf
	s_nop 1
	v_add_f32_dpp v5, v5, v5 row_bcast:15 row_mask:0xa bank_mask:0xf
	s_nop 1
	v_add_f32_dpp v5, v5, v5 row_bcast:31 row_mask:0xc bank_mask:0xf
	s_nop 1
	v_readlane_b32 s32, v5, 63
	s_nop 1
	v_mov_b32_e32 v6, s32
	v_fmamk_f32 v6, v6, 0x3a800000, v146
	v_rsq_f32_e32 v6, v6
	s_nop 0
	v_mul_f32_e32 v8, 0.5, v6
	v_pk_mul_f32 v[14:15], v[118:119], v[8:9] op_sel_hi:[1,0]
	v_pk_fma_f32 v[102:103], v[22:23], v[14:15], v[102:103]
	v_pk_mul_f32 v[14:15], v[120:121], v[8:9] op_sel_hi:[1,0]
	v_pk_fma_f32 v[104:105], v[24:25], v[14:15], v[104:105]
	v_pk_mul_f32 v[14:15], v[122:123], v[8:9] op_sel_hi:[1,0]
	v_pk_fma_f32 v[106:107], v[26:27], v[14:15], v[106:107]
	v_pk_mul_f32 v[14:15], v[124:125], v[8:9] op_sel_hi:[1,0]
	v_pk_fma_f32 v[108:109], v[28:29], v[14:15], v[108:109]
	v_pk_mul_f32 v[14:15], v[134:135], v[8:9] op_sel_hi:[1,0]
	v_pk_fma_f32 v[110:111], v[30:31], v[14:15], v[110:111]
	v_pk_mul_f32 v[14:15], v[136:137], v[8:9] op_sel_hi:[1,0]
	v_pk_fma_f32 v[112:113], v[32:33], v[14:15], v[112:113]
	v_pk_mul_f32 v[14:15], v[138:139], v[8:9] op_sel_hi:[1,0]
	v_pk_fma_f32 v[114:115], v[34:35], v[14:15], v[114:115]
	v_pk_mul_f32 v[14:15], v[140:141], v[8:9] op_sel_hi:[1,0]
	v_pk_fma_f32 v[116:117], v[36:37], v[14:15], v[116:117]
	v_pk_mul_f32 v[12:13], v[102:103], v[102:103]
	v_pk_fma_f32 v[12:13], v[104:105], v[104:105], v[12:13]
	v_pk_fma_f32 v[12:13], v[106:107], v[106:107], v[12:13]
	v_pk_fma_f32 v[12:13], v[108:109], v[108:109], v[12:13]
	v_pk_fma_f32 v[12:13], v[110:111], v[110:111], v[12:13]
	v_pk_fma_f32 v[12:13], v[112:113], v[112:113], v[12:13]
	v_pk_fma_f32 v[12:13], v[114:115], v[114:115], v[12:13]
	v_pk_fma_f32 v[12:13], v[116:117], v[116:117], v[12:13]
	v_add_f32_e32 v5, v12, v13
	s_nop 1
	v_add_f32_dpp v5, v5, v5 quad_perm:[1,0,3,2] row_mask:0xf bank_mask:0xf
	s_nop 1
	v_add_f32_dpp v5, v5, v5 quad_perm:[2,3,0,1] row_mask:0xf bank_mask:0xf
	s_nop 1
	v_add_f32_dpp v5, v5, v5 row_half_mirror row_mask:0xf bank_mask:0xf
	s_nop 1
	v_add_f32_dpp v5, v5, v5 row_mirror row_mask:0xf bank_mask:0xf
	s_nop 1
	v_add_f32_dpp v5, v5, v5 row_bcast:15 row_mask:0xa bank_mask:0xf
	s_nop 1
	v_add_f32_dpp v5, v5, v5 row_bcast:31 row_mask:0xc bank_mask:0xf
	s_nop 1
	v_readlane_b32 s32, v5, 63
	s_nop 1
	v_mov_b32_e32 v6, s32
	v_fmamk_f32 v6, v6, 0x3a800000, v146
	v_rsq_f32_e32 v6, v6
	s_nop 0
	v_mov_b32_e32 v10, v6
	v_pk_mul_f32 v[14:15], v[102:103], v[10:11] op_sel_hi:[1,0]
	v_pk_fma_f32 v[16:17], v[54:55], v[14:15], v[38:39]
	v_pk_mul_f32 v[14:15], v[104:105], v[10:11] op_sel_hi:[1,0]
	v_pk_fma_f32 v[18:19], v[56:57], v[14:15], v[40:41]
	v_cvt_pk_bf16_f32 v118, v16, v17
	v_cvt_pk_bf16_f32 v119, v18, v19
	v_pk_mul_f32 v[14:15], v[106:107], v[10:11] op_sel_hi:[1,0]
	v_pk_fma_f32 v[16:17], v[58:59], v[14:15], v[42:43]
	v_pk_mul_f32 v[14:15], v[108:109], v[10:11] op_sel_hi:[1,0]
	v_pk_fma_f32 v[18:19], v[60:61], v[14:15], v[44:45]
	v_cvt_pk_bf16_f32 v122, v16, v17
	v_cvt_pk_bf16_f32 v123, v18, v19
	v_pk_mul_f32 v[14:15], v[110:111], v[10:11] op_sel_hi:[1,0]
	v_pk_fma_f32 v[16:17], v[62:63], v[14:15], v[46:47]
	v_pk_mul_f32 v[14:15], v[112:113], v[10:11] op_sel_hi:[1,0]
	v_pk_fma_f32 v[18:19], v[64:65], v[14:15], v[48:49]
	v_cvt_pk_bf16_f32 v134, v16, v17
	v_cvt_pk_bf16_f32 v135, v18, v19
	v_pk_mul_f32 v[14:15], v[114:115], v[10:11] op_sel_hi:[1,0]
	v_pk_fma_f32 v[16:17], v[66:67], v[14:15], v[50:51]
	v_pk_mul_f32 v[14:15], v[116:117], v[10:11] op_sel_hi:[1,0]
	v_pk_fma_f32 v[18:19], v[68:69], v[14:15], v[52:53]
	v_cvt_pk_bf16_f32 v138, v16, v17
	v_cvt_pk_bf16_f32 v139, v18, v19
	global_store_dwordx4 v0, v[102:105], s[46:47] offset:0 sc1
	global_store_dwordx4 v0, v[106:109], s[46:47] offset:1024 sc1
	global_store_dwordx4 v0, v[110:113], s[46:47] offset:2048 sc1
	global_store_dwordx4 v0, v[114:117], s[46:47] offset:3072 sc1
	global_store_dwordx2 v1, v[118:119], s[62:63] offset:0 sc1
	global_store_dwordx2 v1, v[122:123], s[62:63] offset:512 sc1
	global_store_dwordx2 v1, v[134:135], s[62:63] offset:1024 sc1
	global_store_dwordx2 v1, v[138:139], s[62:63] offset:1536 sc1
	s_add_u32 s46, s46, 0x1000
	s_addc_u32 s47, s47, 0
	s_add_u32 s62, s62, 0x800
	s_addc_u32 s63, s63, 0
	s_waitcnt vmcnt(24)
	v_lshlrev_b32_e32 v14, 16, v172
	v_and_b32_e32 v15, 0xffff0000, v172
	v_lshlrev_b32_e32 v16, 16, v174
	v_and_b32_e32 v17, 0xffff0000, v174
	v_lshlrev_b32_e32 v18, 16, v173
	v_and_b32_e32 v19, 0xffff0000, v173
	v_lshlrev_b32_e32 v20, 16, v175
	v_and_b32_e32 v21, 0xffff0000, v175
	v_pk_add_f32 v[172:173], v[14:15], v[16:17]
	v_pk_add_f32 v[174:175], v[18:19], v[20:21]
	v_lshlrev_b32_e32 v14, 16, v176
	v_and_b32_e32 v15, 0xffff0000, v176
	v_lshlrev_b32_e32 v16, 16, v178
	v_and_b32_e32 v17, 0xffff0000, v178
	v_lshlrev_b32_e32 v18, 16, v177
	v_and_b32_e32 v19, 0xffff0000, v177
	v_lshlrev_b32_e32 v20, 16, v179
	v_and_b32_e32 v21, 0xffff0000, v179
	v_pk_add_f32 v[176:177], v[14:15], v[16:17]
	v_pk_add_f32 v[178:179], v[18:19], v[20:21]
	v_lshlrev_b32_e32 v14, 16, v204
	v_and_b32_e32 v15, 0xffff0000, v204
	v_lshlrev_b32_e32 v16, 16, v206
	v_and_b32_e32 v17, 0xffff0000, v206
	v_lshlrev_b32_e32 v18, 16, v205
	v_and_b32_e32 v19, 0xffff0000, v205
	v_lshlrev_b32_e32 v20, 16, v207
	v_and_b32_e32 v21, 0xffff0000, v207
	v_pk_add_f32 v[204:205], v[14:15], v[16:17]
	v_pk_add_f32 v[206:207], v[18:19], v[20:21]
	v_lshlrev_b32_e32 v14, 16, v214
	v_and_b32_e32 v15, 0xffff0000, v214
	v_lshlrev_b32_e32 v16, 16, v216
	v_and_b32_e32 v17, 0xffff0000, v216
	v_lshlrev_b32_e32 v18, 16, v215
	v_and_b32_e32 v19, 0xffff0000, v215
	v_lshlrev_b32_e32 v20, 16, v217
	v_and_b32_e32 v21, 0xffff0000, v217
	v_pk_add_f32 v[214:215], v[14:15], v[16:17]
	v_pk_add_f32 v[216:217], v[18:19], v[20:21]
	v_pk_mul_f32 v[12:13], v[172:173], v[172:173]
	v_pk_fma_f32 v[12:13], v[174:175], v[174:175], v[12:13]
	v_pk_fma_f32 v[12:13], v[176:177], v[176:177], v[12:13]
	v_pk_fma_f32 v[12:13], v[178:179], v[178:179], v[12:13]
	v_pk_fma_f32 v[12:13], v[204:205], v[204:205], v[12:13]
	v_pk_fma_f32 v[12:13], v[206:207], v[206:207], v[12:13]
	v_pk_fma_f32 v[12:13], v[214:215], v[214:215], v[12:13]
	v_pk_fma_f32 v[12:13], v[216:217], v[216:217], v[12:13]
	v_add_f32_e32 v5, v12, v13
	s_nop 1
	v_add_f32_dpp v5, v5, v5 quad_perm:[1,0,3,2] row_mask:0xf bank_mask:0xf
	s_nop 1
	v_add_f32_dpp v5, v5, v5 quad_perm:[2,3,0,1] row_mask:0xf bank_mask:0xf
	s_nop 1
	v_add_f32_dpp v5, v5, v5 row_half_mirror row_mask:0xf bank_mask:0xf
	s_nop 1
	v_add_f32_dpp v5, v5, v5 row_mirror row_mask:0xf bank_mask:0xf
	s_nop 1
	v_add_f32_dpp v5, v5, v5 row_bcast:15 row_mask:0xa bank_mask:0xf
	s_nop 1
	v_add_f32_dpp v5, v5, v5 row_bcast:31 row_mask:0xc bank_mask:0xf
	s_nop 1
	v_readlane_b32 s32, v5, 63
	s_nop 1
	v_mov_b32_e32 v6, s32
	v_fmamk_f32 v6, v6, 0x3a800000, v146
	v_rsq_f32_e32 v6, v6
	s_nop 0
	v_mul_f32_e32 v8, 0.5, v6
	v_pk_mul_f32 v[14:15], v[172:173], v[8:9] op_sel_hi:[1,0]
	v_pk_fma_f32 v[154:155], v[22:23], v[14:15], v[154:155]
	v_pk_mul_f32 v[14:15], v[174:175], v[8:9] op_sel_hi:[1,0]
	v_pk_fma_f32 v[156:157], v[24:25], v[14:15], v[156:157]
	v_pk_mul_f32 v[14:15], v[176:177], v[8:9] op_sel_hi:[1,0]
	v_pk_fma_f32 v[158:159], v[26:27], v[14:15], v[158:159]
	v_pk_mul_f32 v[14:15], v[178:179], v[8:9] op_sel_hi:[1,0]
	v_pk_fma_f32 v[160:161], v[28:29], v[14:15], v[160:161]
	v_pk_mul_f32 v[14:15], v[204:205], v[8:9] op_sel_hi:[1,0]
	v_pk_fma_f32 v[162:163], v[30:31], v[14:15], v[162:163]
	v_pk_mul_f32 v[14:15], v[206:207], v[8:9] op_sel_hi:[1,0]
	v_pk_fma_f32 v[164:165], v[32:33], v[14:15], v[164:165]
	v_pk_mul_f32 v[14:15], v[214:215], v[8:9] op_sel_hi:[1,0]
	v_pk_fma_f32 v[168:169], v[34:35], v[14:15], v[168:169]
	v_pk_mul_f32 v[14:15], v[216:217], v[8:9] op_sel_hi:[1,0]
	v_pk_fma_f32 v[170:171], v[36:37], v[14:15], v[170:171]
	v_pk_mul_f32 v[12:13], v[154:155], v[154:155]
	v_pk_fma_f32 v[12:13], v[156:157], v[156:157], v[12:13]
	v_pk_fma_f32 v[12:13], v[158:159], v[158:159], v[12:13]
	v_pk_fma_f32 v[12:13], v[160:161], v[160:161], v[12:13]
	v_pk_fma_f32 v[12:13], v[162:163], v[162:163], v[12:13]
	v_pk_fma_f32 v[12:13], v[164:165], v[164:165], v[12:13]
	v_pk_fma_f32 v[12:13], v[168:169], v[168:169], v[12:13]
	v_pk_fma_f32 v[12:13], v[170:171], v[170:171], v[12:13]
	v_add_f32_e32 v5, v12, v13
	s_nop 1
	v_add_f32_dpp v5, v5, v5 quad_perm:[1,0,3,2] row_mask:0xf bank_mask:0xf
	s_nop 1
	v_add_f32_dpp v5, v5, v5 quad_perm:[2,3,0,1] row_mask:0xf bank_mask:0xf
	s_nop 1
	v_add_f32_dpp v5, v5, v5 row_half_mirror row_mask:0xf bank_mask:0xf
	s_nop 1
	v_add_f32_dpp v5, v5, v5 row_mirror row_mask:0xf bank_mask:0xf
	s_nop 1
	v_add_f32_dpp v5, v5, v5 row_bcast:15 row_mask:0xa bank_mask:0xf
	s_nop 1
	v_add_f32_dpp v5, v5, v5 row_bcast:31 row_mask:0xc bank_mask:0xf
	s_nop 1
	v_readlane_b32 s32, v5, 63
	s_nop 1
	v_mov_b32_e32 v6, s32
	v_fmamk_f32 v6, v6, 0x3a800000, v146
	v_rsq_f32_e32 v6, v6
	s_nop 0
	v_mov_b32_e32 v10, v6
	v_pk_mul_f32 v[14:15], v[154:155], v[10:11] op_sel_hi:[1,0]
	v_pk_fma_f32 v[16:17], v[54:55], v[14:15], v[38:39]
	v_pk_mul_f32 v[14:15], v[156:157], v[10:11] op_sel_hi:[1,0]
	v_pk_fma_f32 v[18:19], v[56:57], v[14:15], v[40:41]
	v_cvt_pk_bf16_f32 v172, v16, v17
	v_cvt_pk_bf16_f32 v173, v18, v19
	v_pk_mul_f32 v[14:15], v[158:159], v[10:11] op_sel_hi:[1,0]
	v_pk_fma_f32 v[16:17], v[58:59], v[14:15], v[42:43]
	v_pk_mul_f32 v[14:15], v[160:161], v[10:11] op_sel_hi:[1,0]
	v_pk_fma_f32 v[18:19], v[60:61], v[14:15], v[44:45]
	v_cvt_pk_bf16_f32 v176, v16, v17
	v_cvt_pk_bf16_f32 v177, v18, v19
	v_pk_mul_f32 v[14:15], v[162:163], v[10:11] op_sel_hi:[1,0]
	v_pk_fma_f32 v[16:17], v[62:63], v[14:15], v[46:47]
	v_pk_mul_f32 v[14:15], v[164:165], v[10:11] op_sel_hi:[1,0]
	v_pk_fma_f32 v[18:19], v[64:65], v[14:15], v[48:49]
	v_cvt_pk_bf16_f32 v204, v16, v17
	v_cvt_pk_bf16_f32 v205, v18, v19
	v_pk_mul_f32 v[14:15], v[168:169], v[10:11] op_sel_hi:[1,0]
	v_pk_fma_f32 v[16:17], v[66:67], v[14:15], v[50:51]
	v_pk_mul_f32 v[14:15], v[170:171], v[10:11] op_sel_hi:[1,0]
	v_pk_fma_f32 v[18:19], v[68:69], v[14:15], v[52:53]
	v_cvt_pk_bf16_f32 v214, v16, v17
	v_cvt_pk_bf16_f32 v215, v18, v19
	global_store_dwordx4 v0, v[154:157], s[46:47] offset:0 sc1
	global_store_dwordx4 v0, v[158:161], s[46:47] offset:1024 sc1
	global_store_dwordx4 v0, v[162:165], s[46:47] offset:2048 sc1
	global_store_dwordx4 v0, v[168:171], s[46:47] offset:3072 sc1
	global_store_dwordx2 v1, v[172:173], s[62:63] offset:0 sc1
	global_store_dwordx2 v1, v[176:177], s[62:63] offset:512 sc1
	global_store_dwordx2 v1, v[204:205], s[62:63] offset:1024 sc1
	global_store_dwordx2 v1, v[214:215], s[62:63] offset:1536 sc1
	s_add_u32 s46, s46, 0x1000
	s_addc_u32 s47, s47, 0
	s_add_u32 s62, s62, 0x800
	s_addc_u32 s63, s63, 0
	s_waitcnt vmcnt(24)
	v_lshlrev_b32_e32 v14, 16, v234
	v_and_b32_e32 v15, 0xffff0000, v234
	v_lshlrev_b32_e32 v16, 16, v236
	v_and_b32_e32 v17, 0xffff0000, v236
	v_lshlrev_b32_e32 v18, 16, v235
	v_and_b32_e32 v19, 0xffff0000, v235
	v_lshlrev_b32_e32 v20, 16, v237
	v_and_b32_e32 v21, 0xffff0000, v237
	v_pk_add_f32 v[234:235], v[14:15], v[16:17]
	v_pk_add_f32 v[236:237], v[18:19], v[20:21]
	v_lshlrev_b32_e32 v14, 16, v238
	v_and_b32_e32 v15, 0xffff0000, v238
	v_lshlrev_b32_e32 v16, 16, v240
	v_and_b32_e32 v17, 0xffff0000, v240
	v_lshlrev_b32_e32 v18, 16, v239
	v_and_b32_e32 v19, 0xffff0000, v239
	v_lshlrev_b32_e32 v20, 16, v241
	v_and_b32_e32 v21, 0xffff0000, v241
	v_pk_add_f32 v[238:239], v[14:15], v[16:17]
	v_pk_add_f32 v[240:241], v[18:19], v[20:21]
	v_lshlrev_b32_e32 v14, 16, v242
	v_and_b32_e32 v15, 0xffff0000, v242
	v_lshlrev_b32_e32 v16, 16, v244
	v_and_b32_e32 v17, 0xffff0000, v244
	v_lshlrev_b32_e32 v18, 16, v243
	v_and_b32_e32 v19, 0xffff0000, v243
	v_lshlrev_b32_e32 v20, 16, v245
	v_and_b32_e32 v21, 0xffff0000, v245
	v_pk_add_f32 v[242:243], v[14:15], v[16:17]
	v_pk_add_f32 v[244:245], v[18:19], v[20:21]
	v_lshlrev_b32_e32 v14, 16, v246
	v_and_b32_e32 v15, 0xffff0000, v246
	v_lshlrev_b32_e32 v16, 16, v248
	v_and_b32_e32 v17, 0xffff0000, v248
	v_lshlrev_b32_e32 v18, 16, v247
	v_and_b32_e32 v19, 0xffff0000, v247
	v_lshlrev_b32_e32 v20, 16, v249
	v_and_b32_e32 v21, 0xffff0000, v249
	v_pk_add_f32 v[246:247], v[14:15], v[16:17]
	v_pk_add_f32 v[248:249], v[18:19], v[20:21]
	v_pk_mul_f32 v[12:13], v[234:235], v[234:235]
	v_pk_fma_f32 v[12:13], v[236:237], v[236:237], v[12:13]
	v_pk_fma_f32 v[12:13], v[238:239], v[238:239], v[12:13]
	v_pk_fma_f32 v[12:13], v[240:241], v[240:241], v[12:13]
	v_pk_fma_f32 v[12:13], v[242:243], v[242:243], v[12:13]
	v_pk_fma_f32 v[12:13], v[244:245], v[244:245], v[12:13]
	v_pk_fma_f32 v[12:13], v[246:247], v[246:247], v[12:13]
	v_pk_fma_f32 v[12:13], v[248:249], v[248:249], v[12:13]
	v_add_f32_e32 v5, v12, v13
	s_nop 1
	v_add_f32_dpp v5, v5, v5 quad_perm:[1,0,3,2] row_mask:0xf bank_mask:0xf
	s_nop 1
	v_add_f32_dpp v5, v5, v5 quad_perm:[2,3,0,1] row_mask:0xf bank_mask:0xf
	s_nop 1
	v_add_f32_dpp v5, v5, v5 row_half_mirror row_mask:0xf bank_mask:0xf
	s_nop 1
	v_add_f32_dpp v5, v5, v5 row_mirror row_mask:0xf bank_mask:0xf
	s_nop 1
	v_add_f32_dpp v5, v5, v5 row_bcast:15 row_mask:0xa bank_mask:0xf
	s_nop 1
	v_add_f32_dpp v5, v5, v5 row_bcast:31 row_mask:0xc bank_mask:0xf
	s_nop 1
	v_readlane_b32 s32, v5, 63
	s_nop 1
	v_mov_b32_e32 v6, s32
	v_fmamk_f32 v6, v6, 0x3a800000, v146
	v_rsq_f32_e32 v6, v6
	s_nop 0
	v_mul_f32_e32 v8, 0.5, v6
	v_pk_mul_f32 v[14:15], v[234:235], v[8:9] op_sel_hi:[1,0]
	v_pk_fma_f32 v[218:219], v[22:23], v[14:15], v[218:219]
	v_pk_mul_f32 v[14:15], v[236:237], v[8:9] op_sel_hi:[1,0]
	v_pk_fma_f32 v[220:221], v[24:25], v[14:15], v[220:221]
	v_pk_mul_f32 v[14:15], v[238:239], v[8:9] op_sel_hi:[1,0]
	v_pk_fma_f32 v[222:223], v[26:27], v[14:15], v[222:223]
	v_pk_mul_f32 v[14:15], v[240:241], v[8:9] op_sel_hi:[1,0]
	v_pk_fma_f32 v[224:225], v[28:29], v[14:15], v[224:225]
	v_pk_mul_f32 v[14:15], v[242:243], v[8:9] op_sel_hi:[1,0]
	v_pk_fma_f32 v[226:227], v[30:31], v[14:15], v[226:227]
	v_pk_mul_f32 v[14:15], v[244:245], v[8:9] op_sel_hi:[1,0]
	v_pk_fma_f32 v[228:229], v[32:33], v[14:15], v[228:229]
	v_pk_mul_f32 v[14:15], v[246:247], v[8:9] op_sel_hi:[1,0]
	v_pk_fma_f32 v[230:231], v[34:35], v[14:15], v[230:231]
	v_pk_mul_f32 v[14:15], v[248:249], v[8:9] op_sel_hi:[1,0]
	v_pk_fma_f32 v[232:233], v[36:37], v[14:15], v[232:233]
	v_pk_mul_f32 v[12:13], v[218:219], v[218:219]
	v_pk_fma_f32 v[12:13], v[220:221], v[220:221], v[12:13]
	v_pk_fma_f32 v[12:13], v[222:223], v[222:223], v[12:13]
	v_pk_fma_f32 v[12:13], v[224:225], v[224:225], v[12:13]
	v_pk_fma_f32 v[12:13], v[226:227], v[226:227], v[12:13]
	v_pk_fma_f32 v[12:13], v[228:229], v[228:229], v[12:13]
	v_pk_fma_f32 v[12:13], v[230:231], v[230:231], v[12:13]
	v_pk_fma_f32 v[12:13], v[232:233], v[232:233], v[12:13]
	v_add_f32_e32 v5, v12, v13
	s_nop 1
	v_add_f32_dpp v5, v5, v5 quad_perm:[1,0,3,2] row_mask:0xf bank_mask:0xf
	s_nop 1
	v_add_f32_dpp v5, v5, v5 quad_perm:[2,3,0,1] row_mask:0xf bank_mask:0xf
	s_nop 1
	v_add_f32_dpp v5, v5, v5 row_half_mirror row_mask:0xf bank_mask:0xf
	s_nop 1
	v_add_f32_dpp v5, v5, v5 row_mirror row_mask:0xf bank_mask:0xf
	s_nop 1
	v_add_f32_dpp v5, v5, v5 row_bcast:15 row_mask:0xa bank_mask:0xf
	s_nop 1
	v_add_f32_dpp v5, v5, v5 row_bcast:31 row_mask:0xc bank_mask:0xf
	s_nop 1
	v_readlane_b32 s32, v5, 63
	s_nop 1
	v_mov_b32_e32 v6, s32
	v_fmamk_f32 v6, v6, 0x3a800000, v146
	v_rsq_f32_e32 v6, v6
	s_nop 0
	v_mov_b32_e32 v10, v6
	v_pk_mul_f32 v[14:15], v[218:219], v[10:11] op_sel_hi:[1,0]
	v_pk_fma_f32 v[16:17], v[54:55], v[14:15], v[38:39]
	v_pk_mul_f32 v[14:15], v[220:221], v[10:11] op_sel_hi:[1,0]
	v_pk_fma_f32 v[18:19], v[56:57], v[14:15], v[40:41]
	v_cvt_pk_bf16_f32 v234, v16, v17
	v_cvt_pk_bf16_f32 v235, v18, v19
	v_pk_mul_f32 v[14:15], v[222:223], v[10:11] op_sel_hi:[1,0]
	v_pk_fma_f32 v[16:17], v[58:59], v[14:15], v[42:43]
	v_pk_mul_f32 v[14:15], v[224:225], v[10:11] op_sel_hi:[1,0]
	v_pk_fma_f32 v[18:19], v[60:61], v[14:15], v[44:45]
	v_cvt_pk_bf16_f32 v238, v16, v17
	v_cvt_pk_bf16_f32 v239, v18, v19
	v_pk_mul_f32 v[14:15], v[226:227], v[10:11] op_sel_hi:[1,0]
	v_pk_fma_f32 v[16:17], v[62:63], v[14:15], v[46:47]
	v_pk_mul_f32 v[14:15], v[228:229], v[10:11] op_sel_hi:[1,0]
	v_pk_fma_f32 v[18:19], v[64:65], v[14:15], v[48:49]
	v_cvt_pk_bf16_f32 v242, v16, v17
	v_cvt_pk_bf16_f32 v243, v18, v19
	v_pk_mul_f32 v[14:15], v[230:231], v[10:11] op_sel_hi:[1,0]
	v_pk_fma_f32 v[16:17], v[66:67], v[14:15], v[50:51]
	v_pk_mul_f32 v[14:15], v[232:233], v[10:11] op_sel_hi:[1,0]
	v_pk_fma_f32 v[18:19], v[68:69], v[14:15], v[52:53]
	v_cvt_pk_bf16_f32 v246, v16, v17
	v_cvt_pk_bf16_f32 v247, v18, v19
	global_store_dwordx4 v0, v[218:221], s[46:47] offset:0 sc1
	global_store_dwordx4 v0, v[222:225], s[46:47] offset:1024 sc1
	global_store_dwordx4 v0, v[226:229], s[46:47] offset:2048 sc1
	global_store_dwordx4 v0, v[230:233], s[46:47] offset:3072 sc1
	global_store_dwordx2 v1, v[234:235], s[62:63] offset:0 sc1
	global_store_dwordx2 v1, v[238:239], s[62:63] offset:512 sc1
	global_store_dwordx2 v1, v[242:243], s[62:63] offset:1024 sc1
	global_store_dwordx2 v1, v[246:247], s[62:63] offset:1536 sc1
	s_add_u32 s46, s46, 0x1000
	s_addc_u32 s47, s47, 0
	s_add_u32 s62, s62, 0x800
	s_addc_u32 s63, s63, 0
	s_branch .Lnorm0_done

.LBB0_519:
	s_or_b64 exec, exec, s[4:5]
	s_mov_b64 s[4:5], -1
	v_writelane_b32 v255, s4, 19
	s_and_b64 vcc, exec, s[10:11]
	s_waitcnt lgkmcnt(0)
	v_writelane_b32 v255, s5, 20
	s_mov_b64 s[4:5], -1
	s_barrier
	s_cbranch_vccz .LBB0_335
	s_mov_b64 s[16:17], s[0:1]
	v_mov_b32_e32 v0, v147
	v_readlane_b32 s2, v255, 0
	s_nop 0
	v_ashrrev_i32_e32 v1, 6, v0
	v_lshl_add_u32 v16, s2, 3, v1
	s_movk_i32 s2, 0x2000
	v_cmp_gt_i32_e32 vcc, s2, v16
	s_and_saveexec_b64 s[8:9], vcc
	s_cbranch_execz .LBB0_523
	s_load_dwordx4 s[4:7], s[16:17], 0x90
	s_load_dwordx4 s[12:15], s[16:17], 0x40
	v_lshlrev_b32_e32 v1, 2, v0
	v_cmp_lt_i32_e32 vcc, v188, v183
	v_and_b32_e32 v2, 0xfc, v1
	s_mul_i32 s2, s70, 0x2d000
	v_cndmask_b32_e32 v1, v182, v188, vcc
	v_cmp_lt_i32_e32 vcc, v254, v183
	s_waitcnt lgkmcnt(0)
	s_add_u32 s18, s6, s2
	s_mul_hi_u32 s2, s70, 0x2d000
	v_lshlrev_b32_e32 v28, 2, v1
	v_cndmask_b32_e32 v1, v182, v254, vcc
	s_addc_u32 s19, s7, s2
	v_readlane_b32 s20, v255, 12
	v_lshlrev_b32_e32 v29, 2, v1
	v_xor_b32_e32 v1, 4, v182
	s_add_u32 s10, s18, 0x103000
	v_readlane_b32 s21, v255, 13
	v_cmp_lt_i32_e32 vcc, v1, v183
	s_addc_u32 s11, s19, 0
	s_lshl_b64 s[20:21], s[20:21], 2
	v_cndmask_b32_e32 v1, v182, v1, vcc
	s_add_u32 s12, s12, s20
	v_lshlrev_b32_e32 v144, 2, v2
	v_lshlrev_b32_e32 v30, 2, v1
	v_xor_b32_e32 v1, 8, v182
	s_addc_u32 s13, s13, s21
	v_lshl_add_u64 v[4:5], s[18:19], 0, v[144:145]
	s_mov_b64 s[18:19], 0x102000
	v_cmp_lt_i32_e32 vcc, v1, v183
	v_lshl_add_u64 v[18:19], v[4:5], 0, s[18:19]
	v_lshl_add_u64 v[4:5], s[12:13], 0, v[144:145]
	v_cndmask_b32_e32 v1, v182, v1, vcc
	v_cmp_lt_i32_e32 vcc, v187, v183
	v_ashrrev_i32_e32 v17, 31, v16
	v_lshl_add_u64 v[22:23], v[4:5], 0, s[94:95]
	v_lshlrev_b32_e32 v31, 2, v1
	v_cndmask_b32_e32 v1, v182, v187, vcc
	v_cmp_lt_i32_e32 vcc, v184, v183
	v_lshlrev_b64 v[4:5], 11, v[16:17]
	v_and_b32_e32 v3, 63, v0
	v_lshlrev_b32_e32 v32, 2, v1
	v_cndmask_b32_e32 v1, v182, v184, vcc
	v_lshl_or_b32 v4, v3, 3, v4
	v_lshlrev_b32_e32 v33, 2, v1
	v_lshl_add_u64 v[0:1], s[6:7], 0, v[4:5]
	s_mov_b64 s[6:7], 0x9800600
	s_add_u32 s14, s14, s20
	v_lshl_add_u64 v[24:25], v[0:1], 0, s[6:7]
	v_lshlrev_b64 v[0:1], 12, v[16:17]
	s_addc_u32 s15, s15, s21
	v_lshl_or_b32 v0, v3, 4, v0
	v_lshl_add_u64 v[20:21], s[14:15], 0, v[144:145]
	v_lshl_add_u64 v[26:27], s[4:5], 0, v[0:1]
	s_mov_b64 s[4:5], 0
	v_lshlrev_b32_e32 v144, 2, v2
	v_readlane_b32 s2, v255, 0
	v_readfirstlane_b32 s7, v147
	s_load_dwordx2 s[4:5], s[16:17], 0x90
	s_load_dwordx2 s[12:13], s[16:17], 0x98
	s_load_dwordx2 s[14:15], s[16:17], 0x40
	s_load_dwordx2 s[40:41], s[16:17], 0x48
	v_and_b32_e32 v0, 63, v147
	v_lshlrev_b32_e32 v1, 3, v0
	v_lshlrev_b32_e32 v0, 4, v0
	s_lshr_b32 s7, s7, 6
	s_and_b32 s27, s2, 6
	s_lshl_b32 s27, s27, 5
	s_and_b32 s37, s2, 0x39
	s_or_b32 s27, s27, s37
	s_lshr_b32 s37, s2, 6
	s_lshl_b32 s37, s37, 1
	s_or_b32 s2, s27, s37
	s_lshl_b32 s2, s2, 3
	s_add_u32 s2, s2, s7
	s_lshl_b32 s24, s2, 2
	s_sub_u32 s27, s24, 0x1000
	s_lshr_b32 s27, s27, 10
	s_add_u32 s27, s27, 1
	s_cmp_lt_u32 s24, 0x1000
	s_cselect_b32 s30, 0, s27
	v_add_u32_e32 v2, 0x2000, v0
	v_add_u32_e32 v3, 0x3000, v0
	v_add_u32_e32 v4, 0x4000, v0
	s_waitcnt lgkmcnt(0)
	s_lshl_b32 s27, s24, 11
	s_add_u32 s62, s12, s27
	s_addc_u32 s63, s13, 0
	s_add_u32 s58, s62, 0x8800000
	s_addc_u32 s59, s63, 0
	s_add_u32 s60, s58, 0x1000000
	s_addc_u32 s61, s59, 0
	s_add_u32 s62, s62, 0x1000000
	s_addc_u32 s63, s63, 0
	s_lshl_b32 s27, s24, 12
	s_add_u32 s46, s4, s27
	s_addc_u32 s47, s5, 0
	s_mov_b64 s[4:5], s[46:47]
	s_mul_i32 s27, s70, 5
	s_add_u32 s27, s27, s30
	s_mul_i32 s27, s27, 0x9000
	s_add_u32 s27, s27, 0x100000
	s_add_u32 s88, s12, s27
	s_addc_u32 s89, s13, 0
	s_mov_b64 s[100:101], s[88:89]
	s_mul_i32 s27, s70, 0x3000
	s_add_u32 s40, s40, s27
	s_addc_u32 s41, s41, 0
	s_mul_i32 s27, s70, 0x3000
	s_add_u32 s27, s27, 0x1000
	s_add_u32 s14, s14, s27
	s_addc_u32 s15, s15, 0
	global_load_dwordx4 v[22:25], v2, s[100:101] offset:0
	global_load_dwordx4 v[172:175], v0, s[40:41] offset:0
	global_load_dwordx4 v[38:41], v3, s[88:89] offset:0
	global_load_dwordx4 v[54:57], v4, s[88:89] offset:0
	global_load_dwordx4 v[234:237], v0, s[14:15] offset:0
	global_load_dwordx4 v[26:29], v2, s[100:101] offset:1024
	global_load_dwordx4 v[176:179], v0, s[40:41] offset:1024
	global_load_dwordx4 v[42:45], v3, s[88:89] offset:1024
	global_load_dwordx4 v[58:61], v4, s[88:89] offset:1024
	global_load_dwordx4 v[238:241], v0, s[14:15] offset:1024
	global_load_dwordx4 v[30:33], v2, s[100:101] offset:2048
	global_load_dwordx4 v[204:207], v0, s[40:41] offset:2048
	global_load_dwordx4 v[46:49], v3, s[88:89] offset:2048
	global_load_dwordx4 v[62:65], v4, s[88:89] offset:2048
	global_load_dwordx4 v[242:245], v0, s[14:15] offset:2048
	global_load_dwordx4 v[34:37], v2, s[100:101] offset:3072
	global_load_dwordx4 v[214:217], v0, s[40:41] offset:3072
	global_load_dwordx4 v[50:53], v3, s[88:89] offset:3072
	global_load_dwordx4 v[66:69], v4, s[88:89] offset:3072
	global_load_dwordx4 v[246:249], v0, s[14:15] offset:3072
	global_load_dwordx4 v[70:73], v0, s[4:5] offset:0
	global_load_dwordx4 v[74:77], v0, s[4:5] offset:1024
	global_load_dwordx4 v[78:81], v0, s[4:5] offset:2048
	global_load_dwordx4 v[82:85], v0, s[4:5] offset:3072
	s_add_u32 s4, s4, 0x1000
	s_addc_u32 s5, s5, 0
	global_load_dwordx4 v[102:105], v0, s[4:5] offset:0
	global_load_dwordx4 v[106:109], v0, s[4:5] offset:1024
	global_load_dwordx4 v[110:113], v0, s[4:5] offset:2048
	global_load_dwordx4 v[114:117], v0, s[4:5] offset:3072
	s_add_u32 s4, s4, 0x1000
	s_addc_u32 s5, s5, 0
	global_load_dwordx4 v[154:157], v0, s[4:5] offset:0
	global_load_dwordx4 v[158:161], v0, s[4:5] offset:1024
	global_load_dwordx4 v[162:165], v0, s[4:5] offset:2048
	global_load_dwordx4 v[168:171], v0, s[4:5] offset:3072
	s_add_u32 s4, s4, 0x1000
	s_addc_u32 s5, s5, 0
	global_load_dwordx4 v[218:221], v0, s[4:5] offset:0
	global_load_dwordx4 v[222:225], v0, s[4:5] offset:1024
	global_load_dwordx4 v[226:229], v0, s[4:5] offset:2048
	global_load_dwordx4 v[230:233], v0, s[4:5] offset:3072
	s_add_u32 s4, s4, 0x1000
	s_addc_u32 s5, s5, 0
	s_waitcnt vmcnt(16)
	v_pk_mul_f32 v[22:23], v[22:23], v[172:173]
	v_pk_mul_f32 v[24:25], v[24:25], v[174:175]
	v_pk_mul_f32 v[26:27], v[26:27], v[176:177]
	v_pk_mul_f32 v[28:29], v[28:29], v[178:179]
	v_pk_mul_f32 v[30:31], v[30:31], v[204:205]
	v_pk_mul_f32 v[32:33], v[32:33], v[206:207]
	v_pk_mul_f32 v[34:35], v[34:35], v[214:215]
	v_pk_mul_f32 v[36:37], v[36:37], v[216:217]
	v_pk_add_f32 v[54:55], v[54:55], 1.0 op_sel_hi:[1,0]
	v_pk_mul_f32 v[54:55], v[54:55], v[234:235]
	v_pk_add_f32 v[56:57], v[56:57], 1.0 op_sel_hi:[1,0]
	v_pk_mul_f32 v[56:57], v[56:57], v[236:237]
	v_pk_add_f32 v[58:59], v[58:59], 1.0 op_sel_hi:[1,0]
	v_pk_mul_f32 v[58:59], v[58:59], v[238:239]
	v_pk_add_f32 v[60:61], v[60:61], 1.0 op_sel_hi:[1,0]
	v_pk_mul_f32 v[60:61], v[60:61], v[240:241]
	v_pk_add_f32 v[62:63], v[62:63], 1.0 op_sel_hi:[1,0]
	v_pk_mul_f32 v[62:63], v[62:63], v[242:243]
	v_pk_add_f32 v[64:65], v[64:65], 1.0 op_sel_hi:[1,0]
	v_pk_mul_f32 v[64:65], v[64:65], v[244:245]
	v_pk_add_f32 v[66:67], v[66:67], 1.0 op_sel_hi:[1,0]
	v_pk_mul_f32 v[66:67], v[66:67], v[246:247]
	v_pk_add_f32 v[68:69], v[68:69], 1.0 op_sel_hi:[1,0]
	v_pk_mul_f32 v[68:69], v[68:69], v[248:249]
	v_cmp_eq_u32_e32 vcc, 0, v147
	s_and_saveexec_b64 s[40:41], vcc
	s_cbranch_execz .Lnw_skip_n1
	v_readlane_b32 s2, v255, 0
	v_readlane_b32 s7, v255, 46
	s_nop 0
	s_lshr_b32 s24, s2, 3
	s_and_b32 s24, s24, 7
	s_and_b32 s27, s2, 6
	s_lshl_b32 s27, s27, 2
	s_or_b32 s27, s27, s24
	s_lshl_b32 s27, s27, 7
	s_add_u32 s27, s27, 0xa000
	v_mov_b32_e32 v14, s27
	s_mov_b32 s30, 0

.Lnw_skip_n1:
	s_or_b64 exec, exec, s[40:41]
	s_barrier
	global_load_dwordx2 v[86:87], v1, s[58:59] offset:0
	global_load_dwordx2 v[90:91], v1, s[58:59] offset:512
	global_load_dwordx2 v[94:95], v1, s[58:59] offset:1024
	global_load_dwordx2 v[98:99], v1, s[58:59] offset:1536
	global_load_dwordx2 v[88:89], v1, s[60:61] offset:0
	global_load_dwordx2 v[92:93], v1, s[60:61] offset:512
	global_load_dwordx2 v[96:97], v1, s[60:61] offset:1024
	global_load_dwordx2 v[100:101], v1, s[60:61] offset:1536
	s_add_u32 s58, s58, 0x800
	s_addc_u32 s59, s59, 0
	s_add_u32 s60, s60, 0x800
	s_addc_u32 s61, s61, 0
	global_load_dwordx2 v[118:119], v1, s[58:59] offset:0
	global_load_dwordx2 v[122:123], v1, s[58:59] offset:512
	global_load_dwordx2 v[134:135], v1, s[58:59] offset:1024
	global_load_dwordx2 v[138:139], v1, s[58:59] offset:1536
	global_load_dwordx2 v[120:121], v1, s[60:61] offset:0
	global_load_dwordx2 v[124:125], v1, s[60:61] offset:512
	global_load_dwordx2 v[136:137], v1, s[60:61] offset:1024
	global_load_dwordx2 v[140:141], v1, s[60:61] offset:1536
	s_add_u32 s58, s58, 0x800
	s_addc_u32 s59, s59, 0
	s_add_u32 s60, s60, 0x800
	s_addc_u32 s61, s61, 0
	global_load_dwordx2 v[172:173], v1, s[58:59] offset:0
	global_load_dwordx2 v[176:177], v1, s[58:59] offset:512
	global_load_dwordx2 v[204:205], v1, s[58:59] offset:1024
	global_load_dwordx2 v[214:215], v1, s[58:59] offset:1536
	global_load_dwordx2 v[174:175], v1, s[60:61] offset:0
	global_load_dwordx2 v[178:179], v1, s[60:61] offset:512
	global_load_dwordx2 v[206:207], v1, s[60:61] offset:1024
	global_load_dwordx2 v[216:217], v1, s[60:61] offset:1536
	s_add_u32 s58, s58, 0x800
	s_addc_u32 s59, s59, 0
	s_add_u32 s60, s60, 0x800
	s_addc_u32 s61, s61, 0
	global_load_dwordx2 v[234:235], v1, s[58:59] offset:0
	global_load_dwordx2 v[238:239], v1, s[58:59] offset:512
	global_load_dwordx2 v[242:243], v1, s[58:59] offset:1024
	global_load_dwordx2 v[246:247], v1, s[58:59] offset:1536
	global_load_dwordx2 v[236:237], v1, s[60:61] offset:0
	global_load_dwordx2 v[240:241], v1, s[60:61] offset:512
	global_load_dwordx2 v[244:245], v1, s[60:61] offset:1024
	global_load_dwordx2 v[248:249], v1, s[60:61] offset:1536
	s_add_u32 s58, s58, 0x800
	s_addc_u32 s59, s59, 0
	s_add_u32 s60, s60, 0x800
	s_addc_u32 s61, s61, 0
	s_waitcnt vmcnt(24)
	v_lshlrev_b32_e32 v14, 16, v86
	v_and_b32_e32 v15, 0xffff0000, v86
	v_lshlrev_b32_e32 v16, 16, v88
	v_and_b32_e32 v17, 0xffff0000, v88
	v_lshlrev_b32_e32 v18, 16, v87
	v_and_b32_e32 v19, 0xffff0000, v87
	v_lshlrev_b32_e32 v20, 16, v89
	v_and_b32_e32 v21, 0xffff0000, v89
	v_pk_add_f32 v[86:87], v[14:15], v[16:17]
	v_pk_add_f32 v[88:89], v[18:19], v[20:21]
	v_lshlrev_b32_e32 v14, 16, v90
	v_and_b32_e32 v15, 0xffff0000, v90
	v_lshlrev_b32_e32 v16, 16, v92
	v_and_b32_e32 v17, 0xffff0000, v92
	v_lshlrev_b32_e32 v18, 16, v91
	v_and_b32_e32 v19, 0xffff0000, v91
	v_lshlrev_b32_e32 v20, 16, v93
	v_and_b32_e32 v21, 0xffff0000, v93
	v_pk_add_f32 v[90:91], v[14:15], v[16:17]
	v_pk_add_f32 v[92:93], v[18:19], v[20:21]
	v_lshlrev_b32_e32 v14, 16, v94
	v_and_b32_e32 v15, 0xffff0000, v94
	v_lshlrev_b32_e32 v16, 16, v96
	v_and_b32_e32 v17, 0xffff0000, v96
	v_lshlrev_b32_e32 v18, 16, v95
	v_and_b32_e32 v19, 0xffff0000, v95
	v_lshlrev_b32_e32 v20, 16, v97
	v_and_b32_e32 v21, 0xffff0000, v97
	v_pk_add_f32 v[94:95], v[14:15], v[16:17]
	v_pk_add_f32 v[96:97], v[18:19], v[20:21]
	v_lshlrev_b32_e32 v14, 16, v98
	v_and_b32_e32 v15, 0xffff0000, v98
	v_lshlrev_b32_e32 v16, 16, v100
	v_and_b32_e32 v17, 0xffff0000, v100
	v_lshlrev_b32_e32 v18, 16, v99
	v_and_b32_e32 v19, 0xffff0000, v99
	v_lshlrev_b32_e32 v20, 16, v101
	v_and_b32_e32 v21, 0xffff0000, v101
	v_pk_add_f32 v[98:99], v[14:15], v[16:17]
	v_pk_add_f32 v[100:101], v[18:19], v[20:21]
	v_pk_mul_f32 v[12:13], v[86:87], v[86:87]
	v_pk_fma_f32 v[12:13], v[88:89], v[88:89], v[12:13]
	v_pk_fma_f32 v[12:13], v[90:91], v[90:91], v[12:13]
	v_pk_fma_f32 v[12:13], v[92:93], v[92:93], v[12:13]
	v_pk_fma_f32 v[12:13], v[94:95], v[94:95], v[12:13]
	v_pk_fma_f32 v[12:13], v[96:97], v[96:97], v[12:13]
	v_pk_fma_f32 v[12:13], v[98:99], v[98:99], v[12:13]
	v_pk_fma_f32 v[12:13], v[100:101], v[100:101], v[12:13]
	v_add_f32_e32 v5, v12, v13
	s_nop 1
	v_add_f32_dpp v5, v5, v5 quad_perm:[1,0,3,2] row_mask:0xf bank_mask:0xf
	s_nop 1
	v_add_f32_dpp v5, v5, v5 quad_perm:[2,3,0,1] row_mask:0xf bank_mask:0xf
	s_nop 1
	v_add_f32_dpp v5, v5, v5 row_half_mirror row_mask:0xf bank_mask:0xf
	s_nop 1
	v_add_f32_dpp v5, v5, v5 row_mirror row_mask:0xf bank_mask:0xf
	s_nop 1
	v_add_f32_dpp v5, v5, v5 row_bcast:15 row_mask:0xa bank_mask:0xf
	s_nop 1
	v_add_f32_dpp v5, v5, v5 row_bcast:31 row_mask:0xc bank_mask:0xf
	s_nop 1
	v_readlane_b32 s32, v5, 63
	s_nop 1
	v_mov_b32_e32 v6, s32
	v_fmamk_f32 v6, v6, 0x3a800000, v146
	v_rsq_f32_e32 v6, v6
	s_nop 0
	v_mul_f32_e32 v8, 0.5, v6
	v_pk_mul_f32 v[14:15], v[86:87], v[8:9] op_sel_hi:[1,0]
	v_pk_fma_f32 v[70:71], v[22:23], v[14:15], v[70:71]
	v_pk_mul_f32 v[14:15], v[88:89], v[8:9] op_sel_hi:[1,0]
	v_pk_fma_f32 v[72:73], v[24:25], v[14:15], v[72:73]
	v_pk_mul_f32 v[14:15], v[90:91], v[8:9] op_sel_hi:[1,0]
	v_pk_fma_f32 v[74:75], v[26:27], v[14:15], v[74:75]
	v_pk_mul_f32 v[14:15], v[92:93], v[8:9] op_sel_hi:[1,0]
	v_pk_fma_f32 v[76:77], v[28:29], v[14:15], v[76:77]
	v_pk_mul_f32 v[14:15], v[94:95], v[8:9] op_sel_hi:[1,0]
	v_pk_fma_f32 v[78:79], v[30:31], v[14:15], v[78:79]
	v_pk_mul_f32 v[14:15], v[96:97], v[8:9] op_sel_hi:[1,0]
	v_pk_fma_f32 v[80:81], v[32:33], v[14:15], v[80:81]
	v_pk_mul_f32 v[14:15], v[98:99], v[8:9] op_sel_hi:[1,0]
	v_pk_fma_f32 v[82:83], v[34:35], v[14:15], v[82:83]
	v_pk_mul_f32 v[14:15], v[100:101], v[8:9] op_sel_hi:[1,0]
	v_pk_fma_f32 v[84:85], v[36:37], v[14:15], v[84:85]
	v_pk_mul_f32 v[12:13], v[70:71], v[70:71]
	v_pk_fma_f32 v[12:13], v[72:73], v[72:73], v[12:13]
	v_pk_fma_f32 v[12:13], v[74:75], v[74:75], v[12:13]
	v_pk_fma_f32 v[12:13], v[76:77], v[76:77], v[12:13]
	v_pk_fma_f32 v[12:13], v[78:79], v[78:79], v[12:13]
	v_pk_fma_f32 v[12:13], v[80:81], v[80:81], v[12:13]
	v_pk_fma_f32 v[12:13], v[82:83], v[82:83], v[12:13]
	v_pk_fma_f32 v[12:13], v[84:85], v[84:85], v[12:13]
	v_add_f32_e32 v5, v12, v13
	s_nop 1
	v_add_f32_dpp v5, v5, v5 quad_perm:[1,0,3,2] row_mask:0xf bank_mask:0xf
	s_nop 1
	v_add_f32_dpp v5, v5, v5 quad_perm:[2,3,0,1] row_mask:0xf bank_mask:0xf
	s_nop 1
	v_add_f32_dpp v5, v5, v5 row_half_mirror row_mask:0xf bank_mask:0xf
	s_nop 1
	v_add_f32_dpp v5, v5, v5 row_mirror row_mask:0xf bank_mask:0xf
	s_nop 1
	v_add_f32_dpp v5, v5, v5 row_bcast:15 row_mask:0xa bank_mask:0xf
	s_nop 1
	v_add_f32_dpp v5, v5, v5 row_bcast:31 row_mask:0xc bank_mask:0xf
	s_nop 1
	v_readlane_b32 s32, v5, 63
	s_nop 1
	v_mov_b32_e32 v6, s32
	v_fmamk_f32 v6, v6, 0x3a800000, v146
	v_rsq_f32_e32 v6, v6
	s_nop 0
	v_mov_b32_e32 v10, v6
	v_pk_mul_f32 v[14:15], v[70:71], v[10:11] op_sel_hi:[1,0]
	v_pk_fma_f32 v[16:17], v[54:55], v[14:15], v[38:39]
	v_pk_mul_f32 v[14:15], v[72:73], v[10:11] op_sel_hi:[1,0]
	v_pk_fma_f32 v[18:19], v[56:57], v[14:15], v[40:41]
	v_cvt_pk_bf16_f32 v86, v16, v17
	v_cvt_pk_bf16_f32 v87, v18, v19
	v_pk_mul_f32 v[14:15], v[74:75], v[10:11] op_sel_hi:[1,0]
	v_pk_fma_f32 v[16:17], v[58:59], v[14:15], v[42:43]
	v_pk_mul_f32 v[14:15], v[76:77], v[10:11] op_sel_hi:[1,0]
	v_pk_fma_f32 v[18:19], v[60:61], v[14:15], v[44:45]
	v_cvt_pk_bf16_f32 v90, v16, v17
	v_cvt_pk_bf16_f32 v91, v18, v19
	v_pk_mul_f32 v[14:15], v[78:79], v[10:11] op_sel_hi:[1,0]
	v_pk_fma_f32 v[16:17], v[62:63], v[14:15], v[46:47]
	v_pk_mul_f32 v[14:15], v[80:81], v[10:11] op_sel_hi:[1,0]
	v_pk_fma_f32 v[18:19], v[64:65], v[14:15], v[48:49]
	v_cvt_pk_bf16_f32 v94, v16, v17
	v_cvt_pk_bf16_f32 v95, v18, v19
	v_pk_mul_f32 v[14:15], v[82:83], v[10:11] op_sel_hi:[1,0]
	v_pk_fma_f32 v[16:17], v[66:67], v[14:15], v[50:51]
	v_pk_mul_f32 v[14:15], v[84:85], v[10:11] op_sel_hi:[1,0]
	v_pk_fma_f32 v[18:19], v[68:69], v[14:15], v[52:53]
	v_cvt_pk_bf16_f32 v98, v16, v17
	v_cvt_pk_bf16_f32 v99, v18, v19
	global_store_dwordx4 v0, v[70:73], s[46:47] offset:0 sc1
	global_store_dwordx4 v0, v[74:77], s[46:47] offset:1024 sc1
	global_store_dwordx4 v0, v[78:81], s[46:47] offset:2048 sc1
	global_store_dwordx4 v0, v[82:85], s[46:47] offset:3072 sc1
	global_store_dwordx2 v1, v[86:87], s[62:63] offset:0 sc1
	global_store_dwordx2 v1, v[90:91], s[62:63] offset:512 sc1
	global_store_dwordx2 v1, v[94:95], s[62:63] offset:1024 sc1
	global_store_dwordx2 v1, v[98:99], s[62:63] offset:1536 sc1
	s_add_u32 s46, s46, 0x1000
	s_addc_u32 s47, s47, 0
	s_add_u32 s62, s62, 0x800
	s_addc_u32 s63, s63, 0
	s_waitcnt vmcnt(24)
	v_lshlrev_b32_e32 v14, 16, v118
	v_and_b32_e32 v15, 0xffff0000, v118
	v_lshlrev_b32_e32 v16, 16, v120
	v_and_b32_e32 v17, 0xffff0000, v120
	v_lshlrev_b32_e32 v18, 16, v119
	v_and_b32_e32 v19, 0xffff0000, v119
	v_lshlrev_b32_e32 v20, 16, v121
	v_and_b32_e32 v21, 0xffff0000, v121
	v_pk_add_f32 v[118:119], v[14:15], v[16:17]
	v_pk_add_f32 v[120:121], v[18:19], v[20:21]
	v_lshlrev_b32_e32 v14, 16, v122
	v_and_b32_e32 v15, 0xffff0000, v122
	v_lshlrev_b32_e32 v16, 16, v124
	v_and_b32_e32 v17, 0xffff0000, v124
	v_lshlrev_b32_e32 v18, 16, v123
	v_and_b32_e32 v19, 0xffff0000, v123
	v_lshlrev_b32_e32 v20, 16, v125
	v_and_b32_e32 v21, 0xffff0000, v125
	v_pk_add_f32 v[122:123], v[14:15], v[16:17]
	v_pk_add_f32 v[124:125], v[18:19], v[20:21]
	v_lshlrev_b32_e32 v14, 16, v134
	v_and_b32_e32 v15, 0xffff0000, v134
	v_lshlrev_b32_e32 v16, 16, v136
	v_and_b32_e32 v17, 0xffff0000, v136
	v_lshlrev_b32_e32 v18, 16, v135
	v_and_b32_e32 v19, 0xffff0000, v135
	v_lshlrev_b32_e32 v20, 16, v137
	v_and_b32_e32 v21, 0xffff0000, v137
	v_pk_add_f32 v[134:135], v[14:15], v[16:17]
	v_pk_add_f32 v[136:137], v[18:19], v[20:21]
	v_lshlrev_b32_e32 v14, 16, v138
	v_and_b32_e32 v15, 0xffff0000, v138
	v_lshlrev_b32_e32 v16, 16, v140
	v_and_b32_e32 v17, 0xffff0000, v140
	v_lshlrev_b32_e32 v18, 16, v139
	v_and_b32_e32 v19, 0xffff0000, v139
	v_lshlrev_b32_e32 v20, 16, v141
	v_and_b32_e32 v21, 0xffff0000, v141
	v_pk_add_f32 v[138:139], v[14:15], v[16:17]
	v_pk_add_f32 v[140:141], v[18:19], v[20:21]
	v_pk_mul_f32 v[12:13], v[118:119], v[118:119]
	v_pk_fma_f32 v[12:13], v[120:121], v[120:121], v[12:13]
	v_pk_fma_f32 v[12:13], v[122:123], v[122:123], v[12:13]
	v_pk_fma_f32 v[12:13], v[124:125], v[124:125], v[12:13]
	v_pk_fma_f32 v[12:13], v[134:135], v[134:135], v[12:13]
	v_pk_fma_f32 v[12:13], v[136:137], v[136:137], v[12:13]
	v_pk_fma_f32 v[12:13], v[138:139], v[138:139], v[12:13]
	v_pk_fma_f32 v[12:13], v[140:141], v[140:141], v[12:13]
	v_add_f32_e32 v5, v12, v13
	s_nop 1
	v_add_f32_dpp v5, v5, v5 quad_perm:[1,0,3,2] row_mask:0xf bank_mask:0xf
	s_nop 1
	v_add_f32_dpp v5, v5, v5 quad_perm:[2,3,0,1] row_mask:0xf bank_mask:0xf
	s_nop 1
	v_add_f32_dpp v5, v5, v5 row_half_mirror row_mask:0xf bank_mask:0xf
	s_nop 1
	v_add_f32_dpp v5, v5, v5 row_mirror row_mask:0xf bank_mask:0xf
	s_nop 1
	v_add_f32_dpp v5, v5, v5 row_bcast:15 row_mask:0xa bank_mask:0xf
	s_nop 1
	v_add_f32_dpp v5, v5, v5 row_bcast:31 row_mask:0xc bank_mask:0xf
	s_nop 1
	v_readlane_b32 s32, v5, 63
	s_nop 1
	v_mov_b32_e32 v6, s32
	v_fmamk_f32 v6, v6, 0x3a800000, v146
	v_rsq_f32_e32 v6, v6
	s_nop 0
	v_mul_f32_e32 v8, 0.5, v6
	v_pk_mul_f32 v[14:15], v[118:119], v[8:9] op_sel_hi:[1,0]
	v_pk_fma_f32 v[102:103], v[22:23], v[14:15], v[102:103]
	v_pk_mul_f32 v[14:15], v[120:121], v[8:9] op_sel_hi:[1,0]
	v_pk_fma_f32 v[104:105], v[24:25], v[14:15], v[104:105]
	v_pk_mul_f32 v[14:15], v[122:123], v[8:9] op_sel_hi:[1,0]
	v_pk_fma_f32 v[106:107], v[26:27], v[14:15], v[106:107]
	v_pk_mul_f32 v[14:15], v[124:125], v[8:9] op_sel_hi:[1,0]
	v_pk_fma_f32 v[108:109], v[28:29], v[14:15], v[108:109]
	v_pk_mul_f32 v[14:15], v[134:135], v[8:9] op_sel_hi:[1,0]
	v_pk_fma_f32 v[110:111], v[30:31], v[14:15], v[110:111]
	v_pk_mul_f32 v[14:15], v[136:137], v[8:9] op_sel_hi:[1,0]
	v_pk_fma_f32 v[112:113], v[32:33], v[14:15], v[112:113]
	v_pk_mul_f32 v[14:15], v[138:139], v[8:9] op_sel_hi:[1,0]
	v_pk_fma_f32 v[114:115], v[34:35], v[14:15], v[114:115]
	v_pk_mul_f32 v[14:15], v[140:141], v[8:9] op_sel_hi:[1,0]
	v_pk_fma_f32 v[116:117], v[36:37], v[14:15], v[116:117]
	v_pk_mul_f32 v[12:13], v[102:103], v[102:103]
	v_pk_fma_f32 v[12:13], v[104:105], v[104:105], v[12:13]
	v_pk_fma_f32 v[12:13], v[106:107], v[106:107], v[12:13]
	v_pk_fma_f32 v[12:13], v[108:109], v[108:109], v[12:13]
	v_pk_fma_f32 v[12:13], v[110:111], v[110:111], v[12:13]
	v_pk_fma_f32 v[12:13], v[112:113], v[112:113], v[12:13]
	v_pk_fma_f32 v[12:13], v[114:115], v[114:115], v[12:13]
	v_pk_fma_f32 v[12:13], v[116:117], v[116:117], v[12:13]
	v_add_f32_e32 v5, v12, v13
	s_nop 1
	v_add_f32_dpp v5, v5, v5 quad_perm:[1,0,3,2] row_mask:0xf bank_mask:0xf
	s_nop 1
	v_add_f32_dpp v5, v5, v5 quad_perm:[2,3,0,1] row_mask:0xf bank_mask:0xf
	s_nop 1
	v_add_f32_dpp v5, v5, v5 row_half_mirror row_mask:0xf bank_mask:0xf
	s_nop 1
	v_add_f32_dpp v5, v5, v5 row_mirror row_mask:0xf bank_mask:0xf
	s_nop 1
	v_add_f32_dpp v5, v5, v5 row_bcast:15 row_mask:0xa bank_mask:0xf
	s_nop 1
	v_add_f32_dpp v5, v5, v5 row_bcast:31 row_mask:0xc bank_mask:0xf
	s_nop 1
	v_readlane_b32 s32, v5, 63
	s_nop 1
	v_mov_b32_e32 v6, s32
	v_fmamk_f32 v6, v6, 0x3a800000, v146
	v_rsq_f32_e32 v6, v6
	s_nop 0
	v_mov_b32_e32 v10, v6
	v_pk_mul_f32 v[14:15], v[102:103], v[10:11] op_sel_hi:[1,0]
	v_pk_fma_f32 v[16:17], v[54:55], v[14:15], v[38:39]
	v_pk_mul_f32 v[14:15], v[104:105], v[10:11] op_sel_hi:[1,0]
	v_pk_fma_f32 v[18:19], v[56:57], v[14:15], v[40:41]
	v_cvt_pk_bf16_f32 v118, v16, v17
	v_cvt_pk_bf16_f32 v119, v18, v19
	v_pk_mul_f32 v[14:15], v[106:107], v[10:11] op_sel_hi:[1,0]
	v_pk_fma_f32 v[16:17], v[58:59], v[14:15], v[42:43]
	v_pk_mul_f32 v[14:15], v[108:109], v[10:11] op_sel_hi:[1,0]
	v_pk_fma_f32 v[18:19], v[60:61], v[14:15], v[44:45]
	v_cvt_pk_bf16_f32 v122, v16, v17
	v_cvt_pk_bf16_f32 v123, v18, v19
	v_pk_mul_f32 v[14:15], v[110:111], v[10:11] op_sel_hi:[1,0]
	v_pk_fma_f32 v[16:17], v[62:63], v[14:15], v[46:47]
	v_pk_mul_f32 v[14:15], v[112:113], v[10:11] op_sel_hi:[1,0]
	v_pk_fma_f32 v[18:19], v[64:65], v[14:15], v[48:49]
	v_cvt_pk_bf16_f32 v134, v16, v17
	v_cvt_pk_bf16_f32 v135, v18, v19
	v_pk_mul_f32 v[14:15], v[114:115], v[10:11] op_sel_hi:[1,0]
	v_pk_fma_f32 v[16:17], v[66:67], v[14:15], v[50:51]
	v_pk_mul_f32 v[14:15], v[116:117], v[10:11] op_sel_hi:[1,0]
	v_pk_fma_f32 v[18:19], v[68:69], v[14:15], v[52:53]
	v_cvt_pk_bf16_f32 v138, v16, v17
	v_cvt_pk_bf16_f32 v139, v18, v19
	global_store_dwordx4 v0, v[102:105], s[46:47] offset:0 sc1
	global_store_dwordx4 v0, v[106:109], s[46:47] offset:1024 sc1
	global_store_dwordx4 v0, v[110:113], s[46:47] offset:2048 sc1
	global_store_dwordx4 v0, v[114:117], s[46:47] offset:3072 sc1
	global_store_dwordx2 v1, v[118:119], s[62:63] offset:0 sc1
	global_store_dwordx2 v1, v[122:123], s[62:63] offset:512 sc1
	global_store_dwordx2 v1, v[134:135], s[62:63] offset:1024 sc1
	global_store_dwordx2 v1, v[138:139], s[62:63] offset:1536 sc1
	s_add_u32 s46, s46, 0x1000
	s_addc_u32 s47, s47, 0
	s_add_u32 s62, s62, 0x800
	s_addc_u32 s63, s63, 0
	s_waitcnt vmcnt(24)
	v_lshlrev_b32_e32 v14, 16, v172
	v_and_b32_e32 v15, 0xffff0000, v172
	v_lshlrev_b32_e32 v16, 16, v174
	v_and_b32_e32 v17, 0xffff0000, v174
	v_lshlrev_b32_e32 v18, 16, v173
	v_and_b32_e32 v19, 0xffff0000, v173
	v_lshlrev_b32_e32 v20, 16, v175
	v_and_b32_e32 v21, 0xffff0000, v175
	v_pk_add_f32 v[172:173], v[14:15], v[16:17]
	v_pk_add_f32 v[174:175], v[18:19], v[20:21]
	v_lshlrev_b32_e32 v14, 16, v176
	v_and_b32_e32 v15, 0xffff0000, v176
	v_lshlrev_b32_e32 v16, 16, v178
	v_and_b32_e32 v17, 0xffff0000, v178
	v_lshlrev_b32_e32 v18, 16, v177
	v_and_b32_e32 v19, 0xffff0000, v177
	v_lshlrev_b32_e32 v20, 16, v179
	v_and_b32_e32 v21, 0xffff0000, v179
	v_pk_add_f32 v[176:177], v[14:15], v[16:17]
	v_pk_add_f32 v[178:179], v[18:19], v[20:21]
	v_lshlrev_b32_e32 v14, 16, v204
	v_and_b32_e32 v15, 0xffff0000, v204
	v_lshlrev_b32_e32 v16, 16, v206
	v_and_b32_e32 v17, 0xffff0000, v206
	v_lshlrev_b32_e32 v18, 16, v205
	v_and_b32_e32 v19, 0xffff0000, v205
	v_lshlrev_b32_e32 v20, 16, v207
	v_and_b32_e32 v21, 0xffff0000, v207
	v_pk_add_f32 v[204:205], v[14:15], v[16:17]
	v_pk_add_f32 v[206:207], v[18:19], v[20:21]
	v_lshlrev_b32_e32 v14, 16, v214
	v_and_b32_e32 v15, 0xffff0000, v214
	v_lshlrev_b32_e32 v16, 16, v216
	v_and_b32_e32 v17, 0xffff0000, v216
	v_lshlrev_b32_e32 v18, 16, v215
	v_and_b32_e32 v19, 0xffff0000, v215
	v_lshlrev_b32_e32 v20, 16, v217
	v_and_b32_e32 v21, 0xffff0000, v217
	v_pk_add_f32 v[214:215], v[14:15], v[16:17]
	v_pk_add_f32 v[216:217], v[18:19], v[20:21]
	v_pk_mul_f32 v[12:13], v[172:173], v[172:173]
	v_pk_fma_f32 v[12:13], v[174:175], v[174:175], v[12:13]
	v_pk_fma_f32 v[12:13], v[176:177], v[176:177], v[12:13]
	v_pk_fma_f32 v[12:13], v[178:179], v[178:179], v[12:13]
	v_pk_fma_f32 v[12:13], v[204:205], v[204:205], v[12:13]
	v_pk_fma_f32 v[12:13], v[206:207], v[206:207], v[12:13]
	v_pk_fma_f32 v[12:13], v[214:215], v[214:215], v[12:13]
	v_pk_fma_f32 v[12:13], v[216:217], v[216:217], v[12:13]
	v_add_f32_e32 v5, v12, v13
	s_nop 1
	v_add_f32_dpp v5, v5, v5 quad_perm:[1,0,3,2] row_mask:0xf bank_mask:0xf
	s_nop 1
	v_add_f32_dpp v5, v5, v5 quad_perm:[2,3,0,1] row_mask:0xf bank_mask:0xf
	s_nop 1
	v_add_f32_dpp v5, v5, v5 row_half_mirror row_mask:0xf bank_mask:0xf
	s_nop 1
	v_add_f32_dpp v5, v5, v5 row_mirror row_mask:0xf bank_mask:0xf
	s_nop 1
	v_add_f32_dpp v5, v5, v5 row_bcast:15 row_mask:0xa bank_mask:0xf
	s_nop 1
	v_add_f32_dpp v5, v5, v5 row_bcast:31 row_mask:0xc bank_mask:0xf
	s_nop 1
	v_readlane_b32 s32, v5, 63
	s_nop 1
	v_mov_b32_e32 v6, s32
	v_fmamk_f32 v6, v6, 0x3a800000, v146
	v_rsq_f32_e32 v6, v6
	s_nop 0
	v_mul_f32_e32 v8, 0.5, v6
	v_pk_mul_f32 v[14:15], v[172:173], v[8:9] op_sel_hi:[1,0]
	v_pk_fma_f32 v[154:155], v[22:23], v[14:15], v[154:155]
	v_pk_mul_f32 v[14:15], v[174:175], v[8:9] op_sel_hi:[1,0]
	v_pk_fma_f32 v[156:157], v[24:25], v[14:15], v[156:157]
	v_pk_mul_f32 v[14:15], v[176:177], v[8:9] op_sel_hi:[1,0]
	v_pk_fma_f32 v[158:159], v[26:27], v[14:15], v[158:159]
	v_pk_mul_f32 v[14:15], v[178:179], v[8:9] op_sel_hi:[1,0]
	v_pk_fma_f32 v[160:161], v[28:29], v[14:15], v[160:161]
	v_pk_mul_f32 v[14:15], v[204:205], v[8:9] op_sel_hi:[1,0]
	v_pk_fma_f32 v[162:163], v[30:31], v[14:15], v[162:163]
	v_pk_mul_f32 v[14:15], v[206:207], v[8:9] op_sel_hi:[1,0]
	v_pk_fma_f32 v[164:165], v[32:33], v[14:15], v[164:165]
	v_pk_mul_f32 v[14:15], v[214:215], v[8:9] op_sel_hi:[1,0]
	v_pk_fma_f32 v[168:169], v[34:35], v[14:15], v[168:169]
	v_pk_mul_f32 v[14:15], v[216:217], v[8:9] op_sel_hi:[1,0]
	v_pk_fma_f32 v[170:171], v[36:37], v[14:15], v[170:171]
	v_pk_mul_f32 v[12:13], v[154:155], v[154:155]
	v_pk_fma_f32 v[12:13], v[156:157], v[156:157], v[12:13]
	v_pk_fma_f32 v[12:13], v[158:159], v[158:159], v[12:13]
	v_pk_fma_f32 v[12:13], v[160:161], v[160:161], v[12:13]
	v_pk_fma_f32 v[12:13], v[162:163], v[162:163], v[12:13]
	v_pk_fma_f32 v[12:13], v[164:165], v[164:165], v[12:13]
	v_pk_fma_f32 v[12:13], v[168:169], v[168:169], v[12:13]
	v_pk_fma_f32 v[12:13], v[170:171], v[170:171], v[12:13]
	v_add_f32_e32 v5, v12, v13
	s_nop 1
	v_add_f32_dpp v5, v5, v5 quad_perm:[1,0,3,2] row_mask:0xf bank_mask:0xf
	s_nop 1
	v_add_f32_dpp v5, v5, v5 quad_perm:[2,3,0,1] row_mask:0xf bank_mask:0xf
	s_nop 1
	v_add_f32_dpp v5, v5, v5 row_half_mirror row_mask:0xf bank_mask:0xf
	s_nop 1
	v_add_f32_dpp v5, v5, v5 row_mirror row_mask:0xf bank_mask:0xf
	s_nop 1
	v_add_f32_dpp v5, v5, v5 row_bcast:15 row_mask:0xa bank_mask:0xf
	s_nop 1
	v_add_f32_dpp v5, v5, v5 row_bcast:31 row_mask:0xc bank_mask:0xf
	s_nop 1
	v_readlane_b32 s32, v5, 63
	s_nop 1
	v_mov_b32_e32 v6, s32
	v_fmamk_f32 v6, v6, 0x3a800000, v146
	v_rsq_f32_e32 v6, v6
	s_nop 0
	v_mov_b32_e32 v10, v6
	v_pk_mul_f32 v[14:15], v[154:155], v[10:11] op_sel_hi:[1,0]
	v_pk_fma_f32 v[16:17], v[54:55], v[14:15], v[38:39]
	v_pk_mul_f32 v[14:15], v[156:157], v[10:11] op_sel_hi:[1,0]
	v_pk_fma_f32 v[18:19], v[56:57], v[14:15], v[40:41]
	v_cvt_pk_bf16_f32 v172, v16, v17
	v_cvt_pk_bf16_f32 v173, v18, v19
	v_pk_mul_f32 v[14:15], v[158:159], v[10:11] op_sel_hi:[1,0]
	v_pk_fma_f32 v[16:17], v[58:59], v[14:15], v[42:43]
	v_pk_mul_f32 v[14:15], v[160:161], v[10:11] op_sel_hi:[1,0]
	v_pk_fma_f32 v[18:19], v[60:61], v[14:15], v[44:45]
	v_cvt_pk_bf16_f32 v176, v16, v17
	v_cvt_pk_bf16_f32 v177, v18, v19
	v_pk_mul_f32 v[14:15], v[162:163], v[10:11] op_sel_hi:[1,0]
	v_pk_fma_f32 v[16:17], v[62:63], v[14:15], v[46:47]
	v_pk_mul_f32 v[14:15], v[164:165], v[10:11] op_sel_hi:[1,0]
	v_pk_fma_f32 v[18:19], v[64:65], v[14:15], v[48:49]
	v_cvt_pk_bf16_f32 v204, v16, v17
	v_cvt_pk_bf16_f32 v205, v18, v19
	v_pk_mul_f32 v[14:15], v[168:169], v[10:11] op_sel_hi:[1,0]
	v_pk_fma_f32 v[16:17], v[66:67], v[14:15], v[50:51]
	v_pk_mul_f32 v[14:15], v[170:171], v[10:11] op_sel_hi:[1,0]
	v_pk_fma_f32 v[18:19], v[68:69], v[14:15], v[52:53]
	v_cvt_pk_bf16_f32 v214, v16, v17
	v_cvt_pk_bf16_f32 v215, v18, v19
	global_store_dwordx4 v0, v[154:157], s[46:47] offset:0 sc1
	global_store_dwordx4 v0, v[158:161], s[46:47] offset:1024 sc1
	global_store_dwordx4 v0, v[162:165], s[46:47] offset:2048 sc1
	global_store_dwordx4 v0, v[168:171], s[46:47] offset:3072 sc1
	global_store_dwordx2 v1, v[172:173], s[62:63] offset:0 sc1
	global_store_dwordx2 v1, v[176:177], s[62:63] offset:512 sc1
	global_store_dwordx2 v1, v[204:205], s[62:63] offset:1024 sc1
	global_store_dwordx2 v1, v[214:215], s[62:63] offset:1536 sc1
	s_add_u32 s46, s46, 0x1000
	s_addc_u32 s47, s47, 0
	s_add_u32 s62, s62, 0x800
	s_addc_u32 s63, s63, 0
	s_waitcnt vmcnt(24)
	v_lshlrev_b32_e32 v14, 16, v234
	v_and_b32_e32 v15, 0xffff0000, v234
	v_lshlrev_b32_e32 v16, 16, v236
	v_and_b32_e32 v17, 0xffff0000, v236
	v_lshlrev_b32_e32 v18, 16, v235
	v_and_b32_e32 v19, 0xffff0000, v235
	v_lshlrev_b32_e32 v20, 16, v237
	v_and_b32_e32 v21, 0xffff0000, v237
	v_pk_add_f32 v[234:235], v[14:15], v[16:17]
	v_pk_add_f32 v[236:237], v[18:19], v[20:21]
	v_lshlrev_b32_e32 v14, 16, v238
	v_and_b32_e32 v15, 0xffff0000, v238
	v_lshlrev_b32_e32 v16, 16, v240
	v_and_b32_e32 v17, 0xffff0000, v240
	v_lshlrev_b32_e32 v18, 16, v239
	v_and_b32_e32 v19, 0xffff0000, v239
	v_lshlrev_b32_e32 v20, 16, v241
	v_and_b32_e32 v21, 0xffff0000, v241
	v_pk_add_f32 v[238:239], v[14:15], v[16:17]
	v_pk_add_f32 v[240:241], v[18:19], v[20:21]
	v_lshlrev_b32_e32 v14, 16, v242
	v_and_b32_e32 v15, 0xffff0000, v242
	v_lshlrev_b32_e32 v16, 16, v244
	v_and_b32_e32 v17, 0xffff0000, v244
	v_lshlrev_b32_e32 v18, 16, v243
	v_and_b32_e32 v19, 0xffff0000, v243
	v_lshlrev_b32_e32 v20, 16, v245
	v_and_b32_e32 v21, 0xffff0000, v245
	v_pk_add_f32 v[242:243], v[14:15], v[16:17]
	v_pk_add_f32 v[244:245], v[18:19], v[20:21]
	v_lshlrev_b32_e32 v14, 16, v246
	v_and_b32_e32 v15, 0xffff0000, v246
	v_lshlrev_b32_e32 v16, 16, v248
	v_and_b32_e32 v17, 0xffff0000, v248
	v_lshlrev_b32_e32 v18, 16, v247
	v_and_b32_e32 v19, 0xffff0000, v247
	v_lshlrev_b32_e32 v20, 16, v249
	v_and_b32_e32 v21, 0xffff0000, v249
	v_pk_add_f32 v[246:247], v[14:15], v[16:17]
	v_pk_add_f32 v[248:249], v[18:19], v[20:21]
	v_pk_mul_f32 v[12:13], v[234:235], v[234:235]
	v_pk_fma_f32 v[12:13], v[236:237], v[236:237], v[12:13]
	v_pk_fma_f32 v[12:13], v[238:239], v[238:239], v[12:13]
	v_pk_fma_f32 v[12:13], v[240:241], v[240:241], v[12:13]
	v_pk_fma_f32 v[12:13], v[242:243], v[242:243], v[12:13]
	v_pk_fma_f32 v[12:13], v[244:245], v[244:245], v[12:13]
	v_pk_fma_f32 v[12:13], v[246:247], v[246:247], v[12:13]
	v_pk_fma_f32 v[12:13], v[248:249], v[248:249], v[12:13]
	v_add_f32_e32 v5, v12, v13
	s_nop 1
	v_add_f32_dpp v5, v5, v5 quad_perm:[1,0,3,2] row_mask:0xf bank_mask:0xf
	s_nop 1
	v_add_f32_dpp v5, v5, v5 quad_perm:[2,3,0,1] row_mask:0xf bank_mask:0xf
	s_nop 1
	v_add_f32_dpp v5, v5, v5 row_half_mirror row_mask:0xf bank_mask:0xf
	s_nop 1
	v_add_f32_dpp v5, v5, v5 row_mirror row_mask:0xf bank_mask:0xf
	s_nop 1
	v_add_f32_dpp v5, v5, v5 row_bcast:15 row_mask:0xa bank_mask:0xf
	s_nop 1
	v_add_f32_dpp v5, v5, v5 row_bcast:31 row_mask:0xc bank_mask:0xf
	s_nop 1
	v_readlane_b32 s32, v5, 63
	s_nop 1
	v_mov_b32_e32 v6, s32
	v_fmamk_f32 v6, v6, 0x3a800000, v146
	v_rsq_f32_e32 v6, v6
	s_nop 0
	v_mul_f32_e32 v8, 0.5, v6
	v_pk_mul_f32 v[14:15], v[234:235], v[8:9] op_sel_hi:[1,0]
	v_pk_fma_f32 v[218:219], v[22:23], v[14:15], v[218:219]
	v_pk_mul_f32 v[14:15], v[236:237], v[8:9] op_sel_hi:[1,0]
	v_pk_fma_f32 v[220:221], v[24:25], v[14:15], v[220:221]
	v_pk_mul_f32 v[14:15], v[238:239], v[8:9] op_sel_hi:[1,0]
	v_pk_fma_f32 v[222:223], v[26:27], v[14:15], v[222:223]
	v_pk_mul_f32 v[14:15], v[240:241], v[8:9] op_sel_hi:[1,0]
	v_pk_fma_f32 v[224:225], v[28:29], v[14:15], v[224:225]
	v_pk_mul_f32 v[14:15], v[242:243], v[8:9] op_sel_hi:[1,0]
	v_pk_fma_f32 v[226:227], v[30:31], v[14:15], v[226:227]
	v_pk_mul_f32 v[14:15], v[244:245], v[8:9] op_sel_hi:[1,0]
	v_pk_fma_f32 v[228:229], v[32:33], v[14:15], v[228:229]
	v_pk_mul_f32 v[14:15], v[246:247], v[8:9] op_sel_hi:[1,0]
	v_pk_fma_f32 v[230:231], v[34:35], v[14:15], v[230:231]
	v_pk_mul_f32 v[14:15], v[248:249], v[8:9] op_sel_hi:[1,0]
	v_pk_fma_f32 v[232:233], v[36:37], v[14:15], v[232:233]
	v_pk_mul_f32 v[12:13], v[218:219], v[218:219]
	v_pk_fma_f32 v[12:13], v[220:221], v[220:221], v[12:13]
	v_pk_fma_f32 v[12:13], v[222:223], v[222:223], v[12:13]
	v_pk_fma_f32 v[12:13], v[224:225], v[224:225], v[12:13]
	v_pk_fma_f32 v[12:13], v[226:227], v[226:227], v[12:13]
	v_pk_fma_f32 v[12:13], v[228:229], v[228:229], v[12:13]
	v_pk_fma_f32 v[12:13], v[230:231], v[230:231], v[12:13]
	v_pk_fma_f32 v[12:13], v[232:233], v[232:233], v[12:13]
	v_add_f32_e32 v5, v12, v13
	s_nop 1
	v_add_f32_dpp v5, v5, v5 quad_perm:[1,0,3,2] row_mask:0xf bank_mask:0xf
	s_nop 1
	v_add_f32_dpp v5, v5, v5 quad_perm:[2,3,0,1] row_mask:0xf bank_mask:0xf
	s_nop 1
	v_add_f32_dpp v5, v5, v5 row_half_mirror row_mask:0xf bank_mask:0xf
	s_nop 1
	v_add_f32_dpp v5, v5, v5 row_mirror row_mask:0xf bank_mask:0xf
	s_nop 1
	v_add_f32_dpp v5, v5, v5 row_bcast:15 row_mask:0xa bank_mask:0xf
	s_nop 1
	v_add_f32_dpp v5, v5, v5 row_bcast:31 row_mask:0xc bank_mask:0xf
	s_nop 1
	v_readlane_b32 s32, v5, 63
	s_nop 1
	v_mov_b32_e32 v6, s32
	v_fmamk_f32 v6, v6, 0x3a800000, v146
	v_rsq_f32_e32 v6, v6
	s_nop 0
	v_mov_b32_e32 v10, v6
	v_pk_mul_f32 v[14:15], v[218:219], v[10:11] op_sel_hi:[1,0]
	v_pk_fma_f32 v[16:17], v[54:55], v[14:15], v[38:39]
	v_pk_mul_f32 v[14:15], v[220:221], v[10:11] op_sel_hi:[1,0]
	v_pk_fma_f32 v[18:19], v[56:57], v[14:15], v[40:41]
	v_cvt_pk_bf16_f32 v234, v16, v17
	v_cvt_pk_bf16_f32 v235, v18, v19
	v_pk_mul_f32 v[14:15], v[222:223], v[10:11] op_sel_hi:[1,0]
	v_pk_fma_f32 v[16:17], v[58:59], v[14:15], v[42:43]
	v_pk_mul_f32 v[14:15], v[224:225], v[10:11] op_sel_hi:[1,0]
	v_pk_fma_f32 v[18:19], v[60:61], v[14:15], v[44:45]
	v_cvt_pk_bf16_f32 v238, v16, v17
	v_cvt_pk_bf16_f32 v239, v18, v19
	v_pk_mul_f32 v[14:15], v[226:227], v[10:11] op_sel_hi:[1,0]
	v_pk_fma_f32 v[16:17], v[62:63], v[14:15], v[46:47]
	v_pk_mul_f32 v[14:15], v[228:229], v[10:11] op_sel_hi:[1,0]
	v_pk_fma_f32 v[18:19], v[64:65], v[14:15], v[48:49]
	v_cvt_pk_bf16_f32 v242, v16, v17
	v_cvt_pk_bf16_f32 v243, v18, v19
	v_pk_mul_f32 v[14:15], v[230:231], v[10:11] op_sel_hi:[1,0]
	v_pk_fma_f32 v[16:17], v[66:67], v[14:15], v[50:51]
	v_pk_mul_f32 v[14:15], v[232:233], v[10:11] op_sel_hi:[1,0]
	v_pk_fma_f32 v[18:19], v[68:69], v[14:15], v[52:53]
	v_cvt_pk_bf16_f32 v246, v16, v17
	v_cvt_pk_bf16_f32 v247, v18, v19
	global_store_dwordx4 v0, v[218:221], s[46:47] offset:0 sc1
	global_store_dwordx4 v0, v[222:225], s[46:47] offset:1024 sc1
	global_store_dwordx4 v0, v[226:229], s[46:47] offset:2048 sc1
	global_store_dwordx4 v0, v[230:233], s[46:47] offset:3072 sc1
	global_store_dwordx2 v1, v[234:235], s[62:63] offset:0 sc1
	global_store_dwordx2 v1, v[238:239], s[62:63] offset:512 sc1
	global_store_dwordx2 v1, v[242:243], s[62:63] offset:1024 sc1
	global_store_dwordx2 v1, v[246:247], s[62:63] offset:1536 sc1
	s_add_u32 s46, s46, 0x1000
	s_addc_u32 s47, s47, 0
	s_add_u32 s62, s62, 0x800
	s_addc_u32 s63, s63, 0

.LBB0_1222:
	s_or_b64 exec, exec, s[4:5]
	s_waitcnt lgkmcnt(0)
	v_mov_b32_e32 v0, v147
	v_readlane_b32 s2, v255, 0
	s_barrier
	s_nop 0
	v_ashrrev_i32_e32 v1, 6, v0
	v_lshl_add_u32 v16, s2, 3, v1
	s_movk_i32 s2, 0x2000
	v_cmp_gt_i32_e32 vcc, s2, v16
	s_and_saveexec_b64 s[10:11], vcc
	s_cbranch_execz .LBB0_1225
	s_load_dwordx4 s[4:7], s[8:9], 0x90
	s_load_dwordx4 s[16:19], s[8:9], 0x40
	s_mul_i32 s2, s70, 0x2d000
	v_lshlrev_b32_e32 v1, 2, v0
	v_readlane_b32 s20, v255, 12
	s_waitcnt lgkmcnt(0)
	s_add_u32 s14, s6, s2
	s_mul_hi_u32 s2, s70, 0x2d000
	s_addc_u32 s15, s7, s2
	v_cmp_lt_i32_e32 vcc, v188, v183
	v_and_b32_e32 v2, 0xfc, v1
	s_add_u32 s12, s14, 0x106000
	v_readlane_b32 s21, v255, 13
	v_cndmask_b32_e32 v1, v182, v188, vcc
	v_cmp_lt_i32_e32 vcc, v254, v183
	s_addc_u32 s13, s15, 0
	s_lshl_b64 s[20:21], s[20:21], 2
	v_lshlrev_b32_e32 v28, 2, v1
	v_cndmask_b32_e32 v1, v182, v254, vcc
	s_add_u32 s16, s16, s20
	v_lshlrev_b32_e32 v29, 2, v1
	v_xor_b32_e32 v1, 4, v182
	s_addc_u32 s17, s17, s21
	v_cmp_lt_i32_e32 vcc, v1, v183
	s_add_u32 s18, s18, s20
	v_lshlrev_b32_e32 v144, 2, v2
	v_cndmask_b32_e32 v1, v182, v1, vcc
	s_addc_u32 s19, s19, s21
	v_lshl_add_u64 v[4:5], s[14:15], 0, v[144:145]
	s_mov_b64 s[14:15], 0x105000
	v_lshlrev_b32_e32 v30, 2, v1
	v_xor_b32_e32 v1, 8, v182
	v_lshl_add_u64 v[18:19], v[4:5], 0, s[14:15]
	v_lshl_add_u64 v[4:5], s[18:19], 0, v[144:145]
	v_cmp_lt_i32_e32 vcc, v1, v183
	v_lshl_add_u64 v[20:21], v[4:5], 0, s[94:95]
	v_lshl_add_u64 v[4:5], s[16:17], 0, v[144:145]
	s_mov_b64 s[14:15], 0x2000
	v_cndmask_b32_e32 v1, v182, v1, vcc
	v_cmp_lt_i32_e32 vcc, v187, v183
	v_ashrrev_i32_e32 v17, 31, v16
	v_lshl_add_u64 v[22:23], v[4:5], 0, s[14:15]
	v_lshlrev_b32_e32 v31, 2, v1
	v_cndmask_b32_e32 v1, v182, v187, vcc
	v_cmp_lt_i32_e32 vcc, v184, v183
	v_lshlrev_b64 v[4:5], 11, v[16:17]
	v_and_b32_e32 v3, 63, v0
	v_lshlrev_b32_e32 v32, 2, v1
	v_cndmask_b32_e32 v1, v182, v184, vcc
	v_lshl_or_b32 v4, v3, 3, v4
	v_lshlrev_b32_e32 v33, 2, v1
	v_lshl_add_u64 v[0:1], s[6:7], 0, v[4:5]
	s_mov_b64 s[6:7], 0x9800600
	v_lshl_add_u64 v[24:25], v[0:1], 0, s[6:7]
	v_lshlrev_b64 v[0:1], 12, v[16:17]
	v_lshl_or_b32 v0, v3, 4, v0
	v_lshl_add_u64 v[26:27], s[4:5], 0, v[0:1]
	s_mov_b64 s[4:5], 0
	v_lshlrev_b32_e32 v144, 2, v2
	v_readlane_b32 s2, v255, 0
	v_readfirstlane_b32 s7, v147
	s_load_dwordx2 s[4:5], s[8:9], 0x90
	s_load_dwordx2 s[12:13], s[8:9], 0x98
	s_load_dwordx2 s[14:15], s[8:9], 0x40
	s_load_dwordx2 s[40:41], s[8:9], 0x48
	v_and_b32_e32 v0, 63, v147
	v_lshlrev_b32_e32 v1, 3, v0
	v_lshlrev_b32_e32 v0, 4, v0
	s_lshr_b32 s7, s7, 6
	s_and_b32 s27, s2, 6
	s_lshl_b32 s27, s27, 5
	s_and_b32 s37, s2, 0x39
	s_or_b32 s27, s27, s37
	s_lshr_b32 s37, s2, 6
	s_lshl_b32 s37, s37, 1
	s_or_b32 s2, s27, s37
	s_lshl_b32 s2, s2, 3
	s_add_u32 s2, s2, s7
	s_lshl_b32 s24, s2, 2
	s_sub_u32 s27, s24, 0x1000
	s_lshr_b32 s27, s27, 10
	s_add_u32 s27, s27, 1
	s_cmp_lt_u32 s24, 0x1000
	s_cselect_b32 s30, 0, s27
	v_add_u32_e32 v2, 0x5000, v0
	v_add_u32_e32 v3, 0x6000, v0
	v_add_u32_e32 v4, 0x7000, v0
	s_waitcnt lgkmcnt(0)
	s_lshl_b32 s27, s24, 11
	s_add_u32 s62, s12, s27
	s_addc_u32 s63, s13, 0
	s_add_u32 s58, s62, 0x8800000
	s_addc_u32 s59, s63, 0
	s_add_u32 s60, s58, 0x1000000
	s_addc_u32 s61, s59, 0
	s_add_u32 s62, s62, 0x1000000
	s_addc_u32 s63, s63, 0
	s_lshl_b32 s27, s24, 12
	s_add_u32 s46, s4, s27
	s_addc_u32 s47, s5, 0
	s_mov_b64 s[4:5], s[46:47]
	s_mul_i32 s27, s70, 5
	s_add_u32 s27, s27, s30
	s_mul_i32 s27, s27, 0x9000
	s_add_u32 s27, s27, 0x100000
	s_add_u32 s88, s12, s27
	s_addc_u32 s89, s13, 0
	s_mov_b64 s[100:101], s[88:89]
	s_mul_i32 s27, s70, 0x3000
	s_add_u32 s27, s27, 0x1000
	s_add_u32 s40, s40, s27
	s_addc_u32 s41, s41, 0
	s_mul_i32 s27, s70, 0x3000
	s_add_u32 s27, s27, 0x2000
	s_add_u32 s14, s14, s27
	s_addc_u32 s15, s15, 0
	global_load_dwordx4 v[22:25], v2, s[100:101] offset:0
	global_load_dwordx4 v[172:175], v0, s[40:41] offset:0
	global_load_dwordx4 v[38:41], v3, s[88:89] offset:0
	global_load_dwordx4 v[54:57], v4, s[88:89] offset:0
	global_load_dwordx4 v[234:237], v0, s[14:15] offset:0
	global_load_dwordx4 v[26:29], v2, s[100:101] offset:1024
	global_load_dwordx4 v[176:179], v0, s[40:41] offset:1024
	global_load_dwordx4 v[42:45], v3, s[88:89] offset:1024
	global_load_dwordx4 v[58:61], v4, s[88:89] offset:1024
	global_load_dwordx4 v[238:241], v0, s[14:15] offset:1024
	global_load_dwordx4 v[30:33], v2, s[100:101] offset:2048
	global_load_dwordx4 v[204:207], v0, s[40:41] offset:2048
	global_load_dwordx4 v[46:49], v3, s[88:89] offset:2048
	global_load_dwordx4 v[62:65], v4, s[88:89] offset:2048
	global_load_dwordx4 v[242:245], v0, s[14:15] offset:2048
	global_load_dwordx4 v[34:37], v2, s[100:101] offset:3072
	global_load_dwordx4 v[214:217], v0, s[40:41] offset:3072
	global_load_dwordx4 v[50:53], v3, s[88:89] offset:3072
	global_load_dwordx4 v[66:69], v4, s[88:89] offset:3072
	global_load_dwordx4 v[246:249], v0, s[14:15] offset:3072
	global_load_dwordx4 v[70:73], v0, s[4:5] offset:0
	global_load_dwordx4 v[74:77], v0, s[4:5] offset:1024
	global_load_dwordx4 v[78:81], v0, s[4:5] offset:2048
	global_load_dwordx4 v[82:85], v0, s[4:5] offset:3072
	s_add_u32 s4, s4, 0x1000
	s_addc_u32 s5, s5, 0
	global_load_dwordx4 v[102:105], v0, s[4:5] offset:0
	global_load_dwordx4 v[106:109], v0, s[4:5] offset:1024
	global_load_dwordx4 v[110:113], v0, s[4:5] offset:2048
	global_load_dwordx4 v[114:117], v0, s[4:5] offset:3072
	s_add_u32 s4, s4, 0x1000
	s_addc_u32 s5, s5, 0
	global_load_dwordx4 v[154:157], v0, s[4:5] offset:0
	global_load_dwordx4 v[158:161], v0, s[4:5] offset:1024
	global_load_dwordx4 v[162:165], v0, s[4:5] offset:2048
	global_load_dwordx4 v[168:171], v0, s[4:5] offset:3072
	s_add_u32 s4, s4, 0x1000
	s_addc_u32 s5, s5, 0
	global_load_dwordx4 v[218:221], v0, s[4:5] offset:0
	global_load_dwordx4 v[222:225], v0, s[4:5] offset:1024
	global_load_dwordx4 v[226:229], v0, s[4:5] offset:2048
	global_load_dwordx4 v[230:233], v0, s[4:5] offset:3072
	s_add_u32 s4, s4, 0x1000
	s_addc_u32 s5, s5, 0
	s_waitcnt vmcnt(16)
	v_pk_mul_f32 v[22:23], v[22:23], v[172:173]
	v_pk_mul_f32 v[24:25], v[24:25], v[174:175]
	v_pk_mul_f32 v[26:27], v[26:27], v[176:177]
	v_pk_mul_f32 v[28:29], v[28:29], v[178:179]
	v_pk_mul_f32 v[30:31], v[30:31], v[204:205]
	v_pk_mul_f32 v[32:33], v[32:33], v[206:207]
	v_pk_mul_f32 v[34:35], v[34:35], v[214:215]
	v_pk_mul_f32 v[36:37], v[36:37], v[216:217]
	v_pk_add_f32 v[54:55], v[54:55], 1.0 op_sel_hi:[1,0]
	v_pk_mul_f32 v[54:55], v[54:55], v[234:235]
	v_pk_add_f32 v[56:57], v[56:57], 1.0 op_sel_hi:[1,0]
	v_pk_mul_f32 v[56:57], v[56:57], v[236:237]
	v_pk_add_f32 v[58:59], v[58:59], 1.0 op_sel_hi:[1,0]
	v_pk_mul_f32 v[58:59], v[58:59], v[238:239]
	v_pk_add_f32 v[60:61], v[60:61], 1.0 op_sel_hi:[1,0]
	v_pk_mul_f32 v[60:61], v[60:61], v[240:241]
	v_pk_add_f32 v[62:63], v[62:63], 1.0 op_sel_hi:[1,0]
	v_pk_mul_f32 v[62:63], v[62:63], v[242:243]
	v_pk_add_f32 v[64:65], v[64:65], 1.0 op_sel_hi:[1,0]
	v_pk_mul_f32 v[64:65], v[64:65], v[244:245]
	v_pk_add_f32 v[66:67], v[66:67], 1.0 op_sel_hi:[1,0]
	v_pk_mul_f32 v[66:67], v[66:67], v[246:247]
	v_pk_add_f32 v[68:69], v[68:69], 1.0 op_sel_hi:[1,0]
	v_pk_mul_f32 v[68:69], v[68:69], v[248:249]
	v_cmp_eq_u32_e32 vcc, 0, v147
	s_and_saveexec_b64 s[40:41], vcc
	s_cbranch_execz .Lnw_skip_n2
	v_readlane_b32 s2, v255, 0
	v_readlane_b32 s7, v255, 46
	s_nop 0
	s_lshr_b32 s24, s2, 3
	s_and_b32 s24, s24, 7
	s_and_b32 s27, s2, 6
	s_lshl_b32 s27, s27, 2
	s_or_b32 s27, s27, s24
	s_lshl_b32 s27, s27, 7
	s_add_u32 s27, s27, 0xa000
	v_mov_b32_e32 v14, s27
	s_mov_b32 s30, 0

.Lnw_skip_n2:
	s_or_b64 exec, exec, s[40:41]
	s_barrier
	global_load_dwordx2 v[86:87], v1, s[58:59] offset:0
	global_load_dwordx2 v[90:91], v1, s[58:59] offset:512
	global_load_dwordx2 v[94:95], v1, s[58:59] offset:1024
	global_load_dwordx2 v[98:99], v1, s[58:59] offset:1536
	global_load_dwordx2 v[88:89], v1, s[60:61] offset:0
	global_load_dwordx2 v[92:93], v1, s[60:61] offset:512
	global_load_dwordx2 v[96:97], v1, s[60:61] offset:1024
	global_load_dwordx2 v[100:101], v1, s[60:61] offset:1536
	s_add_u32 s58, s58, 0x800
	s_addc_u32 s59, s59, 0
	s_add_u32 s60, s60, 0x800
	s_addc_u32 s61, s61, 0
	global_load_dwordx2 v[118:119], v1, s[58:59] offset:0
	global_load_dwordx2 v[122:123], v1, s[58:59] offset:512
	global_load_dwordx2 v[134:135], v1, s[58:59] offset:1024
	global_load_dwordx2 v[138:139], v1, s[58:59] offset:1536
	global_load_dwordx2 v[120:121], v1, s[60:61] offset:0
	global_load_dwordx2 v[124:125], v1, s[60:61] offset:512
	global_load_dwordx2 v[136:137], v1, s[60:61] offset:1024
	global_load_dwordx2 v[140:141], v1, s[60:61] offset:1536
	s_add_u32 s58, s58, 0x800
	s_addc_u32 s59, s59, 0
	s_add_u32 s60, s60, 0x800
	s_addc_u32 s61, s61, 0
	global_load_dwordx2 v[172:173], v1, s[58:59] offset:0
	global_load_dwordx2 v[176:177], v1, s[58:59] offset:512
	global_load_dwordx2 v[204:205], v1, s[58:59] offset:1024
	global_load_dwordx2 v[214:215], v1, s[58:59] offset:1536
	global_load_dwordx2 v[174:175], v1, s[60:61] offset:0
	global_load_dwordx2 v[178:179], v1, s[60:61] offset:512
	global_load_dwordx2 v[206:207], v1, s[60:61] offset:1024
	global_load_dwordx2 v[216:217], v1, s[60:61] offset:1536
	s_add_u32 s58, s58, 0x800
	s_addc_u32 s59, s59, 0
	s_add_u32 s60, s60, 0x800
	s_addc_u32 s61, s61, 0
	global_load_dwordx2 v[234:235], v1, s[58:59] offset:0
	global_load_dwordx2 v[238:239], v1, s[58:59] offset:512
	global_load_dwordx2 v[242:243], v1, s[58:59] offset:1024
	global_load_dwordx2 v[246:247], v1, s[58:59] offset:1536
	global_load_dwordx2 v[236:237], v1, s[60:61] offset:0
	global_load_dwordx2 v[240:241], v1, s[60:61] offset:512
	global_load_dwordx2 v[244:245], v1, s[60:61] offset:1024
	global_load_dwordx2 v[248:249], v1, s[60:61] offset:1536
	s_add_u32 s58, s58, 0x800
	s_addc_u32 s59, s59, 0
	s_add_u32 s60, s60, 0x800
	s_addc_u32 s61, s61, 0
	s_waitcnt vmcnt(24)
	v_lshlrev_b32_e32 v14, 16, v86
	v_and_b32_e32 v15, 0xffff0000, v86
	v_lshlrev_b32_e32 v16, 16, v88
	v_and_b32_e32 v17, 0xffff0000, v88
	v_lshlrev_b32_e32 v18, 16, v87
	v_and_b32_e32 v19, 0xffff0000, v87
	v_lshlrev_b32_e32 v20, 16, v89
	v_and_b32_e32 v21, 0xffff0000, v89
	v_pk_add_f32 v[86:87], v[14:15], v[16:17]
	v_pk_add_f32 v[88:89], v[18:19], v[20:21]
	v_lshlrev_b32_e32 v14, 16, v90
	v_and_b32_e32 v15, 0xffff0000, v90
	v_lshlrev_b32_e32 v16, 16, v92
	v_and_b32_e32 v17, 0xffff0000, v92
	v_lshlrev_b32_e32 v18, 16, v91
	v_and_b32_e32 v19, 0xffff0000, v91
	v_lshlrev_b32_e32 v20, 16, v93
	v_and_b32_e32 v21, 0xffff0000, v93
	v_pk_add_f32 v[90:91], v[14:15], v[16:17]
	v_pk_add_f32 v[92:93], v[18:19], v[20:21]
	v_lshlrev_b32_e32 v14, 16, v94
	v_and_b32_e32 v15, 0xffff0000, v94
	v_lshlrev_b32_e32 v16, 16, v96
	v_and_b32_e32 v17, 0xffff0000, v96
	v_lshlrev_b32_e32 v18, 16, v95
	v_and_b32_e32 v19, 0xffff0000, v95
	v_lshlrev_b32_e32 v20, 16, v97
	v_and_b32_e32 v21, 0xffff0000, v97
	v_pk_add_f32 v[94:95], v[14:15], v[16:17]
	v_pk_add_f32 v[96:97], v[18:19], v[20:21]
	v_lshlrev_b32_e32 v14, 16, v98
	v_and_b32_e32 v15, 0xffff0000, v98
	v_lshlrev_b32_e32 v16, 16, v100
	v_and_b32_e32 v17, 0xffff0000, v100
	v_lshlrev_b32_e32 v18, 16, v99
	v_and_b32_e32 v19, 0xffff0000, v99
	v_lshlrev_b32_e32 v20, 16, v101
	v_and_b32_e32 v21, 0xffff0000, v101
	v_pk_add_f32 v[98:99], v[14:15], v[16:17]
	v_pk_add_f32 v[100:101], v[18:19], v[20:21]
	v_pk_mul_f32 v[12:13], v[86:87], v[86:87]
	v_pk_fma_f32 v[12:13], v[88:89], v[88:89], v[12:13]
	v_pk_fma_f32 v[12:13], v[90:91], v[90:91], v[12:13]
	v_pk_fma_f32 v[12:13], v[92:93], v[92:93], v[12:13]
	v_pk_fma_f32 v[12:13], v[94:95], v[94:95], v[12:13]
	v_pk_fma_f32 v[12:13], v[96:97], v[96:97], v[12:13]
	v_pk_fma_f32 v[12:13], v[98:99], v[98:99], v[12:13]
	v_pk_fma_f32 v[12:13], v[100:101], v[100:101], v[12:13]
	v_add_f32_e32 v5, v12, v13
	s_nop 1
	v_add_f32_dpp v5, v5, v5 quad_perm:[1,0,3,2] row_mask:0xf bank_mask:0xf
	s_nop 1
	v_add_f32_dpp v5, v5, v5 quad_perm:[2,3,0,1] row_mask:0xf bank_mask:0xf
	s_nop 1
	v_add_f32_dpp v5, v5, v5 row_half_mirror row_mask:0xf bank_mask:0xf
	s_nop 1
	v_add_f32_dpp v5, v5, v5 row_mirror row_mask:0xf bank_mask:0xf
	s_nop 1
	v_add_f32_dpp v5, v5, v5 row_bcast:15 row_mask:0xa bank_mask:0xf
	s_nop 1
	v_add_f32_dpp v5, v5, v5 row_bcast:31 row_mask:0xc bank_mask:0xf
	s_nop 1
	v_readlane_b32 s32, v5, 63
	s_nop 1
	v_mov_b32_e32 v6, s32
	v_fmamk_f32 v6, v6, 0x3a800000, v146
	v_rsq_f32_e32 v6, v6
	s_nop 0
	v_mov_b32_e32 v8, v6
	v_pk_mul_f32 v[14:15], v[86:87], v[8:9] op_sel_hi:[1,0]
	v_pk_fma_f32 v[70:71], v[22:23], v[14:15], v[70:71]
	v_pk_mul_f32 v[14:15], v[88:89], v[8:9] op_sel_hi:[1,0]
	v_pk_fma_f32 v[72:73], v[24:25], v[14:15], v[72:73]
	v_pk_mul_f32 v[14:15], v[90:91], v[8:9] op_sel_hi:[1,0]
	v_pk_fma_f32 v[74:75], v[26:27], v[14:15], v[74:75]
	v_pk_mul_f32 v[14:15], v[92:93], v[8:9] op_sel_hi:[1,0]
	v_pk_fma_f32 v[76:77], v[28:29], v[14:15], v[76:77]
	v_pk_mul_f32 v[14:15], v[94:95], v[8:9] op_sel_hi:[1,0]
	v_pk_fma_f32 v[78:79], v[30:31], v[14:15], v[78:79]
	v_pk_mul_f32 v[14:15], v[96:97], v[8:9] op_sel_hi:[1,0]
	v_pk_fma_f32 v[80:81], v[32:33], v[14:15], v[80:81]
	v_pk_mul_f32 v[14:15], v[98:99], v[8:9] op_sel_hi:[1,0]
	v_pk_fma_f32 v[82:83], v[34:35], v[14:15], v[82:83]
	v_pk_mul_f32 v[14:15], v[100:101], v[8:9] op_sel_hi:[1,0]
	v_pk_fma_f32 v[84:85], v[36:37], v[14:15], v[84:85]
	v_pk_mul_f32 v[12:13], v[70:71], v[70:71]
	v_pk_fma_f32 v[12:13], v[72:73], v[72:73], v[12:13]
	v_pk_fma_f32 v[12:13], v[74:75], v[74:75], v[12:13]
	v_pk_fma_f32 v[12:13], v[76:77], v[76:77], v[12:13]
	v_pk_fma_f32 v[12:13], v[78:79], v[78:79], v[12:13]
	v_pk_fma_f32 v[12:13], v[80:81], v[80:81], v[12:13]
	v_pk_fma_f32 v[12:13], v[82:83], v[82:83], v[12:13]
	v_pk_fma_f32 v[12:13], v[84:85], v[84:85], v[12:13]
	v_add_f32_e32 v5, v12, v13
	s_nop 1
	v_add_f32_dpp v5, v5, v5 quad_perm:[1,0,3,2] row_mask:0xf bank_mask:0xf
	s_nop 1
	v_add_f32_dpp v5, v5, v5 quad_perm:[2,3,0,1] row_mask:0xf bank_mask:0xf
	s_nop 1
	v_add_f32_dpp v5, v5, v5 row_half_mirror row_mask:0xf bank_mask:0xf
	s_nop 1
	v_add_f32_dpp v5, v5, v5 row_mirror row_mask:0xf bank_mask:0xf
	s_nop 1
	v_add_f32_dpp v5, v5, v5 row_bcast:15 row_mask:0xa bank_mask:0xf
	s_nop 1
	v_add_f32_dpp v5, v5, v5 row_bcast:31 row_mask:0xc bank_mask:0xf
	s_nop 1
	v_readlane_b32 s32, v5, 63
	s_nop 1
	v_mov_b32_e32 v6, s32
	v_fmamk_f32 v6, v6, 0x3a800000, v146
	v_rsq_f32_e32 v6, v6
	s_nop 0
	v_mov_b32_e32 v10, v6
	v_pk_mul_f32 v[14:15], v[70:71], v[10:11] op_sel_hi:[1,0]
	v_pk_fma_f32 v[16:17], v[54:55], v[14:15], v[38:39]
	v_pk_mul_f32 v[14:15], v[72:73], v[10:11] op_sel_hi:[1,0]
	v_pk_fma_f32 v[18:19], v[56:57], v[14:15], v[40:41]
	v_cvt_pk_bf16_f32 v86, v16, v17
	v_cvt_pk_bf16_f32 v87, v18, v19
	v_pk_mul_f32 v[14:15], v[74:75], v[10:11] op_sel_hi:[1,0]
	v_pk_fma_f32 v[16:17], v[58:59], v[14:15], v[42:43]
	v_pk_mul_f32 v[14:15], v[76:77], v[10:11] op_sel_hi:[1,0]
	v_pk_fma_f32 v[18:19], v[60:61], v[14:15], v[44:45]
	v_cvt_pk_bf16_f32 v90, v16, v17
	v_cvt_pk_bf16_f32 v91, v18, v19
	v_pk_mul_f32 v[14:15], v[78:79], v[10:11] op_sel_hi:[1,0]
	v_pk_fma_f32 v[16:17], v[62:63], v[14:15], v[46:47]
	v_pk_mul_f32 v[14:15], v[80:81], v[10:11] op_sel_hi:[1,0]
	v_pk_fma_f32 v[18:19], v[64:65], v[14:15], v[48:49]
	v_cvt_pk_bf16_f32 v94, v16, v17
	v_cvt_pk_bf16_f32 v95, v18, v19
	v_pk_mul_f32 v[14:15], v[82:83], v[10:11] op_sel_hi:[1,0]
	v_pk_fma_f32 v[16:17], v[66:67], v[14:15], v[50:51]
	v_pk_mul_f32 v[14:15], v[84:85], v[10:11] op_sel_hi:[1,0]
	v_pk_fma_f32 v[18:19], v[68:69], v[14:15], v[52:53]
	v_cvt_pk_bf16_f32 v98, v16, v17
	v_cvt_pk_bf16_f32 v99, v18, v19
	global_store_dwordx4 v0, v[70:73], s[46:47] offset:0 sc1
	global_store_dwordx4 v0, v[74:77], s[46:47] offset:1024 sc1
	global_store_dwordx4 v0, v[78:81], s[46:47] offset:2048 sc1
	global_store_dwordx4 v0, v[82:85], s[46:47] offset:3072 sc1
	global_store_dwordx2 v1, v[86:87], s[62:63] offset:0 sc1
	global_store_dwordx2 v1, v[90:91], s[62:63] offset:512 sc1
	global_store_dwordx2 v1, v[94:95], s[62:63] offset:1024 sc1
	global_store_dwordx2 v1, v[98:99], s[62:63] offset:1536 sc1
	s_add_u32 s46, s46, 0x1000
	s_addc_u32 s47, s47, 0
	s_add_u32 s62, s62, 0x800
	s_addc_u32 s63, s63, 0
	s_waitcnt vmcnt(24)
	v_lshlrev_b32_e32 v14, 16, v118
	v_and_b32_e32 v15, 0xffff0000, v118
	v_lshlrev_b32_e32 v16, 16, v120
	v_and_b32_e32 v17, 0xffff0000, v120
	v_lshlrev_b32_e32 v18, 16, v119
	v_and_b32_e32 v19, 0xffff0000, v119
	v_lshlrev_b32_e32 v20, 16, v121
	v_and_b32_e32 v21, 0xffff0000, v121
	v_pk_add_f32 v[118:119], v[14:15], v[16:17]
	v_pk_add_f32 v[120:121], v[18:19], v[20:21]
	v_lshlrev_b32_e32 v14, 16, v122
	v_and_b32_e32 v15, 0xffff0000, v122
	v_lshlrev_b32_e32 v16, 16, v124
	v_and_b32_e32 v17, 0xffff0000, v124
	v_lshlrev_b32_e32 v18, 16, v123
	v_and_b32_e32 v19, 0xffff0000, v123
	v_lshlrev_b32_e32 v20, 16, v125
	v_and_b32_e32 v21, 0xffff0000, v125
	v_pk_add_f32 v[122:123], v[14:15], v[16:17]
	v_pk_add_f32 v[124:125], v[18:19], v[20:21]
	v_lshlrev_b32_e32 v14, 16, v134
	v_and_b32_e32 v15, 0xffff0000, v134
	v_lshlrev_b32_e32 v16, 16, v136
	v_and_b32_e32 v17, 0xffff0000, v136
	v_lshlrev_b32_e32 v18, 16, v135
	v_and_b32_e32 v19, 0xffff0000, v135
	v_lshlrev_b32_e32 v20, 16, v137
	v_and_b32_e32 v21, 0xffff0000, v137
	v_pk_add_f32 v[134:135], v[14:15], v[16:17]
	v_pk_add_f32 v[136:137], v[18:19], v[20:21]
	v_lshlrev_b32_e32 v14, 16, v138
	v_and_b32_e32 v15, 0xffff0000, v138
	v_lshlrev_b32_e32 v16, 16, v140
	v_and_b32_e32 v17, 0xffff0000, v140
	v_lshlrev_b32_e32 v18, 16, v139
	v_and_b32_e32 v19, 0xffff0000, v139
	v_lshlrev_b32_e32 v20, 16, v141
	v_and_b32_e32 v21, 0xffff0000, v141
	v_pk_add_f32 v[138:139], v[14:15], v[16:17]
	v_pk_add_f32 v[140:141], v[18:19], v[20:21]
	v_pk_mul_f32 v[12:13], v[118:119], v[118:119]
	v_pk_fma_f32 v[12:13], v[120:121], v[120:121], v[12:13]
	v_pk_fma_f32 v[12:13], v[122:123], v[122:123], v[12:13]
	v_pk_fma_f32 v[12:13], v[124:125], v[124:125], v[12:13]
	v_pk_fma_f32 v[12:13], v[134:135], v[134:135], v[12:13]
	v_pk_fma_f32 v[12:13], v[136:137], v[136:137], v[12:13]
	v_pk_fma_f32 v[12:13], v[138:139], v[138:139], v[12:13]
	v_pk_fma_f32 v[12:13], v[140:141], v[140:141], v[12:13]
	v_add_f32_e32 v5, v12, v13
	s_nop 1
	v_add_f32_dpp v5, v5, v5 quad_perm:[1,0,3,2] row_mask:0xf bank_mask:0xf
	s_nop 1
	v_add_f32_dpp v5, v5, v5 quad_perm:[2,3,0,1] row_mask:0xf bank_mask:0xf
	s_nop 1
	v_add_f32_dpp v5, v5, v5 row_half_mirror row_mask:0xf bank_mask:0xf
	s_nop 1
	v_add_f32_dpp v5, v5, v5 row_mirror row_mask:0xf bank_mask:0xf
	s_nop 1
	v_add_f32_dpp v5, v5, v5 row_bcast:15 row_mask:0xa bank_mask:0xf
	s_nop 1
	v_add_f32_dpp v5, v5, v5 row_bcast:31 row_mask:0xc bank_mask:0xf
	s_nop 1
	v_readlane_b32 s32, v5, 63
	s_nop 1
	v_mov_b32_e32 v6, s32
	v_fmamk_f32 v6, v6, 0x3a800000, v146
	v_rsq_f32_e32 v6, v6
	s_nop 0
	v_mov_b32_e32 v8, v6
	v_pk_mul_f32 v[14:15], v[118:119], v[8:9] op_sel_hi:[1,0]
	v_pk_fma_f32 v[102:103], v[22:23], v[14:15], v[102:103]
	v_pk_mul_f32 v[14:15], v[120:121], v[8:9] op_sel_hi:[1,0]
	v_pk_fma_f32 v[104:105], v[24:25], v[14:15], v[104:105]
	v_pk_mul_f32 v[14:15], v[122:123], v[8:9] op_sel_hi:[1,0]
	v_pk_fma_f32 v[106:107], v[26:27], v[14:15], v[106:107]
	v_pk_mul_f32 v[14:15], v[124:125], v[8:9] op_sel_hi:[1,0]
	v_pk_fma_f32 v[108:109], v[28:29], v[14:15], v[108:109]
	v_pk_mul_f32 v[14:15], v[134:135], v[8:9] op_sel_hi:[1,0]
	v_pk_fma_f32 v[110:111], v[30:31], v[14:15], v[110:111]
	v_pk_mul_f32 v[14:15], v[136:137], v[8:9] op_sel_hi:[1,0]
	v_pk_fma_f32 v[112:113], v[32:33], v[14:15], v[112:113]
	v_pk_mul_f32 v[14:15], v[138:139], v[8:9] op_sel_hi:[1,0]
	v_pk_fma_f32 v[114:115], v[34:35], v[14:15], v[114:115]
	v_pk_mul_f32 v[14:15], v[140:141], v[8:9] op_sel_hi:[1,0]
	v_pk_fma_f32 v[116:117], v[36:37], v[14:15], v[116:117]
	v_pk_mul_f32 v[12:13], v[102:103], v[102:103]
	v_pk_fma_f32 v[12:13], v[104:105], v[104:105], v[12:13]
	v_pk_fma_f32 v[12:13], v[106:107], v[106:107], v[12:13]
	v_pk_fma_f32 v[12:13], v[108:109], v[108:109], v[12:13]
	v_pk_fma_f32 v[12:13], v[110:111], v[110:111], v[12:13]
	v_pk_fma_f32 v[12:13], v[112:113], v[112:113], v[12:13]
	v_pk_fma_f32 v[12:13], v[114:115], v[114:115], v[12:13]
	v_pk_fma_f32 v[12:13], v[116:117], v[116:117], v[12:13]
	v_add_f32_e32 v5, v12, v13
	s_nop 1
	v_add_f32_dpp v5, v5, v5 quad_perm:[1,0,3,2] row_mask:0xf bank_mask:0xf
	s_nop 1
	v_add_f32_dpp v5, v5, v5 quad_perm:[2,3,0,1] row_mask:0xf bank_mask:0xf
	s_nop 1
	v_add_f32_dpp v5, v5, v5 row_half_mirror row_mask:0xf bank_mask:0xf
	s_nop 1
	v_add_f32_dpp v5, v5, v5 row_mirror row_mask:0xf bank_mask:0xf
	s_nop 1
	v_add_f32_dpp v5, v5, v5 row_bcast:15 row_mask:0xa bank_mask:0xf
	s_nop 1
	v_add_f32_dpp v5, v5, v5 row_bcast:31 row_mask:0xc bank_mask:0xf
	s_nop 1
	v_readlane_b32 s32, v5, 63
	s_nop 1
	v_mov_b32_e32 v6, s32
	v_fmamk_f32 v6, v6, 0x3a800000, v146
	v_rsq_f32_e32 v6, v6
	s_nop 0
	v_mov_b32_e32 v10, v6
	v_pk_mul_f32 v[14:15], v[102:103], v[10:11] op_sel_hi:[1,0]
	v_pk_fma_f32 v[16:17], v[54:55], v[14:15], v[38:39]
	v_pk_mul_f32 v[14:15], v[104:105], v[10:11] op_sel_hi:[1,0]
	v_pk_fma_f32 v[18:19], v[56:57], v[14:15], v[40:41]
	v_cvt_pk_bf16_f32 v118, v16, v17
	v_cvt_pk_bf16_f32 v119, v18, v19
	v_pk_mul_f32 v[14:15], v[106:107], v[10:11] op_sel_hi:[1,0]
	v_pk_fma_f32 v[16:17], v[58:59], v[14:15], v[42:43]
	v_pk_mul_f32 v[14:15], v[108:109], v[10:11] op_sel_hi:[1,0]
	v_pk_fma_f32 v[18:19], v[60:61], v[14:15], v[44:45]
	v_cvt_pk_bf16_f32 v122, v16, v17
	v_cvt_pk_bf16_f32 v123, v18, v19
	v_pk_mul_f32 v[14:15], v[110:111], v[10:11] op_sel_hi:[1,0]
	v_pk_fma_f32 v[16:17], v[62:63], v[14:15], v[46:47]
	v_pk_mul_f32 v[14:15], v[112:113], v[10:11] op_sel_hi:[1,0]
	v_pk_fma_f32 v[18:19], v[64:65], v[14:15], v[48:49]
	v_cvt_pk_bf16_f32 v134, v16, v17
	v_cvt_pk_bf16_f32 v135, v18, v19
	v_pk_mul_f32 v[14:15], v[114:115], v[10:11] op_sel_hi:[1,0]
	v_pk_fma_f32 v[16:17], v[66:67], v[14:15], v[50:51]
	v_pk_mul_f32 v[14:15], v[116:117], v[10:11] op_sel_hi:[1,0]
	v_pk_fma_f32 v[18:19], v[68:69], v[14:15], v[52:53]
	v_cvt_pk_bf16_f32 v138, v16, v17
	v_cvt_pk_bf16_f32 v139, v18, v19
	global_store_dwordx4 v0, v[102:105], s[46:47] offset:0 sc1
	global_store_dwordx4 v0, v[106:109], s[46:47] offset:1024 sc1
	global_store_dwordx4 v0, v[110:113], s[46:47] offset:2048 sc1
	global_store_dwordx4 v0, v[114:117], s[46:47] offset:3072 sc1
	global_store_dwordx2 v1, v[118:119], s[62:63] offset:0 sc1
	global_store_dwordx2 v1, v[122:123], s[62:63] offset:512 sc1
	global_store_dwordx2 v1, v[134:135], s[62:63] offset:1024 sc1
	global_store_dwordx2 v1, v[138:139], s[62:63] offset:1536 sc1
	s_add_u32 s46, s46, 0x1000
	s_addc_u32 s47, s47, 0
	s_add_u32 s62, s62, 0x800
	s_addc_u32 s63, s63, 0
	s_waitcnt vmcnt(24)
	v_lshlrev_b32_e32 v14, 16, v172
	v_and_b32_e32 v15, 0xffff0000, v172
	v_lshlrev_b32_e32 v16, 16, v174
	v_and_b32_e32 v17, 0xffff0000, v174
	v_lshlrev_b32_e32 v18, 16, v173
	v_and_b32_e32 v19, 0xffff0000, v173
	v_lshlrev_b32_e32 v20, 16, v175
	v_and_b32_e32 v21, 0xffff0000, v175
	v_pk_add_f32 v[172:173], v[14:15], v[16:17]
	v_pk_add_f32 v[174:175], v[18:19], v[20:21]
	v_lshlrev_b32_e32 v14, 16, v176
	v_and_b32_e32 v15, 0xffff0000, v176
	v_lshlrev_b32_e32 v16, 16, v178
	v_and_b32_e32 v17, 0xffff0000, v178
	v_lshlrev_b32_e32 v18, 16, v177
	v_and_b32_e32 v19, 0xffff0000, v177
	v_lshlrev_b32_e32 v20, 16, v179
	v_and_b32_e32 v21, 0xffff0000, v179
	v_pk_add_f32 v[176:177], v[14:15], v[16:17]
	v_pk_add_f32 v[178:179], v[18:19], v[20:21]
	v_lshlrev_b32_e32 v14, 16, v204
	v_and_b32_e32 v15, 0xffff0000, v204
	v_lshlrev_b32_e32 v16, 16, v206
	v_and_b32_e32 v17, 0xffff0000, v206
	v_lshlrev_b32_e32 v18, 16, v205
	v_and_b32_e32 v19, 0xffff0000, v205
	v_lshlrev_b32_e32 v20, 16, v207
	v_and_b32_e32 v21, 0xffff0000, v207
	v_pk_add_f32 v[204:205], v[14:15], v[16:17]
	v_pk_add_f32 v[206:207], v[18:19], v[20:21]
	v_lshlrev_b32_e32 v14, 16, v214
	v_and_b32_e32 v15, 0xffff0000, v214
	v_lshlrev_b32_e32 v16, 16, v216
	v_and_b32_e32 v17, 0xffff0000, v216
	v_lshlrev_b32_e32 v18, 16, v215
	v_and_b32_e32 v19, 0xffff0000, v215
	v_lshlrev_b32_e32 v20, 16, v217
	v_and_b32_e32 v21, 0xffff0000, v217
	v_pk_add_f32 v[214:215], v[14:15], v[16:17]
	v_pk_add_f32 v[216:217], v[18:19], v[20:21]
	v_pk_mul_f32 v[12:13], v[172:173], v[172:173]
	v_pk_fma_f32 v[12:13], v[174:175], v[174:175], v[12:13]
	v_pk_fma_f32 v[12:13], v[176:177], v[176:177], v[12:13]
	v_pk_fma_f32 v[12:13], v[178:179], v[178:179], v[12:13]
	v_pk_fma_f32 v[12:13], v[204:205], v[204:205], v[12:13]
	v_pk_fma_f32 v[12:13], v[206:207], v[206:207], v[12:13]
	v_pk_fma_f32 v[12:13], v[214:215], v[214:215], v[12:13]
	v_pk_fma_f32 v[12:13], v[216:217], v[216:217], v[12:13]
	v_add_f32_e32 v5, v12, v13
	s_nop 1
	v_add_f32_dpp v5, v5, v5 quad_perm:[1,0,3,2] row_mask:0xf bank_mask:0xf
	s_nop 1
	v_add_f32_dpp v5, v5, v5 quad_perm:[2,3,0,1] row_mask:0xf bank_mask:0xf
	s_nop 1
	v_add_f32_dpp v5, v5, v5 row_half_mirror row_mask:0xf bank_mask:0xf
	s_nop 1
	v_add_f32_dpp v5, v5, v5 row_mirror row_mask:0xf bank_mask:0xf
	s_nop 1
	v_add_f32_dpp v5, v5, v5 row_bcast:15 row_mask:0xa bank_mask:0xf
	s_nop 1
	v_add_f32_dpp v5, v5, v5 row_bcast:31 row_mask:0xc bank_mask:0xf
	s_nop 1
	v_readlane_b32 s32, v5, 63
	s_nop 1
	v_mov_b32_e32 v6, s32
	v_fmamk_f32 v6, v6, 0x3a800000, v146
	v_rsq_f32_e32 v6, v6
	s_nop 0
	v_mov_b32_e32 v8, v6
	v_pk_mul_f32 v[14:15], v[172:173], v[8:9] op_sel_hi:[1,0]
	v_pk_fma_f32 v[154:155], v[22:23], v[14:15], v[154:155]
	v_pk_mul_f32 v[14:15], v[174:175], v[8:9] op_sel_hi:[1,0]
	v_pk_fma_f32 v[156:157], v[24:25], v[14:15], v[156:157]
	v_pk_mul_f32 v[14:15], v[176:177], v[8:9] op_sel_hi:[1,0]
	v_pk_fma_f32 v[158:159], v[26:27], v[14:15], v[158:159]
	v_pk_mul_f32 v[14:15], v[178:179], v[8:9] op_sel_hi:[1,0]
	v_pk_fma_f32 v[160:161], v[28:29], v[14:15], v[160:161]
	v_pk_mul_f32 v[14:15], v[204:205], v[8:9] op_sel_hi:[1,0]
	v_pk_fma_f32 v[162:163], v[30:31], v[14:15], v[162:163]
	v_pk_mul_f32 v[14:15], v[206:207], v[8:9] op_sel_hi:[1,0]
	v_pk_fma_f32 v[164:165], v[32:33], v[14:15], v[164:165]
	v_pk_mul_f32 v[14:15], v[214:215], v[8:9] op_sel_hi:[1,0]
	v_pk_fma_f32 v[168:169], v[34:35], v[14:15], v[168:169]
	v_pk_mul_f32 v[14:15], v[216:217], v[8:9] op_sel_hi:[1,0]
	v_pk_fma_f32 v[170:171], v[36:37], v[14:15], v[170:171]
	v_pk_mul_f32 v[12:13], v[154:155], v[154:155]
	v_pk_fma_f32 v[12:13], v[156:157], v[156:157], v[12:13]
	v_pk_fma_f32 v[12:13], v[158:159], v[158:159], v[12:13]
	v_pk_fma_f32 v[12:13], v[160:161], v[160:161], v[12:13]
	v_pk_fma_f32 v[12:13], v[162:163], v[162:163], v[12:13]
	v_pk_fma_f32 v[12:13], v[164:165], v[164:165], v[12:13]
	v_pk_fma_f32 v[12:13], v[168:169], v[168:169], v[12:13]
	v_pk_fma_f32 v[12:13], v[170:171], v[170:171], v[12:13]
	v_add_f32_e32 v5, v12, v13
	s_nop 1
	v_add_f32_dpp v5, v5, v5 quad_perm:[1,0,3,2] row_mask:0xf bank_mask:0xf
	s_nop 1
	v_add_f32_dpp v5, v5, v5 quad_perm:[2,3,0,1] row_mask:0xf bank_mask:0xf
	s_nop 1
	v_add_f32_dpp v5, v5, v5 row_half_mirror row_mask:0xf bank_mask:0xf
	s_nop 1
	v_add_f32_dpp v5, v5, v5 row_mirror row_mask:0xf bank_mask:0xf
	s_nop 1
	v_add_f32_dpp v5, v5, v5 row_bcast:15 row_mask:0xa bank_mask:0xf
	s_nop 1
	v_add_f32_dpp v5, v5, v5 row_bcast:31 row_mask:0xc bank_mask:0xf
	s_nop 1
	v_readlane_b32 s32, v5, 63
	s_nop 1
	v_mov_b32_e32 v6, s32
	v_fmamk_f32 v6, v6, 0x3a800000, v146
	v_rsq_f32_e32 v6, v6
	s_nop 0
	v_mov_b32_e32 v10, v6
	v_pk_mul_f32 v[14:15], v[154:155], v[10:11] op_sel_hi:[1,0]
	v_pk_fma_f32 v[16:17], v[54:55], v[14:15], v[38:39]
	v_pk_mul_f32 v[14:15], v[156:157], v[10:11] op_sel_hi:[1,0]
	v_pk_fma_f32 v[18:19], v[56:57], v[14:15], v[40:41]
	v_cvt_pk_bf16_f32 v172, v16, v17
	v_cvt_pk_bf16_f32 v173, v18, v19
	v_pk_mul_f32 v[14:15], v[158:159], v[10:11] op_sel_hi:[1,0]
	v_pk_fma_f32 v[16:17], v[58:59], v[14:15], v[42:43]
	v_pk_mul_f32 v[14:15], v[160:161], v[10:11] op_sel_hi:[1,0]
	v_pk_fma_f32 v[18:19], v[60:61], v[14:15], v[44:45]
	v_cvt_pk_bf16_f32 v176, v16, v17
	v_cvt_pk_bf16_f32 v177, v18, v19
	v_pk_mul_f32 v[14:15], v[162:163], v[10:11] op_sel_hi:[1,0]
	v_pk_fma_f32 v[16:17], v[62:63], v[14:15], v[46:47]
	v_pk_mul_f32 v[14:15], v[164:165], v[10:11] op_sel_hi:[1,0]
	v_pk_fma_f32 v[18:19], v[64:65], v[14:15], v[48:49]
	v_cvt_pk_bf16_f32 v204, v16, v17
	v_cvt_pk_bf16_f32 v205, v18, v19
	v_pk_mul_f32 v[14:15], v[168:169], v[10:11] op_sel_hi:[1,0]
	v_pk_fma_f32 v[16:17], v[66:67], v[14:15], v[50:51]
	v_pk_mul_f32 v[14:15], v[170:171], v[10:11] op_sel_hi:[1,0]
	v_pk_fma_f32 v[18:19], v[68:69], v[14:15], v[52:53]
	v_cvt_pk_bf16_f32 v214, v16, v17
	v_cvt_pk_bf16_f32 v215, v18, v19
	global_store_dwordx4 v0, v[154:157], s[46:47] offset:0 sc1
	global_store_dwordx4 v0, v[158:161], s[46:47] offset:1024 sc1
	global_store_dwordx4 v0, v[162:165], s[46:47] offset:2048 sc1
	global_store_dwordx4 v0, v[168:171], s[46:47] offset:3072 sc1
	global_store_dwordx2 v1, v[172:173], s[62:63] offset:0 sc1
	global_store_dwordx2 v1, v[176:177], s[62:63] offset:512 sc1
	global_store_dwordx2 v1, v[204:205], s[62:63] offset:1024 sc1
	global_store_dwordx2 v1, v[214:215], s[62:63] offset:1536 sc1
	s_add_u32 s46, s46, 0x1000
	s_addc_u32 s47, s47, 0
	s_add_u32 s62, s62, 0x800
	s_addc_u32 s63, s63, 0
	s_waitcnt vmcnt(24)
	v_lshlrev_b32_e32 v14, 16, v234
	v_and_b32_e32 v15, 0xffff0000, v234
	v_lshlrev_b32_e32 v16, 16, v236
	v_and_b32_e32 v17, 0xffff0000, v236
	v_lshlrev_b32_e32 v18, 16, v235
	v_and_b32_e32 v19, 0xffff0000, v235
	v_lshlrev_b32_e32 v20, 16, v237
	v_and_b32_e32 v21, 0xffff0000, v237
	v_pk_add_f32 v[234:235], v[14:15], v[16:17]
	v_pk_add_f32 v[236:237], v[18:19], v[20:21]
	v_lshlrev_b32_e32 v14, 16, v238
	v_and_b32_e32 v15, 0xffff0000, v238
	v_lshlrev_b32_e32 v16, 16, v240
	v_and_b32_e32 v17, 0xffff0000, v240
	v_lshlrev_b32_e32 v18, 16, v239
	v_and_b32_e32 v19, 0xffff0000, v239
	v_lshlrev_b32_e32 v20, 16, v241
	v_and_b32_e32 v21, 0xffff0000, v241
	v_pk_add_f32 v[238:239], v[14:15], v[16:17]
	v_pk_add_f32 v[240:241], v[18:19], v[20:21]
	v_lshlrev_b32_e32 v14, 16, v242
	v_and_b32_e32 v15, 0xffff0000, v242
	v_lshlrev_b32_e32 v16, 16, v244
	v_and_b32_e32 v17, 0xffff0000, v244
	v_lshlrev_b32_e32 v18, 16, v243
	v_and_b32_e32 v19, 0xffff0000, v243
	v_lshlrev_b32_e32 v20, 16, v245
	v_and_b32_e32 v21, 0xffff0000, v245
	v_pk_add_f32 v[242:243], v[14:15], v[16:17]
	v_pk_add_f32 v[244:245], v[18:19], v[20:21]
	v_lshlrev_b32_e32 v14, 16, v246
	v_and_b32_e32 v15, 0xffff0000, v246
	v_lshlrev_b32_e32 v16, 16, v248
	v_and_b32_e32 v17, 0xffff0000, v248
	v_lshlrev_b32_e32 v18, 16, v247
	v_and_b32_e32 v19, 0xffff0000, v247
	v_lshlrev_b32_e32 v20, 16, v249
	v_and_b32_e32 v21, 0xffff0000, v249
	v_pk_add_f32 v[246:247], v[14:15], v[16:17]
	v_pk_add_f32 v[248:249], v[18:19], v[20:21]
	v_pk_mul_f32 v[12:13], v[234:235], v[234:235]
	v_pk_fma_f32 v[12:13], v[236:237], v[236:237], v[12:13]
	v_pk_fma_f32 v[12:13], v[238:239], v[238:239], v[12:13]
	v_pk_fma_f32 v[12:13], v[240:241], v[240:241], v[12:13]
	v_pk_fma_f32 v[12:13], v[242:243], v[242:243], v[12:13]
	v_pk_fma_f32 v[12:13], v[244:245], v[244:245], v[12:13]
	v_pk_fma_f32 v[12:13], v[246:247], v[246:247], v[12:13]
	v_pk_fma_f32 v[12:13], v[248:249], v[248:249], v[12:13]
	v_add_f32_e32 v5, v12, v13
	s_nop 1
	v_add_f32_dpp v5, v5, v5 quad_perm:[1,0,3,2] row_mask:0xf bank_mask:0xf
	s_nop 1
	v_add_f32_dpp v5, v5, v5 quad_perm:[2,3,0,1] row_mask:0xf bank_mask:0xf
	s_nop 1
	v_add_f32_dpp v5, v5, v5 row_half_mirror row_mask:0xf bank_mask:0xf
	s_nop 1
	v_add_f32_dpp v5, v5, v5 row_mirror row_mask:0xf bank_mask:0xf
	s_nop 1
	v_add_f32_dpp v5, v5, v5 row_bcast:15 row_mask:0xa bank_mask:0xf
	s_nop 1
	v_add_f32_dpp v5, v5, v5 row_bcast:31 row_mask:0xc bank_mask:0xf
	s_nop 1
	v_readlane_b32 s32, v5, 63
	s_nop 1
	v_mov_b32_e32 v6, s32
	v_fmamk_f32 v6, v6, 0x3a800000, v146
	v_rsq_f32_e32 v6, v6
	s_nop 0
	v_mov_b32_e32 v8, v6
	v_pk_mul_f32 v[14:15], v[234:235], v[8:9] op_sel_hi:[1,0]
	v_pk_fma_f32 v[218:219], v[22:23], v[14:15], v[218:219]
	v_pk_mul_f32 v[14:15], v[236:237], v[8:9] op_sel_hi:[1,0]
	v_pk_fma_f32 v[220:221], v[24:25], v[14:15], v[220:221]
	v_pk_mul_f32 v[14:15], v[238:239], v[8:9] op_sel_hi:[1,0]
	v_pk_fma_f32 v[222:223], v[26:27], v[14:15], v[222:223]
	v_pk_mul_f32 v[14:15], v[240:241], v[8:9] op_sel_hi:[1,0]
	v_pk_fma_f32 v[224:225], v[28:29], v[14:15], v[224:225]
	v_pk_mul_f32 v[14:15], v[242:243], v[8:9] op_sel_hi:[1,0]
	v_pk_fma_f32 v[226:227], v[30:31], v[14:15], v[226:227]
	v_pk_mul_f32 v[14:15], v[244:245], v[8:9] op_sel_hi:[1,0]
	v_pk_fma_f32 v[228:229], v[32:33], v[14:15], v[228:229]
	v_pk_mul_f32 v[14:15], v[246:247], v[8:9] op_sel_hi:[1,0]
	v_pk_fma_f32 v[230:231], v[34:35], v[14:15], v[230:231]
	v_pk_mul_f32 v[14:15], v[248:249], v[8:9] op_sel_hi:[1,0]
	v_pk_fma_f32 v[232:233], v[36:37], v[14:15], v[232:233]
	v_pk_mul_f32 v[12:13], v[218:219], v[218:219]
	v_pk_fma_f32 v[12:13], v[220:221], v[220:221], v[12:13]
	v_pk_fma_f32 v[12:13], v[222:223], v[222:223], v[12:13]
	v_pk_fma_f32 v[12:13], v[224:225], v[224:225], v[12:13]
	v_pk_fma_f32 v[12:13], v[226:227], v[226:227], v[12:13]
	v_pk_fma_f32 v[12:13], v[228:229], v[228:229], v[12:13]
	v_pk_fma_f32 v[12:13], v[230:231], v[230:231], v[12:13]
	v_pk_fma_f32 v[12:13], v[232:233], v[232:233], v[12:13]
	v_add_f32_e32 v5, v12, v13
	s_nop 1
	v_add_f32_dpp v5, v5, v5 quad_perm:[1,0,3,2] row_mask:0xf bank_mask:0xf
	s_nop 1
	v_add_f32_dpp v5, v5, v5 quad_perm:[2,3,0,1] row_mask:0xf bank_mask:0xf
	s_nop 1
	v_add_f32_dpp v5, v5, v5 row_half_mirror row_mask:0xf bank_mask:0xf
	s_nop 1
	v_add_f32_dpp v5, v5, v5 row_mirror row_mask:0xf bank_mask:0xf
	s_nop 1
	v_add_f32_dpp v5, v5, v5 row_bcast:15 row_mask:0xa bank_mask:0xf
	s_nop 1
	v_add_f32_dpp v5, v5, v5 row_bcast:31 row_mask:0xc bank_mask:0xf
	s_nop 1
	v_readlane_b32 s32, v5, 63
	s_nop 1
	v_mov_b32_e32 v6, s32
	v_fmamk_f32 v6, v6, 0x3a800000, v146
	v_rsq_f32_e32 v6, v6
	s_nop 0
	v_mov_b32_e32 v10, v6
	v_pk_mul_f32 v[14:15], v[218:219], v[10:11] op_sel_hi:[1,0]
	v_pk_fma_f32 v[16:17], v[54:55], v[14:15], v[38:39]
	v_pk_mul_f32 v[14:15], v[220:221], v[10:11] op_sel_hi:[1,0]
	v_pk_fma_f32 v[18:19], v[56:57], v[14:15], v[40:41]
	v_cvt_pk_bf16_f32 v234, v16, v17
	v_cvt_pk_bf16_f32 v235, v18, v19
	v_pk_mul_f32 v[14:15], v[222:223], v[10:11] op_sel_hi:[1,0]
	v_pk_fma_f32 v[16:17], v[58:59], v[14:15], v[42:43]
	v_pk_mul_f32 v[14:15], v[224:225], v[10:11] op_sel_hi:[1,0]
	v_pk_fma_f32 v[18:19], v[60:61], v[14:15], v[44:45]
	v_cvt_pk_bf16_f32 v238, v16, v17
	v_cvt_pk_bf16_f32 v239, v18, v19
	v_pk_mul_f32 v[14:15], v[226:227], v[10:11] op_sel_hi:[1,0]
	v_pk_fma_f32 v[16:17], v[62:63], v[14:15], v[46:47]
	v_pk_mul_f32 v[14:15], v[228:229], v[10:11] op_sel_hi:[1,0]
	v_pk_fma_f32 v[18:19], v[64:65], v[14:15], v[48:49]
	v_cvt_pk_bf16_f32 v242, v16, v17
	v_cvt_pk_bf16_f32 v243, v18, v19
	v_pk_mul_f32 v[14:15], v[230:231], v[10:11] op_sel_hi:[1,0]
	v_pk_fma_f32 v[16:17], v[66:67], v[14:15], v[50:51]
	v_pk_mul_f32 v[14:15], v[232:233], v[10:11] op_sel_hi:[1,0]
	v_pk_fma_f32 v[18:19], v[68:69], v[14:15], v[52:53]
	v_cvt_pk_bf16_f32 v246, v16, v17
	v_cvt_pk_bf16_f32 v247, v18, v19
	global_store_dwordx4 v0, v[218:221], s[46:47] offset:0 sc1
	global_store_dwordx4 v0, v[222:225], s[46:47] offset:1024 sc1
	global_store_dwordx4 v0, v[226:229], s[46:47] offset:2048 sc1
	global_store_dwordx4 v0, v[230:233], s[46:47] offset:3072 sc1
	global_store_dwordx2 v1, v[234:235], s[62:63] offset:0 sc1
	global_store_dwordx2 v1, v[238:239], s[62:63] offset:512 sc1
	global_store_dwordx2 v1, v[242:243], s[62:63] offset:1024 sc1
	global_store_dwordx2 v1, v[246:247], s[62:63] offset:1536 sc1
	s_add_u32 s46, s46, 0x1000
	s_addc_u32 s47, s47, 0
	s_add_u32 s62, s62, 0x800
	s_addc_u32 s63, s63, 0

.LBB0_1276:
	v_readlane_b32 s2, v255, 0
	s_nop 0
	v_ashrrev_i32_e32 v0, 6, v147
	v_lshl_add_u32 v32, s2, 3, v0
	s_movk_i32 s2, 0x2000
	v_cmp_gt_i32_e32 vcc, s2, v32
	s_and_saveexec_b64 s[2:3], vcc
	s_cbranch_execz .LBB0_1279
	v_readlane_b32 s2, v255, 0
	v_readfirstlane_b32 s7, v147
	s_load_dwordx2 s[4:5], s[0:1], 0x90
	s_load_dwordx2 s[12:13], s[0:1], 0x98
	s_load_dwordx2 s[40:41], s[0:1], 0x48
	v_and_b32_e32 v0, 63, v147
	v_lshlrev_b32_e32 v1, 3, v0
	v_lshlrev_b32_e32 v0, 4, v0
	s_lshr_b32 s7, s7, 6
	s_and_b32 s27, s2, 6
	s_lshl_b32 s27, s27, 5
	s_and_b32 s37, s2, 0x39
	s_or_b32 s27, s27, s37
	s_lshr_b32 s37, s2, 6
	s_lshl_b32 s37, s37, 1
	s_or_b32 s2, s27, s37
	s_lshl_b32 s2, s2, 3
	s_add_u32 s2, s2, s7
	s_lshl_b32 s24, s2, 2
	s_sub_u32 s27, s24, 0x1000
	s_lshr_b32 s27, s27, 10
	s_add_u32 s27, s27, 1
	s_cmp_lt_u32 s24, 0x1000
	s_cselect_b32 s30, 0, s27
	v_add_u32_e32 v2, 0x8000, v0
	v_mov_b32_e32 v3, v0
	v_add_u32_e32 v4, 0x1000, v0
	s_waitcnt lgkmcnt(0)
	s_lshl_b32 s27, s24, 11
	s_add_u32 s62, s12, s27
	s_addc_u32 s63, s13, 0
	s_add_u32 s58, s62, 0x8800000
	s_addc_u32 s59, s63, 0
	s_add_u32 s60, s58, 0x1000000
	s_addc_u32 s61, s59, 0
	s_add_u32 s62, s62, 0x1000000
	s_addc_u32 s63, s63, 0
	s_lshl_b32 s27, s24, 12
	s_add_u32 s46, s4, s27
	s_addc_u32 s47, s5, 0
	s_mov_b64 s[4:5], s[46:47]
	s_add_u32 s27, s30, 15
	s_mul_i32 s27, s27, 0x9000
	s_add_u32 s27, s27, 0x100000
	s_add_u32 s88, s12, s27
	s_addc_u32 s89, s13, 0
	s_mov_b64 s[100:101], s[88:89]
	s_mov_b32 s27, 0xb000
	s_add_u32 s40, s40, s27
	s_addc_u32 s41, s41, 0
	global_load_dwordx4 v[22:25], v2, s[100:101] offset:0
	global_load_dwordx4 v[118:121], v0, s[40:41] offset:0
	global_load_dwordx4 v[26:29], v2, s[100:101] offset:1024
	global_load_dwordx4 v[122:125], v0, s[40:41] offset:1024
	global_load_dwordx4 v[30:33], v2, s[100:101] offset:2048
	global_load_dwordx4 v[134:137], v0, s[40:41] offset:2048
	global_load_dwordx4 v[34:37], v2, s[100:101] offset:3072
	global_load_dwordx4 v[138:141], v0, s[40:41] offset:3072
	global_load_dwordx4 v[38:41], v0, s[4:5] offset:0
	global_load_dwordx4 v[42:45], v0, s[4:5] offset:1024
	global_load_dwordx4 v[46:49], v0, s[4:5] offset:2048
	global_load_dwordx4 v[50:53], v0, s[4:5] offset:3072
	s_add_u32 s4, s4, 0x1000
	s_addc_u32 s5, s5, 0
	global_load_dwordx4 v[70:73], v0, s[4:5] offset:0
	global_load_dwordx4 v[74:77], v0, s[4:5] offset:1024
	global_load_dwordx4 v[78:81], v0, s[4:5] offset:2048
	global_load_dwordx4 v[82:85], v0, s[4:5] offset:3072
	s_add_u32 s4, s4, 0x1000
	s_addc_u32 s5, s5, 0
	global_load_dwordx4 v[102:105], v0, s[4:5] offset:0
	global_load_dwordx4 v[106:109], v0, s[4:5] offset:1024
	global_load_dwordx4 v[110:113], v0, s[4:5] offset:2048
	global_load_dwordx4 v[114:117], v0, s[4:5] offset:3072
	s_add_u32 s4, s4, 0x1000
	s_addc_u32 s5, s5, 0
	global_load_dwordx4 v[154:157], v0, s[4:5] offset:0
	global_load_dwordx4 v[158:161], v0, s[4:5] offset:1024
	global_load_dwordx4 v[162:165], v0, s[4:5] offset:2048
	global_load_dwordx4 v[168:171], v0, s[4:5] offset:3072
	s_add_u32 s4, s4, 0x1000
	s_addc_u32 s5, s5, 0
	s_waitcnt vmcnt(16)
	v_pk_mul_f32 v[22:23], v[22:23], v[118:119]
	v_pk_mul_f32 v[24:25], v[24:25], v[120:121]
	v_pk_mul_f32 v[26:27], v[26:27], v[122:123]
	v_pk_mul_f32 v[28:29], v[28:29], v[124:125]
	v_pk_mul_f32 v[30:31], v[30:31], v[134:135]
	v_pk_mul_f32 v[32:33], v[32:33], v[136:137]
	v_pk_mul_f32 v[34:35], v[34:35], v[138:139]
	v_pk_mul_f32 v[36:37], v[36:37], v[140:141]
	v_cmp_eq_u32_e32 vcc, 0, v147
	s_and_saveexec_b64 s[40:41], vcc
	s_cbranch_execz .Lnw_skip_n3
	v_readlane_b32 s2, v255, 0
	v_readlane_b32 s7, v255, 46
	s_nop 0
	s_lshr_b32 s24, s2, 3
	s_and_b32 s24, s24, 7
	s_and_b32 s27, s2, 6
	s_lshl_b32 s27, s27, 2
	s_or_b32 s27, s27, s24
	s_lshl_b32 s27, s27, 7
	s_add_u32 s27, s27, 0xa000
	v_mov_b32_e32 v14, s27
	s_mov_b32 s30, 0

.Lnw_skip_n3:
	s_or_b64 exec, exec, s[40:41]
	s_barrier
	global_load_dwordx2 v[54:55], v1, s[58:59] offset:0
	global_load_dwordx2 v[58:59], v1, s[58:59] offset:512
	global_load_dwordx2 v[62:63], v1, s[58:59] offset:1024
	global_load_dwordx2 v[66:67], v1, s[58:59] offset:1536
	global_load_dwordx2 v[56:57], v1, s[60:61] offset:0
	global_load_dwordx2 v[60:61], v1, s[60:61] offset:512
	global_load_dwordx2 v[64:65], v1, s[60:61] offset:1024
	global_load_dwordx2 v[68:69], v1, s[60:61] offset:1536
	s_add_u32 s58, s58, 0x800
	s_addc_u32 s59, s59, 0
	s_add_u32 s60, s60, 0x800
	s_addc_u32 s61, s61, 0
	global_load_dwordx2 v[86:87], v1, s[58:59] offset:0
	global_load_dwordx2 v[90:91], v1, s[58:59] offset:512
	global_load_dwordx2 v[94:95], v1, s[58:59] offset:1024
	global_load_dwordx2 v[98:99], v1, s[58:59] offset:1536
	global_load_dwordx2 v[88:89], v1, s[60:61] offset:0
	global_load_dwordx2 v[92:93], v1, s[60:61] offset:512
	global_load_dwordx2 v[96:97], v1, s[60:61] offset:1024
	global_load_dwordx2 v[100:101], v1, s[60:61] offset:1536
	s_add_u32 s58, s58, 0x800
	s_addc_u32 s59, s59, 0
	s_add_u32 s60, s60, 0x800
	s_addc_u32 s61, s61, 0
	global_load_dwordx2 v[118:119], v1, s[58:59] offset:0
	global_load_dwordx2 v[122:123], v1, s[58:59] offset:512
	global_load_dwordx2 v[134:135], v1, s[58:59] offset:1024
	global_load_dwordx2 v[138:139], v1, s[58:59] offset:1536
	global_load_dwordx2 v[120:121], v1, s[60:61] offset:0
	global_load_dwordx2 v[124:125], v1, s[60:61] offset:512
	global_load_dwordx2 v[136:137], v1, s[60:61] offset:1024
	global_load_dwordx2 v[140:141], v1, s[60:61] offset:1536
	s_add_u32 s58, s58, 0x800
	s_addc_u32 s59, s59, 0
	s_add_u32 s60, s60, 0x800
	s_addc_u32 s61, s61, 0
	global_load_dwordx2 v[172:173], v1, s[58:59] offset:0
	global_load_dwordx2 v[176:177], v1, s[58:59] offset:512
	global_load_dwordx2 v[204:205], v1, s[58:59] offset:1024
	global_load_dwordx2 v[214:215], v1, s[58:59] offset:1536
	global_load_dwordx2 v[174:175], v1, s[60:61] offset:0
	global_load_dwordx2 v[178:179], v1, s[60:61] offset:512
	global_load_dwordx2 v[206:207], v1, s[60:61] offset:1024
	global_load_dwordx2 v[216:217], v1, s[60:61] offset:1536
	s_add_u32 s58, s58, 0x800
	s_addc_u32 s59, s59, 0
	s_add_u32 s60, s60, 0x800
	s_addc_u32 s61, s61, 0
	s_waitcnt vmcnt(24)
	v_lshlrev_b32_e32 v14, 16, v54
	v_and_b32_e32 v15, 0xffff0000, v54
	v_lshlrev_b32_e32 v16, 16, v56
	v_and_b32_e32 v17, 0xffff0000, v56
	v_lshlrev_b32_e32 v18, 16, v55
	v_and_b32_e32 v19, 0xffff0000, v55
	v_lshlrev_b32_e32 v20, 16, v57
	v_and_b32_e32 v21, 0xffff0000, v57
	v_pk_add_f32 v[54:55], v[14:15], v[16:17]
	v_pk_add_f32 v[56:57], v[18:19], v[20:21]
	v_lshlrev_b32_e32 v14, 16, v58
	v_and_b32_e32 v15, 0xffff0000, v58
	v_lshlrev_b32_e32 v16, 16, v60
	v_and_b32_e32 v17, 0xffff0000, v60
	v_lshlrev_b32_e32 v18, 16, v59
	v_and_b32_e32 v19, 0xffff0000, v59
	v_lshlrev_b32_e32 v20, 16, v61
	v_and_b32_e32 v21, 0xffff0000, v61
	v_pk_add_f32 v[58:59], v[14:15], v[16:17]
	v_pk_add_f32 v[60:61], v[18:19], v[20:21]
	v_lshlrev_b32_e32 v14, 16, v62
	v_and_b32_e32 v15, 0xffff0000, v62
	v_lshlrev_b32_e32 v16, 16, v64
	v_and_b32_e32 v17, 0xffff0000, v64
	v_lshlrev_b32_e32 v18, 16, v63
	v_and_b32_e32 v19, 0xffff0000, v63
	v_lshlrev_b32_e32 v20, 16, v65
	v_and_b32_e32 v21, 0xffff0000, v65
	v_pk_add_f32 v[62:63], v[14:15], v[16:17]
	v_pk_add_f32 v[64:65], v[18:19], v[20:21]
	v_lshlrev_b32_e32 v14, 16, v66
	v_and_b32_e32 v15, 0xffff0000, v66
	v_lshlrev_b32_e32 v16, 16, v68
	v_and_b32_e32 v17, 0xffff0000, v68
	v_lshlrev_b32_e32 v18, 16, v67
	v_and_b32_e32 v19, 0xffff0000, v67
	v_lshlrev_b32_e32 v20, 16, v69
	v_and_b32_e32 v21, 0xffff0000, v69
	v_pk_add_f32 v[66:67], v[14:15], v[16:17]
	v_pk_add_f32 v[68:69], v[18:19], v[20:21]
	v_pk_mul_f32 v[12:13], v[54:55], v[54:55]
	v_pk_fma_f32 v[12:13], v[56:57], v[56:57], v[12:13]
	v_pk_fma_f32 v[12:13], v[58:59], v[58:59], v[12:13]
	v_pk_fma_f32 v[12:13], v[60:61], v[60:61], v[12:13]
	v_pk_fma_f32 v[12:13], v[62:63], v[62:63], v[12:13]
	v_pk_fma_f32 v[12:13], v[64:65], v[64:65], v[12:13]
	v_pk_fma_f32 v[12:13], v[66:67], v[66:67], v[12:13]
	v_pk_fma_f32 v[12:13], v[68:69], v[68:69], v[12:13]
	v_add_f32_e32 v5, v12, v13
	s_nop 1
	v_add_f32_dpp v5, v5, v5 quad_perm:[1,0,3,2] row_mask:0xf bank_mask:0xf
	s_nop 1
	v_add_f32_dpp v5, v5, v5 quad_perm:[2,3,0,1] row_mask:0xf bank_mask:0xf
	s_nop 1
	v_add_f32_dpp v5, v5, v5 row_half_mirror row_mask:0xf bank_mask:0xf
	s_nop 1
	v_add_f32_dpp v5, v5, v5 row_mirror row_mask:0xf bank_mask:0xf
	s_nop 1
	v_add_f32_dpp v5, v5, v5 row_bcast:15 row_mask:0xa bank_mask:0xf
	s_nop 1
	v_add_f32_dpp v5, v5, v5 row_bcast:31 row_mask:0xc bank_mask:0xf
	s_nop 1
	v_readlane_b32 s32, v5, 63
	s_nop 1
	v_mov_b32_e32 v6, s32
	v_fmamk_f32 v6, v6, 0x3a800000, v146
	v_rsq_f32_e32 v6, v6
	s_nop 0
	v_mul_f32_e32 v8, 0.5, v6
	v_pk_mul_f32 v[14:15], v[54:55], v[8:9] op_sel_hi:[1,0]
	v_pk_fma_f32 v[38:39], v[22:23], v[14:15], v[38:39]
	v_pk_mul_f32 v[14:15], v[56:57], v[8:9] op_sel_hi:[1,0]
	v_pk_fma_f32 v[40:41], v[24:25], v[14:15], v[40:41]
	v_pk_mul_f32 v[14:15], v[58:59], v[8:9] op_sel_hi:[1,0]
	v_pk_fma_f32 v[42:43], v[26:27], v[14:15], v[42:43]
	v_pk_mul_f32 v[14:15], v[60:61], v[8:9] op_sel_hi:[1,0]
	v_pk_fma_f32 v[44:45], v[28:29], v[14:15], v[44:45]
	v_pk_mul_f32 v[14:15], v[62:63], v[8:9] op_sel_hi:[1,0]
	v_pk_fma_f32 v[46:47], v[30:31], v[14:15], v[46:47]
	v_pk_mul_f32 v[14:15], v[64:65], v[8:9] op_sel_hi:[1,0]
	v_pk_fma_f32 v[48:49], v[32:33], v[14:15], v[48:49]
	v_pk_mul_f32 v[14:15], v[66:67], v[8:9] op_sel_hi:[1,0]
	v_pk_fma_f32 v[50:51], v[34:35], v[14:15], v[50:51]
	v_pk_mul_f32 v[14:15], v[68:69], v[8:9] op_sel_hi:[1,0]
	v_pk_fma_f32 v[52:53], v[36:37], v[14:15], v[52:53]
	global_store_dwordx4 v0, v[38:41], s[46:47] offset:0
	global_store_dwordx4 v0, v[42:45], s[46:47] offset:1024
	global_store_dwordx4 v0, v[46:49], s[46:47] offset:2048
	global_store_dwordx4 v0, v[50:53], s[46:47] offset:3072
	s_add_u32 s46, s46, 0x1000
	s_addc_u32 s47, s47, 0
	s_add_u32 s62, s62, 0x800
	s_addc_u32 s63, s63, 0
	s_waitcnt vmcnt(20)
	v_lshlrev_b32_e32 v14, 16, v86
	v_and_b32_e32 v15, 0xffff0000, v86
	v_lshlrev_b32_e32 v16, 16, v88
	v_and_b32_e32 v17, 0xffff0000, v88
	v_lshlrev_b32_e32 v18, 16, v87
	v_and_b32_e32 v19, 0xffff0000, v87
	v_lshlrev_b32_e32 v20, 16, v89
	v_and_b32_e32 v21, 0xffff0000, v89
	v_pk_add_f32 v[86:87], v[14:15], v[16:17]
	v_pk_add_f32 v[88:89], v[18:19], v[20:21]
	v_lshlrev_b32_e32 v14, 16, v90
	v_and_b32_e32 v15, 0xffff0000, v90
	v_lshlrev_b32_e32 v16, 16, v92
	v_and_b32_e32 v17, 0xffff0000, v92
	v_lshlrev_b32_e32 v18, 16, v91
	v_and_b32_e32 v19, 0xffff0000, v91
	v_lshlrev_b32_e32 v20, 16, v93
	v_and_b32_e32 v21, 0xffff0000, v93
	v_pk_add_f32 v[90:91], v[14:15], v[16:17]
	v_pk_add_f32 v[92:93], v[18:19], v[20:21]
	v_lshlrev_b32_e32 v14, 16, v94
	v_and_b32_e32 v15, 0xffff0000, v94
	v_lshlrev_b32_e32 v16, 16, v96
	v_and_b32_e32 v17, 0xffff0000, v96
	v_lshlrev_b32_e32 v18, 16, v95
	v_and_b32_e32 v19, 0xffff0000, v95
	v_lshlrev_b32_e32 v20, 16, v97
	v_and_b32_e32 v21, 0xffff0000, v97
	v_pk_add_f32 v[94:95], v[14:15], v[16:17]
	v_pk_add_f32 v[96:97], v[18:19], v[20:21]
	v_lshlrev_b32_e32 v14, 16, v98
	v_and_b32_e32 v15, 0xffff0000, v98
	v_lshlrev_b32_e32 v16, 16, v100
	v_and_b32_e32 v17, 0xffff0000, v100
	v_lshlrev_b32_e32 v18, 16, v99
	v_and_b32_e32 v19, 0xffff0000, v99
	v_lshlrev_b32_e32 v20, 16, v101
	v_and_b32_e32 v21, 0xffff0000, v101
	v_pk_add_f32 v[98:99], v[14:15], v[16:17]
	v_pk_add_f32 v[100:101], v[18:19], v[20:21]
	v_pk_mul_f32 v[12:13], v[86:87], v[86:87]
	v_pk_fma_f32 v[12:13], v[88:89], v[88:89], v[12:13]
	v_pk_fma_f32 v[12:13], v[90:91], v[90:91], v[12:13]
	v_pk_fma_f32 v[12:13], v[92:93], v[92:93], v[12:13]
	v_pk_fma_f32 v[12:13], v[94:95], v[94:95], v[12:13]
	v_pk_fma_f32 v[12:13], v[96:97], v[96:97], v[12:13]
	v_pk_fma_f32 v[12:13], v[98:99], v[98:99], v[12:13]
	v_pk_fma_f32 v[12:13], v[100:101], v[100:101], v[12:13]
	v_add_f32_e32 v5, v12, v13
	s_nop 1
	v_add_f32_dpp v5, v5, v5 quad_perm:[1,0,3,2] row_mask:0xf bank_mask:0xf
	s_nop 1
	v_add_f32_dpp v5, v5, v5 quad_perm:[2,3,0,1] row_mask:0xf bank_mask:0xf
	s_nop 1
	v_add_f32_dpp v5, v5, v5 row_half_mirror row_mask:0xf bank_mask:0xf
	s_nop 1
	v_add_f32_dpp v5, v5, v5 row_mirror row_mask:0xf bank_mask:0xf
	s_nop 1
	v_add_f32_dpp v5, v5, v5 row_bcast:15 row_mask:0xa bank_mask:0xf
	s_nop 1
	v_add_f32_dpp v5, v5, v5 row_bcast:31 row_mask:0xc bank_mask:0xf
	s_nop 1
	v_readlane_b32 s32, v5, 63
	s_nop 1
	v_mov_b32_e32 v6, s32
	v_fmamk_f32 v6, v6, 0x3a800000, v146
	v_rsq_f32_e32 v6, v6
	s_nop 0
	v_mul_f32_e32 v8, 0.5, v6
	v_pk_mul_f32 v[14:15], v[86:87], v[8:9] op_sel_hi:[1,0]
	v_pk_fma_f32 v[70:71], v[22:23], v[14:15], v[70:71]
	v_pk_mul_f32 v[14:15], v[88:89], v[8:9] op_sel_hi:[1,0]
	v_pk_fma_f32 v[72:73], v[24:25], v[14:15], v[72:73]
	v_pk_mul_f32 v[14:15], v[90:91], v[8:9] op_sel_hi:[1,0]
	v_pk_fma_f32 v[74:75], v[26:27], v[14:15], v[74:75]
	v_pk_mul_f32 v[14:15], v[92:93], v[8:9] op_sel_hi:[1,0]
	v_pk_fma_f32 v[76:77], v[28:29], v[14:15], v[76:77]
	v_pk_mul_f32 v[14:15], v[94:95], v[8:9] op_sel_hi:[1,0]
	v_pk_fma_f32 v[78:79], v[30:31], v[14:15], v[78:79]
	v_pk_mul_f32 v[14:15], v[96:97], v[8:9] op_sel_hi:[1,0]
	v_pk_fma_f32 v[80:81], v[32:33], v[14:15], v[80:81]
	v_pk_mul_f32 v[14:15], v[98:99], v[8:9] op_sel_hi:[1,0]
	v_pk_fma_f32 v[82:83], v[34:35], v[14:15], v[82:83]
	v_pk_mul_f32 v[14:15], v[100:101], v[8:9] op_sel_hi:[1,0]
	v_pk_fma_f32 v[84:85], v[36:37], v[14:15], v[84:85]
	global_store_dwordx4 v0, v[70:73], s[46:47] offset:0
	global_store_dwordx4 v0, v[74:77], s[46:47] offset:1024
	global_store_dwordx4 v0, v[78:81], s[46:47] offset:2048
	global_store_dwordx4 v0, v[82:85], s[46:47] offset:3072
	s_add_u32 s46, s46, 0x1000
	s_addc_u32 s47, s47, 0
	s_add_u32 s62, s62, 0x800
	s_addc_u32 s63, s63, 0
	s_waitcnt vmcnt(16)
	v_lshlrev_b32_e32 v14, 16, v118
	v_and_b32_e32 v15, 0xffff0000, v118
	v_lshlrev_b32_e32 v16, 16, v120
	v_and_b32_e32 v17, 0xffff0000, v120
	v_lshlrev_b32_e32 v18, 16, v119
	v_and_b32_e32 v19, 0xffff0000, v119
	v_lshlrev_b32_e32 v20, 16, v121
	v_and_b32_e32 v21, 0xffff0000, v121
	v_pk_add_f32 v[118:119], v[14:15], v[16:17]
	v_pk_add_f32 v[120:121], v[18:19], v[20:21]
	v_lshlrev_b32_e32 v14, 16, v122
	v_and_b32_e32 v15, 0xffff0000, v122
	v_lshlrev_b32_e32 v16, 16, v124
	v_and_b32_e32 v17, 0xffff0000, v124
	v_lshlrev_b32_e32 v18, 16, v123
	v_and_b32_e32 v19, 0xffff0000, v123
	v_lshlrev_b32_e32 v20, 16, v125
	v_and_b32_e32 v21, 0xffff0000, v125
	v_pk_add_f32 v[122:123], v[14:15], v[16:17]
	v_pk_add_f32 v[124:125], v[18:19], v[20:21]
	v_lshlrev_b32_e32 v14, 16, v134
	v_and_b32_e32 v15, 0xffff0000, v134
	v_lshlrev_b32_e32 v16, 16, v136
	v_and_b32_e32 v17, 0xffff0000, v136
	v_lshlrev_b32_e32 v18, 16, v135
	v_and_b32_e32 v19, 0xffff0000, v135
	v_lshlrev_b32_e32 v20, 16, v137
	v_and_b32_e32 v21, 0xffff0000, v137
	v_pk_add_f32 v[134:135], v[14:15], v[16:17]
	v_pk_add_f32 v[136:137], v[18:19], v[20:21]
	v_lshlrev_b32_e32 v14, 16, v138
	v_and_b32_e32 v15, 0xffff0000, v138
	v_lshlrev_b32_e32 v16, 16, v140
	v_and_b32_e32 v17, 0xffff0000, v140
	v_lshlrev_b32_e32 v18, 16, v139
	v_and_b32_e32 v19, 0xffff0000, v139
	v_lshlrev_b32_e32 v20, 16, v141
	v_and_b32_e32 v21, 0xffff0000, v141
	v_pk_add_f32 v[138:139], v[14:15], v[16:17]
	v_pk_add_f32 v[140:141], v[18:19], v[20:21]
	v_pk_mul_f32 v[12:13], v[118:119], v[118:119]
	v_pk_fma_f32 v[12:13], v[120:121], v[120:121], v[12:13]
	v_pk_fma_f32 v[12:13], v[122:123], v[122:123], v[12:13]
	v_pk_fma_f32 v[12:13], v[124:125], v[124:125], v[12:13]
	v_pk_fma_f32 v[12:13], v[134:135], v[134:135], v[12:13]
	v_pk_fma_f32 v[12:13], v[136:137], v[136:137], v[12:13]
	v_pk_fma_f32 v[12:13], v[138:139], v[138:139], v[12:13]
	v_pk_fma_f32 v[12:13], v[140:141], v[140:141], v[12:13]
	v_add_f32_e32 v5, v12, v13
	s_nop 1
	v_add_f32_dpp v5, v5, v5 quad_perm:[1,0,3,2] row_mask:0xf bank_mask:0xf
	s_nop 1
	v_add_f32_dpp v5, v5, v5 quad_perm:[2,3,0,1] row_mask:0xf bank_mask:0xf
	s_nop 1
	v_add_f32_dpp v5, v5, v5 row_half_mirror row_mask:0xf bank_mask:0xf
	s_nop 1
	v_add_f32_dpp v5, v5, v5 row_mirror row_mask:0xf bank_mask:0xf
	s_nop 1
	v_add_f32_dpp v5, v5, v5 row_bcast:15 row_mask:0xa bank_mask:0xf
	s_nop 1
	v_add_f32_dpp v5, v5, v5 row_bcast:31 row_mask:0xc bank_mask:0xf
	s_nop 1
	v_readlane_b32 s32, v5, 63
	s_nop 1
	v_mov_b32_e32 v6, s32
	v_fmamk_f32 v6, v6, 0x3a800000, v146
	v_rsq_f32_e32 v6, v6
	s_nop 0
	v_mul_f32_e32 v8, 0.5, v6
	v_pk_mul_f32 v[14:15], v[118:119], v[8:9] op_sel_hi:[1,0]
	v_pk_fma_f32 v[102:103], v[22:23], v[14:15], v[102:103]
	v_pk_mul_f32 v[14:15], v[120:121], v[8:9] op_sel_hi:[1,0]
	v_pk_fma_f32 v[104:105], v[24:25], v[14:15], v[104:105]
	v_pk_mul_f32 v[14:15], v[122:123], v[8:9] op_sel_hi:[1,0]
	v_pk_fma_f32 v[106:107], v[26:27], v[14:15], v[106:107]
	v_pk_mul_f32 v[14:15], v[124:125], v[8:9] op_sel_hi:[1,0]
	v_pk_fma_f32 v[108:109], v[28:29], v[14:15], v[108:109]
	v_pk_mul_f32 v[14:15], v[134:135], v[8:9] op_sel_hi:[1,0]
	v_pk_fma_f32 v[110:111], v[30:31], v[14:15], v[110:111]
	v_pk_mul_f32 v[14:15], v[136:137], v[8:9] op_sel_hi:[1,0]
	v_pk_fma_f32 v[112:113], v[32:33], v[14:15], v[112:113]
	v_pk_mul_f32 v[14:15], v[138:139], v[8:9] op_sel_hi:[1,0]
	v_pk_fma_f32 v[114:115], v[34:35], v[14:15], v[114:115]
	v_pk_mul_f32 v[14:15], v[140:141], v[8:9] op_sel_hi:[1,0]
	v_pk_fma_f32 v[116:117], v[36:37], v[14:15], v[116:117]
	global_store_dwordx4 v0, v[102:105], s[46:47] offset:0
	global_store_dwordx4 v0, v[106:109], s[46:47] offset:1024
	global_store_dwordx4 v0, v[110:113], s[46:47] offset:2048
	global_store_dwordx4 v0, v[114:117], s[46:47] offset:3072
	s_add_u32 s46, s46, 0x1000
	s_addc_u32 s47, s47, 0
	s_add_u32 s62, s62, 0x800
	s_addc_u32 s63, s63, 0
	s_waitcnt vmcnt(12)
	v_lshlrev_b32_e32 v14, 16, v172
	v_and_b32_e32 v15, 0xffff0000, v172
	v_lshlrev_b32_e32 v16, 16, v174
	v_and_b32_e32 v17, 0xffff0000, v174
	v_lshlrev_b32_e32 v18, 16, v173
	v_and_b32_e32 v19, 0xffff0000, v173
	v_lshlrev_b32_e32 v20, 16, v175
	v_and_b32_e32 v21, 0xffff0000, v175
	v_pk_add_f32 v[172:173], v[14:15], v[16:17]
	v_pk_add_f32 v[174:175], v[18:19], v[20:21]
	v_lshlrev_b32_e32 v14, 16, v176
	v_and_b32_e32 v15, 0xffff0000, v176
	v_lshlrev_b32_e32 v16, 16, v178
	v_and_b32_e32 v17, 0xffff0000, v178
	v_lshlrev_b32_e32 v18, 16, v177
	v_and_b32_e32 v19, 0xffff0000, v177
	v_lshlrev_b32_e32 v20, 16, v179
	v_and_b32_e32 v21, 0xffff0000, v179
	v_pk_add_f32 v[176:177], v[14:15], v[16:17]
	v_pk_add_f32 v[178:179], v[18:19], v[20:21]
	v_lshlrev_b32_e32 v14, 16, v204
	v_and_b32_e32 v15, 0xffff0000, v204
	v_lshlrev_b32_e32 v16, 16, v206
	v_and_b32_e32 v17, 0xffff0000, v206
	v_lshlrev_b32_e32 v18, 16, v205
	v_and_b32_e32 v19, 0xffff0000, v205
	v_lshlrev_b32_e32 v20, 16, v207
	v_and_b32_e32 v21, 0xffff0000, v207
	v_pk_add_f32 v[204:205], v[14:15], v[16:17]
	v_pk_add_f32 v[206:207], v[18:19], v[20:21]
	v_lshlrev_b32_e32 v14, 16, v214
	v_and_b32_e32 v15, 0xffff0000, v214
	v_lshlrev_b32_e32 v16, 16, v216
	v_and_b32_e32 v17, 0xffff0000, v216
	v_lshlrev_b32_e32 v18, 16, v215
	v_and_b32_e32 v19, 0xffff0000, v215
	v_lshlrev_b32_e32 v20, 16, v217
	v_and_b32_e32 v21, 0xffff0000, v217
	v_pk_add_f32 v[214:215], v[14:15], v[16:17]
	v_pk_add_f32 v[216:217], v[18:19], v[20:21]
	v_pk_mul_f32 v[12:13], v[172:173], v[172:173]
	v_pk_fma_f32 v[12:13], v[174:175], v[174:175], v[12:13]
	v_pk_fma_f32 v[12:13], v[176:177], v[176:177], v[12:13]
	v_pk_fma_f32 v[12:13], v[178:179], v[178:179], v[12:13]
	v_pk_fma_f32 v[12:13], v[204:205], v[204:205], v[12:13]
	v_pk_fma_f32 v[12:13], v[206:207], v[206:207], v[12:13]
	v_pk_fma_f32 v[12:13], v[214:215], v[214:215], v[12:13]
	v_pk_fma_f32 v[12:13], v[216:217], v[216:217], v[12:13]
	v_add_f32_e32 v5, v12, v13
	s_nop 1
	v_add_f32_dpp v5, v5, v5 quad_perm:[1,0,3,2] row_mask:0xf bank_mask:0xf
	s_nop 1
	v_add_f32_dpp v5, v5, v5 quad_perm:[2,3,0,1] row_mask:0xf bank_mask:0xf
	s_nop 1
	v_add_f32_dpp v5, v5, v5 row_half_mirror row_mask:0xf bank_mask:0xf
	s_nop 1
	v_add_f32_dpp v5, v5, v5 row_mirror row_mask:0xf bank_mask:0xf
	s_nop 1
	v_add_f32_dpp v5, v5, v5 row_bcast:15 row_mask:0xa bank_mask:0xf
	s_nop 1
	v_add_f32_dpp v5, v5, v5 row_bcast:31 row_mask:0xc bank_mask:0xf
	s_nop 1
	v_readlane_b32 s32, v5, 63
	s_nop 1
	v_mov_b32_e32 v6, s32
	v_fmamk_f32 v6, v6, 0x3a800000, v146
	v_rsq_f32_e32 v6, v6
	s_nop 0
	v_mul_f32_e32 v8, 0.5, v6
	v_pk_mul_f32 v[14:15], v[172:173], v[8:9] op_sel_hi:[1,0]
	v_pk_fma_f32 v[154:155], v[22:23], v[14:15], v[154:155]
	v_pk_mul_f32 v[14:15], v[174:175], v[8:9] op_sel_hi:[1,0]
	v_pk_fma_f32 v[156:157], v[24:25], v[14:15], v[156:157]
	v_pk_mul_f32 v[14:15], v[176:177], v[8:9] op_sel_hi:[1,0]
	v_pk_fma_f32 v[158:159], v[26:27], v[14:15], v[158:159]
	v_pk_mul_f32 v[14:15], v[178:179], v[8:9] op_sel_hi:[1,0]
	v_pk_fma_f32 v[160:161], v[28:29], v[14:15], v[160:161]
	v_pk_mul_f32 v[14:15], v[204:205], v[8:9] op_sel_hi:[1,0]
	v_pk_fma_f32 v[162:163], v[30:31], v[14:15], v[162:163]
	v_pk_mul_f32 v[14:15], v[206:207], v[8:9] op_sel_hi:[1,0]
	v_pk_fma_f32 v[164:165], v[32:33], v[14:15], v[164:165]
	v_pk_mul_f32 v[14:15], v[214:215], v[8:9] op_sel_hi:[1,0]
	v_pk_fma_f32 v[168:169], v[34:35], v[14:15], v[168:169]
	v_pk_mul_f32 v[14:15], v[216:217], v[8:9] op_sel_hi:[1,0]
	v_pk_fma_f32 v[170:171], v[36:37], v[14:15], v[170:171]
	global_store_dwordx4 v0, v[154:157], s[46:47] offset:0
	global_store_dwordx4 v0, v[158:161], s[46:47] offset:1024
	global_store_dwordx4 v0, v[162:165], s[46:47] offset:2048
	global_store_dwordx4 v0, v[168:171], s[46:47] offset:3072
	s_add_u32 s46, s46, 0x1000
	s_addc_u32 s47, s47, 0
	s_add_u32 s62, s62, 0x800
	s_addc_u32 s63, s63, 0
